# RG-LRU a/b LDS tiles: 16-byte chunk XOR swizzle by token (writers in the gate sections, readers in the scans) removes the 8-way ds_write_b128 bank conflicts
# speedup vs baseline: 1.0976x; 1.0183x over previous
; __device__ __forceinline__ int TIDX() { int t = threadIdx.x; asm volatile("" : "+v"(t)); return t; }
; __device__ __forceinline__ int BIDX() { int b = blockIdx.x; asm volatile("" : "+s"(b)); return b; }
; template <bool FINAL>
; __device__ void phase_lru(const Params& p, int l, unsigned char* smem) {
;   u16* xs = (u16*)smem;
;   float* u32 = (float*)(smem + 8704);
;   u16* ub = (u16*)(smem + 25088);
;   float* sa = (float*)(smem + 34304);
;   float* sb = (float*)(smem + 50688);
;   float* part = (float*)(smem + 67072);
;   const int tid = TIDX(), lane = tid & 63, w = tid >> 6, l15 = lane & 15, g = lane >> 4;
;   const int e_ = tid & 63, qd = tid >> 6;
;   const int NIT = NCHUNK * 8;
;   const int step = gridDim.x;
;   int it = BIDX();
;   uint4 x0 = make_uint4(0, 0, 0, 0), x1 = x0, x2 = x0;
;   auto load_x = [&](int item, uint4& a0, uint4& a1, uint4& a2) {
;     const int ci = item >> 3, nb = item & 7;
;     const int tb = ci * 64, pos0 = tok_pos(tb), S = tok_len(tb);
;     const u16* zb = p.Z + (long)(tb - 2) * DIN + C_LX + nb * 64;
;     { int idx = tid, r = idx >> 3, ch = idx & 7, pp = pos0 - 2 + r;
;       a0 = (pp >= 0 && pp < S) ? *(const uint4*)(zb + (long)r * DIN + ch * 8) : make_uint4(0, 0, 0, 0); }
;     { int idx = tid + 256, r = idx >> 3, ch = idx & 7, pp = pos0 - 2 + r;
;       a1 = (pp >= 0 && pp < S) ? *(const uint4*)(zb + (long)r * DIN + ch * 8) : make_uint4(0, 0, 0, 0); }
;     { int idx = tid + 512, r = idx >> 3, ch = idx & 7, pp = pos0 - 2 + r;
;       a2 = (idx < 67 * 8 && pp >= 0 && pp < S) ? *(const uint4*)(zb + (long)r * DIN + ch * 8) : make_uint4(0, 0, 0, 0); }
;   };
;   if (it < NIT) load_x(it, x0, x1, x2);
;     ...
;       {
;         float A = 1.f, B = 0.f;
;         if (d == 0) {
; #pragma unroll
;           for (int tt = 0; tt < 16; ++tt) { int t = qd * 16 + tt; float a = sa[t * 64 + e_], b = sb[t * 64 + e_]; B = a * B + b; A *= a; }
;         } else {
; #pragma unroll
;     ...
;         }
;         part[(0 * 4 + qd) * 64 + e_] = A;
;         part[(1 * 4 + qd) * 64 + e_] = B;
.LBB0_196:
	s_mov_b32 s4, s22
	s_andn2_b64 vcc, exec, s[30:31]
	v_writelane_b32 v248, s4, 38
	s_nop 1
	v_writelane_b32 v248, s5, 39
	s_cbranch_vccnz .LBB0_226
	v_and_b32_e32 v38, 63, v12
	v_ashrrev_i32_e32 v13, 6, v12
	v_lshlrev_b32_e32 v17, 1, v38
	v_and_b32_e32 v39, 15, v12
	v_add_u32_e32 v18, 0, v17
	v_lshlrev_b32_e32 v21, 4, v13
	v_bfe_u32 v16, v12, 4, 2
	v_add_u32_e32 v20, 0x100, v12
	v_add_u32_e32 v96, v18, v17
	v_or_b32_e32 v17, v21, v39
	v_ashrrev_i32_e32 v51, 3, v20
	v_add_u32_e32 v20, 0x200, v12
	v_mul_lo_u32 v22, v17, s28
	v_lshlrev_b32_e32 v50, 3, v16
	v_and_b32_e32 v23, 48, v12
	v_lshlrev_b32_e32 v97, 2, v16
	v_readlane_b32 s4, v248, 16
	v_lshlrev_b32_e32 v16, 2, v38
	v_lshlrev_b32_e32 v14, 3, v12
	v_ashrrev_i32_e32 v53, 3, v20
	v_add3_u32 v52, 0, v22, v23
	v_lshl_add_u32 v98, v12, 2, s4
	v_add_u32_e32 v99, s4, v16
	s_movk_i32 s4, 0x70
	v_and_b32_e32 v40, 56, v14
	v_add_u32_e32 v14, 32, v36
	v_mad_u64_u32 v[58:59], s[42:43], v17, s4, v[52:53]
	v_readlane_b32 s4, v248, 17
	v_mad_i64_i32 v[42:43], s[30:31], v36, s26, 0
	v_mad_i64_i32 v[44:45], s[30:31], v14, s26, 0
	v_mad_i64_i32 v[46:47], s[30:31], v51, s26, 0
	v_mad_i64_i32 v[48:49], s[30:31], v53, s26, 0
	v_add_u32_e32 v133, s4, v16
	v_readlane_b32 s4, v248, 18
	v_lshlrev_b32_e32 v15, 4, v12
	s_lshl_b32 s30, s22, 1
	v_add_u32_e32 v134, s4, v16
	v_readlane_b32 s4, v248, 19
	v_and_b32_e32 v15, 0xffffff80, v15
	v_lshlrev_b32_e32 v19, 1, v40
	s_or_b32 s56, s30, 1
	v_add_u32_e32 v135, s4, v16
	v_readlane_b32 s4, v248, 20
	v_add3_u32 v41, 0, v15, v19
	v_cmp_gt_i32_e64 s[38:39], 24, v12
	v_ashrrev_i32_e32 v15, 31, v14
	v_and_b32_e32 v12, 0x3fffffc0, v12
	s_ashr_i32 s31, s30, 31
	s_lshl_b32 s40, s22, 10
	s_lshl_b32 s66, s56, 9
	v_add_u32_e32 v136, s4, v16
	v_readlane_b32 s4, v250, 5
	s_lshl_b32 s58, s22, 11
	s_lshl_b32 s59, s22, 9
	v_lshl_add_u32 v100, v12, 2, v99
	v_mul_lo_u32 v12, v36, s28
	v_lshlrev_b64 v[56:57], 11, v[14:15]
	v_lshlrev_b32_e32 v102, 12, v13
	v_or_b32_e32 v14, 1, v21
	s_ashr_i32 s41, s40, 31
	s_ashr_i32 s57, s56, 31
	s_ashr_i32 s67, s66, 31
	s_lshl_b64 s[30:31], s[30:31], 17
	v_readlane_b32 s10, v250, 11
	v_ashrrev_i32_e32 v37, 31, v36
	v_add3_u32 v12, 0, v12, v19
	v_lshlrev_b32_e32 v103, 8, v14
	v_or_b32_e32 v19, 2, v21
	v_or_b32_e32 v17, v102, v16
	v_readlane_b32 s11, v250, 12
	v_readlane_b32 s16, v250, 17
	v_readlane_b32 s17, v250, 18
	v_readlane_b32 s18, v250, 19
	v_readlane_b32 s19, v250, 20
	s_add_u32 s42, s10, s30
	v_add_u32_e32 v101, 0x6200, v12
	v_lshlrev_b64 v[54:55], 11, v[36:37]
	v_add_u32_e32 v37, 0x7400, v12
	v_mul_lo_u32 v12, v13, s27
	v_mul_lo_u32 v15, v14, s28
	v_lshlrev_b32_e32 v104, 8, v19
	v_or_b32_e32 v22, 3, v21
	v_add_u32_e32 v59, 0, v17
	v_or_b32_e32 v17, v103, v16
	s_addc_u32 s43, s11, s31
	v_readlane_b32 s16, v250, 37
	v_lshlrev_b32_e32 v105, 8, v22
	v_or_b32_e32 v23, 4, v21
	v_add_u32_e32 v118, 0, v17
	v_or_b32_e32 v17, v104, v16
	s_lshl_b64 s[40:41], s[40:41], 2
	v_readlane_b32 s20, v250, 41
	v_readlane_b32 s24, v250, 45
	v_lshlrev_b32_e32 v106, 8, v23
	v_or_b32_e32 v24, 5, v21
	v_add_u32_e32 v119, 0, v17
	v_or_b32_e32 v17, v105, v16
	v_readlane_b32 s21, v250, 42
	v_readlane_b32 s25, v250, 46
	s_mov_b32 s20, s58
	s_add_u32 s58, s24, s40
	v_lshlrev_b32_e32 v107, 8, v24
	v_or_b32_e32 v25, 6, v21
	v_add_u32_e32 v120, 0, v17
	v_or_b32_e32 v17, v106, v16
	v_cmp_lt_i32_e64 s[60:61], 0, v13
	v_readlane_b32 s22, v250, 43
	v_readlane_b32 s23, v250, 44
	v_readlane_b32 s28, v250, 49
	s_mov_b32 s21, s59
	s_addc_u32 s59, s25, s41
	v_lshlrev_b32_e32 v108, 8, v25
	v_or_b32_e32 v26, 7, v21
	v_add_u32_e32 v121, 0, v17
	v_or_b32_e32 v17, v107, v16
	v_readlane_b32 s29, v250, 50
	s_mov_b64 s[22:23], s[60:61]
	s_add_u32 s60, s28, s40
	v_lshlrev_b32_e32 v109, 8, v26
	v_or_b32_e32 v27, 8, v21
	v_add_u32_e32 v122, 0, v17
	v_or_b32_e32 v17, v108, v16
	v_readlane_b32 s14, v250, 15
	s_addc_u32 s61, s29, s41
	v_lshlrev_b32_e32 v110, 8, v27
	v_or_b32_e32 v28, 9, v21
	v_add_u32_e32 v123, 0, v17
	v_or_b32_e32 v17, v109, v16
	v_readlane_b32 s15, v250, 16
	s_add_u32 s62, s14, s40
	v_lshlrev_b32_e32 v111, 8, v28
	v_or_b32_e32 v29, 10, v21
	v_add_u32_e32 v124, 0, v17
	v_or_b32_e32 v17, v110, v16
	s_addc_u32 s63, s15, s41
	s_lshl_b64 s[40:41], s[56:57], 17
	v_lshlrev_b32_e32 v112, 8, v29
	v_or_b32_e32 v30, 11, v21
	v_add_u32_e32 v125, 0, v17
	v_or_b32_e32 v17, v111, v16
	s_add_u32 s64, s10, s40
	v_lshlrev_b32_e32 v113, 8, v30
	v_or_b32_e32 v31, 12, v21
	v_add_u32_e32 v126, 0, v17
	v_or_b32_e32 v17, v112, v16
	s_addc_u32 s65, s11, s41
	s_lshl_b64 s[40:41], s[66:67], 2
; __device__ __forceinline__ int TIDX() { int t = threadIdx.x; asm volatile("" : "+v"(t)); return t; }
; __device__ __forceinline__ int BIDX() { int b = blockIdx.x; asm volatile("" : "+s"(b)); return b; }
; template <bool FINAL>
; __device__ void phase_lru(const Params& p, int l, unsigned char* smem) {
;   u16* xs = (u16*)smem;
;   float* u32 = (float*)(smem + 8704);
;   u16* ub = (u16*)(smem + 25088);
;   float* sa = (float*)(smem + 34304);
;   float* sb = (float*)(smem + 50688);
;   float* part = (float*)(smem + 67072);
;   const int tid = TIDX(), lane = tid & 63, w = tid >> 6, l15 = lane & 15, g = lane >> 4;
;   const int e_ = tid & 63, qd = tid >> 6;
;   const int NIT = NCHUNK * 8;
;   const int step = gridDim.x;
;   int it = BIDX();
;   uint4 x0 = make_uint4(0, 0, 0, 0), x1 = x0, x2 = x0;
;   auto load_x = [&](int item, uint4& a0, uint4& a1, uint4& a2) {
;     const int ci = item >> 3, nb = item & 7;
;     const int tb = ci * 64, pos0 = tok_pos(tb), S = tok_len(tb);
;     const u16* zb = p.Z + (long)(tb - 2) * DIN + C_LX + nb * 64;
;     { int idx = tid, r = idx >> 3, ch = idx & 7, pp = pos0 - 2 + r;
;       a0 = (pp >= 0 && pp < S) ? *(const uint4*)(zb + (long)r * DIN + ch * 8) : make_uint4(0, 0, 0, 0); }
;     { int idx = tid + 256, r = idx >> 3, ch = idx & 7, pp = pos0 - 2 + r;
;       a1 = (pp >= 0 && pp < S) ? *(const uint4*)(zb + (long)r * DIN + ch * 8) : make_uint4(0, 0, 0, 0); }
;     { int idx = tid + 512, r = idx >> 3, ch = idx & 7, pp = pos0 - 2 + r;
;       a2 = (idx < 67 * 8 && pp >= 0 && pp < S) ? *(const uint4*)(zb + (long)r * DIN + ch * 8) : make_uint4(0, 0, 0, 0); }
;   };
;   if (it < NIT) load_x(it, x0, x1, x2);
;     ...
;         uf[0] = *(const bf16x8*)(ub + (16 * w + l15) * 72 + g * 8);
;         uf[1] = *(const bf16x8*)(ub + (16 * w + l15) * 72 + 32 + g * 8);
;         const int t = 16 * w + l15;
; #pragma unroll
;         for (int et = 0; et < 4; ++et) {
;           f32x4 ar = {0.f, 0.f, 0.f, 0.f}, ai = {0.f, 0.f, 0.f, 0.f};
;           const u16* wr = p.WLRU + ((((size_t)(l * 2 + d) * 2 + 0) * 8 + nb) * 64 + et * 16 + l15) * 64 + g * 8;
;           const u16* wi = p.WLRU + ((((size_t)(l * 2 + d) * 2 + 1) * 8 + nb) * 64 + et * 16 + l15) * 64 + g * 8;
; #pragma unroll
	v_lshlrev_b32_e32 v114, 8, v31
	v_or_b32_e32 v32, 13, v21
	v_add_u32_e32 v127, 0, v17
	v_or_b32_e32 v17, v113, v16
	s_add_u32 s66, s24, s40
	v_lshlrev_b32_e32 v115, 8, v32
	v_or_b32_e32 v33, 14, v21
	v_add_u32_e32 v128, 0, v17
	v_or_b32_e32 v17, v114, v16
	v_cmp_lt_i32_e64 s[68:69], 1, v13
	s_addc_u32 s67, s25, s41
	v_lshlrev_b32_e32 v116, 8, v33
	v_or_b32_e32 v21, 15, v21
	v_add_u32_e32 v129, 0, v17
	v_or_b32_e32 v17, v115, v16
	s_mov_b64 s[24:25], s[68:69]
	s_add_u32 s68, s28, s40
	v_lshlrev_b32_e32 v117, 8, v21
	v_add_u32_e32 v130, 0, v17
	v_or_b32_e32 v17, v116, v16
	v_readlane_b32 s5, v250, 6
	s_addc_u32 s69, s29, s41
	v_add_u32_e32 v131, 0, v17
	v_or_b32_e32 v17, v117, v16
	s_add_u32 s72, s14, s40
	v_readlane_b32 s4, v250, 1
	v_lshlrev_b32_e32 v20, 11, v13
	v_add_u32_e32 v132, 0, v17
	v_cmp_lt_i32_e64 s[44:45], 2, v13
	v_cmp_lt_i32_e64 s[46:47], 3, v13
	v_cmp_gt_i32_e64 s[48:49], 3, v13
	v_cmp_gt_i32_e64 s[50:51], 2, v13
	v_cmp_gt_i32_e64 s[52:53], 1, v13
	v_cmp_gt_i32_e64 s[54:55], 0, v13
	v_lshlrev_b32_e32 v13, 7, v14
	v_lshlrev_b32_e32 v14, 7, v19
	v_lshlrev_b32_e32 v16, 7, v22
	v_lshlrev_b32_e32 v17, 7, v23
	v_lshlrev_b32_e32 v19, 7, v24
	v_lshlrev_b32_e32 v22, 7, v25
	v_lshlrev_b32_e32 v23, 7, v26
	v_lshlrev_b32_e32 v24, 7, v27
	v_lshlrev_b32_e32 v25, 7, v28
	v_lshlrev_b32_e32 v26, 7, v29
	v_lshlrev_b32_e32 v27, 7, v30
	v_lshlrev_b32_e32 v28, 7, v31
	v_lshlrev_b32_e32 v29, 7, v32
	v_lshlrev_b32_e32 v30, 7, v33
	v_lshlrev_b32_e32 v21, 7, v21
	s_addc_u32 s73, s15, s41
	s_add_i32 s40, s4, s36
	s_lshl_b32 s99, s40, 3
	s_lshl_b32 s97, s36, 6
	v_lshlrev_b32_e32 v137, 2, v38
	v_add_u32_e32 v138, v18, v13
	v_add_u32_e32 v139, v18, v14
	v_add_u32_e32 v140, v18, v16
	v_add_u32_e32 v141, v18, v17
	v_add_u32_e32 v142, v18, v19
	v_add_u32_e32 v143, v18, v22
	v_add_u32_e32 v149, v18, v23
	v_add_u32_e32 v150, v18, v24
	v_add_u32_e32 v151, v18, v25
	v_add_u32_e32 v152, v18, v26
	v_add_u32_e32 v153, v18, v27
	v_add_u32_e32 v154, v18, v28
	v_add_u32_e32 v155, v18, v29
	v_add_u32_e32 v156, v18, v30
	v_add_u32_e32 v157, v18, v21
	v_add_u32_e32 v158, v18, v20
	v_add_u32_e32 v159, v18, v12
	v_add_u32_e32 v160, v18, v15
	v_readlane_b32 s6, v250, 7
	v_readlane_b32 s7, v250, 8
	v_readlane_b32 s8, v250, 9
	v_readlane_b32 s9, v250, 10
	v_readlane_b32 s12, v250, 13
	v_readlane_b32 s13, v250, 14
	v_readlane_b32 s17, v250, 38
	v_readlane_b32 s18, v250, 39
	v_readlane_b32 s19, v250, 40
	v_readlane_b32 s26, v250, 47
	v_readlane_b32 s27, v250, 48
	v_readlane_b32 s30, v250, 51
	v_readlane_b32 s31, v250, 52
	v_readlane_b32 s5, v250, 2
	s_lshl_b32 s32, s36, 6
	s_and_b32 s32, s32, 0x1c0
	v_lshrrev_b32_e32 v12, 6, v147
	v_and_b32_e32 v22, 15, v147
	v_lshlrev_b32_e32 v13, 4, v12
	v_or_b32_e32 v13, v13, v22
	v_or_b32_e32 v13, s32, v13
	v_lshlrev_b32_e32 v14, 7, v13
	v_mov_b32_e32 v15, v145
	v_bfe_u32 v16, v147, 4, 2
	v_lshlrev_b32_e32 v17, 4, v16
	v_add_u32_e32 v14, v14, v17
	v_lshl_add_u64 v[18:19], s[42:43], 0, v[14:15]
	global_load_dwordx4 v[180:183], v[18:19], off
	global_load_dwordx4 v[184:187], v[18:19], off offset:64
	v_add_co_u32_e32 v20, vcc, 0x10000, v18
	s_nop 0
	v_addc_co_u32_e32 v21, vcc, 0, v19, vcc
	global_load_dwordx4 v[188:191], v[20:21], off
	global_load_dwordx4 v[192:195], v[20:21], off offset:64
	v_lshl_add_u64 v[18:19], s[64:65], 0, v[14:15]
	global_load_dwordx4 v[232:235], v[18:19], off
	global_load_dwordx4 v[236:239], v[18:19], off offset:64
	v_add_co_u32_e32 v20, vcc, 0x10000, v18
	s_nop 0
	v_addc_co_u32_e32 v21, vcc, 0, v19, vcc
	global_load_dwordx4 v[240:243], v[20:21], off
	global_load_dwordx4 v[244:247], v[20:21], off offset:64
	v_mul_u32_u24_e32 v229, 0x90, v22
	v_add_u32_e32 v229, v229, v17
	v_lshlrev_b32_e32 v230, 8, v22
	v_add_u32_e32 v230, v230, v17
	v_lshl_add_u32 v230, v12, 6, v230
	v_lshlrev_b32_e32 v231, 4, v12
	v_lshl_add_u32 v231, v16, 2, v231
	v_or_b32_e32 v231, s32, v231
	v_lshlrev_b32_e32 v231, 2, v231
	v_lshl_add_u32 v204, v12, 2, v16
	v_xor_b32_e32 v204, v204, v22
	v_lshlrev_b32_e32 v204, 4, v204
	v_lshl_add_u32 v204, v22, 8, v204
	v_xor_b32_e32 v118, 0x10, v118
	v_xor_b32_e32 v119, 0x20, v119
	v_xor_b32_e32 v120, 0x30, v120
	v_xor_b32_e32 v121, 0x40, v121
	v_xor_b32_e32 v122, 0x50, v122
	v_xor_b32_e32 v123, 0x60, v123
	v_xor_b32_e32 v124, 0x70, v124
	v_xor_b32_e32 v125, 0x80, v125
	v_xor_b32_e32 v126, 0x90, v126
	v_xor_b32_e32 v127, 0xa0, v127
	v_xor_b32_e32 v128, 0xb0, v128
	v_xor_b32_e32 v129, 0xc0, v129
	v_xor_b32_e32 v130, 0xd0, v130
	v_xor_b32_e32 v131, 0xe0, v131
	v_xor_b32_e32 v132, 0xf0, v132
	s_branch .LBB0_199

; __device__ __forceinline__ float bf2f(unsigned h) { return __uint_as_float(h << 16); }
; template <bool FINAL>
; __device__ void phase_lru(const Params& p, int l, unsigned char* smem) {
;     ...
;     {
;       const int ch = nb * 64 + e_;
;       const float cw0 = p.conv_w[(l * 4 + 0) * 512 + ch], cw1 = p.conv_w[(l * 4 + 1) * 512 + ch],
;                   cw2 = p.conv_w[(l * 4 + 2) * 512 + ch], cw3 = p.conv_w[(l * 4 + 3) * 512 + ch];
;       const float cb = p.conv_b[l * 512 + ch];
;       float xv[19];
; #pragma unroll
;       for (int k = 0; k < 19; ++k) xv[k] = bf2f(xs[(qd * 16 + k) * 64 + e_]);
; #pragma unroll
;       for (int tt = 0; tt < 16; ++tt) {
;         const int t = qd * 16 + tt;
;         const float u = cb + xv[tt] * cw0 + xv[tt + 1] * cw1 + xv[tt + 2] * cw2 + xv[tt + 3] * cw3;
;         u32[t * 64 + e_] = u;
;         ub[t * 72 + e_] = (u16)f2bf(u);
;       }
;     }
.LBB0_209:
	v_or_b32_e32 v26, s40, v38
	v_or_b32_e32 v20, s20, v26
	v_readlane_b32 s4, v250, 37
	v_ashrrev_i32_e32 v21, 31, v20
	v_readlane_b32 s6, v250, 39
	v_readlane_b32 s7, v250, 40
	v_readlane_b32 s8, v250, 41
	v_readlane_b32 s9, v250, 42
	v_lshl_add_u64 v[22:23], v[20:21], 2, s[6:7]
	v_add_co_u32_e32 v24, vcc, 0x1000, v22
	global_load_dword v21, v[22:23], off
	global_load_dword v20, v[22:23], off offset:2048
	v_addc_co_u32_e32 v25, vcc, 0, v23, vcc
	global_load_dword v23, v[24:25], off
	global_load_dword v22, v[24:25], off offset:2048
	v_or_b32_e32 v24, s21, v26
	v_ashrrev_i32_e32 v25, 31, v24
	v_lshl_add_u64 v[24:25], v[24:25], 2, s[8:9]
	global_load_dword v24, v[24:25], off
	ds_read_u16 v25, v158
	ds_read_u16 v26, v158 offset:128
	ds_read_u16 v27, v158 offset:256
	ds_read_u16 v28, v158 offset:384
	ds_read_u16 v29, v158 offset:512
	s_waitcnt lgkmcnt(4)
	v_lshlrev_b32_e32 v25, 16, v25
	s_waitcnt lgkmcnt(3)
	v_lshlrev_b32_e32 v26, 16, v26
	s_waitcnt lgkmcnt(2)
	v_lshlrev_b32_e32 v27, 16, v27
	s_waitcnt lgkmcnt(1)
	v_lshlrev_b32_e32 v28, 16, v28
	v_add_u32_e32 v69, v96, v102
	ds_read_u16 v30, v158 offset:640
	ds_read_u16 v31, v158 offset:768
	ds_read_u16 v32, v158 offset:896
	ds_read_u16 v33, v158 offset:1024
	ds_read_u16 v34, v158 offset:1152
	ds_read_u16 v35, v158 offset:1280
	ds_read_u16 v61, v158 offset:1408
	ds_read_u16 v62, v158 offset:1536
	ds_read_u16 v63, v158 offset:1664
	ds_read_u16 v64, v158 offset:1792
	ds_read_u16 v65, v158 offset:1920
	ds_read_u16 v66, v158 offset:2048
	ds_read_u16 v67, v158 offset:2176
	ds_read_u16 v68, v158 offset:2304
	s_waitcnt lgkmcnt(14)
	v_lshlrev_b32_e32 v29, 16, v29
	s_waitcnt lgkmcnt(13)
	v_lshlrev_b32_e32 v30, 16, v30
	s_waitcnt lgkmcnt(12)
	v_lshlrev_b32_e32 v31, 16, v31
	s_waitcnt lgkmcnt(11)
	v_lshlrev_b32_e32 v32, 16, v32
	s_waitcnt lgkmcnt(10)
	v_lshlrev_b32_e32 v33, 16, v33
	s_waitcnt lgkmcnt(9)
	v_lshlrev_b32_e32 v34, 16, v34
	s_waitcnt lgkmcnt(8)
	v_lshlrev_b32_e32 v35, 16, v35
	s_waitcnt lgkmcnt(7)
	v_lshlrev_b32_e32 v61, 16, v61
	s_waitcnt lgkmcnt(6)
	v_lshlrev_b32_e32 v62, 16, v62
	s_waitcnt lgkmcnt(5)
	v_lshlrev_b32_e32 v63, 16, v63
	s_waitcnt lgkmcnt(4)
	v_lshlrev_b32_e32 v64, 16, v64
	s_waitcnt lgkmcnt(3)
	v_lshlrev_b32_e32 v65, 16, v65
	s_waitcnt lgkmcnt(2)
	v_lshlrev_b32_e32 v66, 16, v66
	s_waitcnt lgkmcnt(1)
	v_lshlrev_b32_e32 v67, 16, v67
	s_waitcnt lgkmcnt(0)
	v_lshlrev_b32_e32 v68, 16, v68
	v_readlane_b32 s5, v250, 38
	s_mov_b64 s[4:5], 0x10000
	s_mov_b32 s6, 0xbe800000
	s_mov_b64 s[8:9], 0x10800
	s_ashr_i32 s93, s92, 31
	v_readlane_b32 s10, v250, 43
	v_readlane_b32 s11, v250, 44
	v_readlane_b32 s12, v250, 45
	v_readlane_b32 s13, v250, 46
	v_readlane_b32 s14, v250, 47
	v_readlane_b32 s15, v250, 48
	v_readlane_b32 s16, v250, 49
	v_readlane_b32 s17, v250, 50
	v_readlane_b32 s18, v250, 51
	v_readlane_b32 s19, v250, 52
	s_waitcnt vmcnt(0)
	v_fma_f32 v25, v21, v25, v24
	v_fmac_f32_e32 v25, v20, v26
	v_fmac_f32_e32 v25, v23, v27
	v_fmac_f32_e32 v25, v22, v28
	ds_write_b32 v69, v25 offset:8704
	v_cvt_pk_bf16_f32 v25, v25, s0
	ds_write_b16 v159, v25 offset:25088
	v_fma_f32 v25, v21, v26, v24
	v_fmac_f32_e32 v25, v20, v27
	v_fmac_f32_e32 v25, v23, v28
	v_fmac_f32_e32 v25, v22, v29
	v_add_u32_e32 v26, v96, v103
	ds_write_b32 v26, v25 offset:8704
	v_cvt_pk_bf16_f32 v25, v25, s0
	ds_write_b16 v160, v25 offset:25088
	v_fma_f32 v25, v21, v27, v24
	v_fmac_f32_e32 v25, v20, v28
	v_fmac_f32_e32 v25, v23, v29
	v_fmac_f32_e32 v25, v22, v30
	v_add_u32_e32 v26, v96, v104
	ds_write_b32 v26, v25 offset:8704
	v_cvt_pk_bf16_f32 v25, v25, s0
	ds_write_b16 v160, v25 offset:25232
	v_fma_f32 v25, v21, v28, v24
	v_fmac_f32_e32 v25, v20, v29
	v_fmac_f32_e32 v25, v23, v30
	v_fmac_f32_e32 v25, v22, v31
	v_add_u32_e32 v26, v96, v105
	ds_write_b32 v26, v25 offset:8704
	v_cvt_pk_bf16_f32 v25, v25, s0
	ds_write_b16 v160, v25 offset:25376
	v_fma_f32 v25, v21, v29, v24
	v_fmac_f32_e32 v25, v20, v30
	v_fmac_f32_e32 v25, v23, v31
	v_fmac_f32_e32 v25, v22, v32
	v_add_u32_e32 v26, v96, v106
	ds_write_b32 v26, v25 offset:8704
	v_cvt_pk_bf16_f32 v25, v25, s0
	ds_write_b16 v160, v25 offset:25520
	v_fma_f32 v25, v21, v30, v24
	v_fmac_f32_e32 v25, v20, v31
	v_fmac_f32_e32 v25, v23, v32
	v_fmac_f32_e32 v25, v22, v33
	v_add_u32_e32 v26, v96, v107
	ds_write_b32 v26, v25 offset:8704
	v_cvt_pk_bf16_f32 v25, v25, s0
	ds_write_b16 v160, v25 offset:25664
	v_fma_f32 v25, v21, v31, v24
	v_fmac_f32_e32 v25, v20, v32
	v_fmac_f32_e32 v25, v23, v33
	v_fmac_f32_e32 v25, v22, v34
	v_add_u32_e32 v26, v96, v108
	ds_write_b32 v26, v25 offset:8704
	v_cvt_pk_bf16_f32 v25, v25, s0
	ds_write_b16 v160, v25 offset:25808
	v_fma_f32 v25, v21, v32, v24
	v_fmac_f32_e32 v25, v20, v33
	v_fmac_f32_e32 v25, v23, v34
	v_fmac_f32_e32 v25, v22, v35
	v_add_u32_e32 v26, v96, v109
	ds_write_b32 v26, v25 offset:8704
	v_cvt_pk_bf16_f32 v25, v25, s0
	ds_write_b16 v160, v25 offset:25952
	v_fma_f32 v25, v21, v33, v24
	v_fmac_f32_e32 v25, v20, v34
	v_fmac_f32_e32 v25, v23, v35
	v_fmac_f32_e32 v25, v22, v61
	v_add_u32_e32 v26, v96, v110
	ds_write_b32 v26, v25 offset:8704
	v_cvt_pk_bf16_f32 v25, v25, s0
	ds_write_b16 v160, v25 offset:26096
	v_fma_f32 v25, v21, v34, v24
	v_fmac_f32_e32 v25, v20, v35
	v_fmac_f32_e32 v25, v23, v61
	v_fmac_f32_e32 v25, v22, v62
	v_add_u32_e32 v26, v96, v111
	ds_write_b32 v26, v25 offset:8704
	v_cvt_pk_bf16_f32 v25, v25, s0
	ds_write_b16 v160, v25 offset:26240
	v_fma_f32 v25, v21, v35, v24
	v_fmac_f32_e32 v25, v20, v61
	v_fmac_f32_e32 v25, v23, v62
	v_fmac_f32_e32 v25, v22, v63
	v_add_u32_e32 v26, v96, v112
	ds_write_b32 v26, v25 offset:8704
	v_cvt_pk_bf16_f32 v25, v25, s0
	ds_write_b16 v160, v25 offset:26384
	v_fma_f32 v25, v21, v61, v24
; template <bool FINAL>
; __device__ void phase_lru(const Params& p, int l, unsigned char* smem) {
;     ...
;       for (int tt = 0; tt < 16; ++tt) {
;         const int t = qd * 16 + tt;
;         const float u = cb + xv[tt] * cw0 + xv[tt + 1] * cw1 + xv[tt + 2] * cw2 + xv[tt + 3] * cw3;
;         u32[t * 64 + e_] = u;
;         ub[t * 72 + e_] = (u16)f2bf(u);
;       }
;     }
;     __syncthreads();
;     if (FINAL) {
;       *(uint4*)(xs + (tid >> 3) * 64 + (tid & 7) * 8) = gz0;
;       *(uint4*)(xs + ((tid >> 3) + 32) * 64 + (tid & 7) * 8) = gz1;
;     }
;     ...
;         for (int et = 0; et < 4; ++et) {
;           f32x4 ar = {0.f, 0.f, 0.f, 0.f}, ai = {0.f, 0.f, 0.f, 0.f};
;           const u16* wr = p.WLRU + ((((size_t)(l * 2 + d) * 2 + 0) * 8 + nb) * 64 + et * 16 + l15) * 64 + g * 8;
;           const u16* wi = p.WLRU + ((((size_t)(l * 2 + d) * 2 + 1) * 8 + nb) * 64 + et * 16 + l15) * 64 + g * 8;
; #pragma unroll
;           for (int ks = 0; ks < 2; ++ks) {
;             ar = mfma16(*(const bf16x8*)(wr + ks * 32), uf[ks], ar);
;             ai = mfma16(*(const bf16x8*)(wi + ks * 32), uf[ks], ai);
;           }
;           const int e0 = et * 16 + 4 * g, ch0 = nb * 64 + e0;
;           const float4 ba4 = *(const float4*)(p.ba + (l * 2 + d) * 512 + ch0);
;           const float4 bx4 = *(const float4*)(p.bx + (l * 2 + d) * 512 + ch0);
;           const float4 sp4 = *(const float4*)(p.SP8 + (l * 2 + d) * 512 + ch0);
;           const float4 uu = *(const float4*)(u32 + t * 64 + e0);
;           const float* bap = (const float*)&ba4; const float* bxp = (const float*)&bx4;
;           const float* spp = (const float*)&sp4; const float* uup = (const float*)&uu;
;           f32x4 av, bv;
; #pragma unroll
;           for (int j = 0; j < 4; ++j) {
;             float r = sigmoidf_(ar[j] + bap[j]);
;             float ig = sigmoidf_(ai[j] + bxp[j]);
;             float la = spp[j] * r;
;             float av_ = __expf(la);
;             float t2 = 2.0f * la;
;             float ser = -t2 * (1.f + t2 * 0.5f * (1.f + t2 * (1.f / 3.f) * (1.f + t2 * 0.25f * (1.f + t2 * 0.2f))));
;             float om = (t2 > -0.25f) ? ser : (1.0f - av_ * av_);
;             av[j] = av_;
;             bv[j] = __builtin_amdgcn_sqrtf(om) * ig * uup[j];
;           }
;           *(f32x4*)(sa + t * 64 + e0) = av;
;           *(f32x4*)(sb + t * 64 + e0) = bv;
;         }
	v_fmac_f32_e32 v25, v20, v62
	v_fmac_f32_e32 v25, v23, v63
	v_fmac_f32_e32 v25, v22, v64
	v_add_u32_e32 v26, v96, v113
	ds_write_b32 v26, v25 offset:8704
	v_cvt_pk_bf16_f32 v25, v25, s0
	ds_write_b16 v160, v25 offset:26528
	v_fma_f32 v25, v21, v62, v24
	v_fmac_f32_e32 v25, v20, v63
	v_fmac_f32_e32 v25, v23, v64
	v_fmac_f32_e32 v25, v22, v65
	v_add_u32_e32 v26, v96, v114
	ds_write_b32 v26, v25 offset:8704
	v_cvt_pk_bf16_f32 v25, v25, s0
	ds_write_b16 v160, v25 offset:26672
	v_fma_f32 v25, v21, v63, v24
	v_fmac_f32_e32 v25, v20, v64
	v_fmac_f32_e32 v25, v23, v65
	v_fmac_f32_e32 v25, v22, v66
	v_add_u32_e32 v26, v96, v115
	ds_write_b32 v26, v25 offset:8704
	v_cvt_pk_bf16_f32 v25, v25, s0
	ds_write_b16 v160, v25 offset:26816
	v_fma_f32 v25, v21, v64, v24
	v_fmac_f32_e32 v24, v21, v65
	v_fmac_f32_e32 v24, v20, v66
	v_fmac_f32_e32 v24, v23, v67
	v_fmac_f32_e32 v25, v20, v65
	v_fmac_f32_e32 v24, v22, v68
	v_add_u32_e32 v20, v96, v117
	ds_write_b32 v20, v24 offset:8704
	v_cvt_pk_bf16_f32 v20, v24, s0
	v_fmac_f32_e32 v25, v23, v66
	ds_write_b16 v160, v20 offset:27104
	v_or_b32_e32 v20, s40, v39
	v_fmac_f32_e32 v25, v22, v67
	v_add_u32_e32 v26, v96, v116
	v_lshlrev_b32_e32 v144, 7, v20
	ds_write_b32 v26, v25 offset:8704
	v_cvt_pk_bf16_f32 v25, v25, s0
	v_lshl_add_u64 v[20:21], s[42:43], 0, v[144:145]
	v_lshlrev_b32_e32 v62, 1, v50
	v_mov_b32_e32 v63, v145
	ds_write_b16 v160, v25 offset:26960
	s_waitcnt lgkmcnt(0)
	s_barrier
	ds_write_b128 v41, v[12:15]
	ds_write_b128 v41, v[16:19] offset:4096
	s_mov_b32 s5, 0x3e4ccccd
	global_load_dwordx4 v[196:199], v231, s[58:59]
	global_load_dwordx4 v[200:203], v231, s[60:61]
	global_load_dwordx4 v[32:35], v231, s[62:63]
	ds_read_b128 v[12:15], v229 offset:25088
	ds_read_b128 v[16:19], v229 offset:25152
	ds_read_b128 v[28:31], v230 offset:8704
	s_waitcnt lgkmcnt(1)
	v_mfma_f32_16x16x32_bf16 v[20:23], v[180:183], v[12:15], 0
	v_mfma_f32_16x16x32_bf16 v[24:27], v[188:191], v[12:15], 0
	v_mfma_f32_16x16x32_bf16 v[20:23], v[184:187], v[16:19], v[20:23]
	v_mfma_f32_16x16x32_bf16 v[24:27], v[192:195], v[16:19], v[24:27]
	s_waitcnt vmcnt(0)
	s_nop 7
	s_nop 3
	s_waitcnt lgkmcnt(0)
	v_add_f32_e32 v20, v20, v196
	v_add_f32_e32 v21, v21, v197
	v_add_f32_e32 v24, v24, v200
	v_add_f32_e32 v25, v25, v201
	v_mul_f32_e32 v20, 0xbfb8aa3b, v20
	v_mul_f32_e32 v21, 0xbfb8aa3b, v21
	v_mul_f32_e32 v24, 0xbfb8aa3b, v24
	v_mul_f32_e32 v25, 0xbfb8aa3b, v25
	v_exp_f32_e32 v20, v20
	v_exp_f32_e32 v21, v21
	v_exp_f32_e32 v24, v24
	v_exp_f32_e32 v25, v25
	v_add_f32_e32 v20, 1.0, v20
	v_add_f32_e32 v21, 1.0, v21
	v_add_f32_e32 v24, 1.0, v24
	v_add_f32_e32 v25, 1.0, v25
	v_rcp_f32_e32 v20, v20
	v_rcp_f32_e32 v21, v21
	v_rcp_f32_e32 v24, v24
	v_rcp_f32_e32 v25, v25
	v_pk_mul_f32 v[12:13], v[20:21], v[32:33]
	s_nop 0
	v_pk_add_f32 v[14:15], v[12:13], v[12:13]
	v_mul_f32_e32 v20, 0x3fb8aa3b, v12
	v_mul_f32_e32 v21, 0x3fb8aa3b, v13
	v_exp_f32_e32 v20, v20
	v_exp_f32_e32 v21, v21
	v_mul_f32_e32 v16, 0x3e800000, v14
	v_fma_f32 v17, v14, s5, 1.0
	v_mul_f32_e32 v18, 0x3eaaaaab, v14
	v_fma_f32 v16, v16, v17, 1.0
	v_mul_f32_e32 v17, 0.5, v14
	v_fma_f32 v18, v18, v16, 1.0
	v_fma_f32 v17, v17, v18, 1.0
	v_mul_f32_e64 v17, v17, -v14
	v_fma_f32 v16, -v20, v20, 1.0
	v_cmp_lt_f32_e32 vcc, s6, v14
	v_mul_f32_e32 v19, 0x3e800000, v15
	v_fma_f32 v12, v15, s5, 1.0
	v_cndmask_b32_e32 v16, v16, v17, vcc
	v_mul_f32_e32 v13, 0x3eaaaaab, v15
	v_fma_f32 v19, v19, v12, 1.0
	v_mul_f32_e32 v12, 0.5, v15
	v_fma_f32 v13, v13, v19, 1.0
	v_fma_f32 v12, v12, v13, 1.0
	v_mul_f32_e64 v12, v12, -v15
	v_fma_f32 v13, -v21, v21, 1.0
	v_cmp_lt_f32_e32 vcc, s6, v15
	v_sqrt_f32_e32 v16, v16
	s_nop 1
	v_cndmask_b32_e32 v17, v13, v12, vcc
	v_sqrt_f32_e32 v17, v17
	s_nop 0
	v_pk_mul_f32 v[24:25], v[24:25], v[16:17]
	s_nop 0
	v_pk_mul_f32 v[24:25], v[28:29], v[24:25]
	v_add_f32_e32 v22, v22, v198
	v_add_f32_e32 v23, v23, v199
	v_add_f32_e32 v26, v26, v202
	v_add_f32_e32 v27, v27, v203
	v_mul_f32_e32 v22, 0xbfb8aa3b, v22
	v_mul_f32_e32 v23, 0xbfb8aa3b, v23
	v_mul_f32_e32 v26, 0xbfb8aa3b, v26
	v_mul_f32_e32 v27, 0xbfb8aa3b, v27
	v_exp_f32_e32 v22, v22
	v_exp_f32_e32 v23, v23
	v_exp_f32_e32 v26, v26
	v_exp_f32_e32 v27, v27
	v_add_f32_e32 v22, 1.0, v22
	v_add_f32_e32 v23, 1.0, v23
	v_add_f32_e32 v26, 1.0, v26
	v_add_f32_e32 v27, 1.0, v27
	v_rcp_f32_e32 v22, v22
	v_rcp_f32_e32 v23, v23
	v_rcp_f32_e32 v26, v26
	v_rcp_f32_e32 v27, v27
	v_pk_mul_f32 v[12:13], v[22:23], v[34:35]
	s_nop 0
	v_pk_add_f32 v[14:15], v[12:13], v[12:13]
	v_mul_f32_e32 v22, 0x3fb8aa3b, v12
	v_mul_f32_e32 v23, 0x3fb8aa3b, v13
	v_exp_f32_e32 v22, v22
	v_exp_f32_e32 v23, v23
	v_mul_f32_e32 v16, 0x3e800000, v14
	v_fma_f32 v17, v14, s5, 1.0
	v_mul_f32_e32 v18, 0x3eaaaaab, v14
	v_fma_f32 v16, v16, v17, 1.0
	v_mul_f32_e32 v17, 0.5, v14
	v_fma_f32 v18, v18, v16, 1.0
	v_fma_f32 v17, v17, v18, 1.0
	v_mul_f32_e64 v17, v17, -v14
	v_fma_f32 v16, -v22, v22, 1.0
	v_cmp_lt_f32_e32 vcc, s6, v14
	v_mul_f32_e32 v19, 0x3e800000, v15
	v_fma_f32 v12, v15, s5, 1.0
	v_cndmask_b32_e32 v16, v16, v17, vcc
	v_mul_f32_e32 v13, 0x3eaaaaab, v15
	v_fma_f32 v19, v19, v12, 1.0
	v_mul_f32_e32 v12, 0.5, v15
	v_fma_f32 v13, v13, v19, 1.0
	v_fma_f32 v12, v12, v13, 1.0
	v_mul_f32_e64 v12, v12, -v15
	v_fma_f32 v13, -v23, v23, 1.0
	v_cmp_lt_f32_e32 vcc, s6, v15
	v_sqrt_f32_e32 v16, v16
	s_nop 1
	v_cndmask_b32_e32 v17, v13, v12, vcc
	v_sqrt_f32_e32 v17, v17
	s_nop 0
	v_pk_mul_f32 v[26:27], v[26:27], v[16:17]
	s_nop 0
	v_pk_mul_f32 v[26:27], v[30:31], v[26:27]
	ds_write_b128 v204, v[20:23] offset:34304
	ds_write_b128 v204, v[24:27] offset:50688
	ds_read_b128 v[12:15], v229 offset:27392
	ds_read_b128 v[16:19], v229 offset:27456
	ds_read_b128 v[28:31], v230 offset:12800
	s_waitcnt lgkmcnt(1)
; __device__ __forceinline__ float sigmoidf_(float x) { return __builtin_amdgcn_rcpf(1.0f + __expf(-x)); }
; template <bool FINAL>
; __device__ void phase_lru(const Params& p, int l, unsigned char* smem) {
;     ...
;         for (int et = 0; et < 4; ++et) {
;           f32x4 ar = {0.f, 0.f, 0.f, 0.f}, ai = {0.f, 0.f, 0.f, 0.f};
;           const u16* wr = p.WLRU + ((((size_t)(l * 2 + d) * 2 + 0) * 8 + nb) * 64 + et * 16 + l15) * 64 + g * 8;
;           const u16* wi = p.WLRU + ((((size_t)(l * 2 + d) * 2 + 1) * 8 + nb) * 64 + et * 16 + l15) * 64 + g * 8;
; #pragma unroll
;           for (int ks = 0; ks < 2; ++ks) {
;             ar = mfma16(*(const bf16x8*)(wr + ks * 32), uf[ks], ar);
;             ai = mfma16(*(const bf16x8*)(wi + ks * 32), uf[ks], ai);
;           }
;           const int e0 = et * 16 + 4 * g, ch0 = nb * 64 + e0;
;           const float4 ba4 = *(const float4*)(p.ba + (l * 2 + d) * 512 + ch0);
;           const float4 bx4 = *(const float4*)(p.bx + (l * 2 + d) * 512 + ch0);
;           const float4 sp4 = *(const float4*)(p.SP8 + (l * 2 + d) * 512 + ch0);
;           const float4 uu = *(const float4*)(u32 + t * 64 + e0);
;           const float* bap = (const float*)&ba4; const float* bxp = (const float*)&bx4;
;           const float* spp = (const float*)&sp4; const float* uup = (const float*)&uu;
;           f32x4 av, bv;
; #pragma unroll
;           for (int j = 0; j < 4; ++j) {
;             float r = sigmoidf_(ar[j] + bap[j]);
;             float ig = sigmoidf_(ai[j] + bxp[j]);
;             float la = spp[j] * r;
;             float av_ = __expf(la);
;             float t2 = 2.0f * la;
;             float ser = -t2 * (1.f + t2 * 0.5f * (1.f + t2 * (1.f / 3.f) * (1.f + t2 * 0.25f * (1.f + t2 * 0.2f))));
;             float om = (t2 > -0.25f) ? ser : (1.0f - av_ * av_);
;             av[j] = av_;
;             bv[j] = __builtin_amdgcn_sqrtf(om) * ig * uup[j];
;           }
;           *(f32x4*)(sa + t * 64 + e0) = av;
;           *(f32x4*)(sb + t * 64 + e0) = bv;
;         }
	v_mfma_f32_16x16x32_bf16 v[20:23], v[180:183], v[12:15], 0
	v_mfma_f32_16x16x32_bf16 v[24:27], v[188:191], v[12:15], 0
	v_mfma_f32_16x16x32_bf16 v[20:23], v[184:187], v[16:19], v[20:23]
	v_mfma_f32_16x16x32_bf16 v[24:27], v[192:195], v[16:19], v[24:27]
	s_nop 7
	s_nop 3
	s_waitcnt lgkmcnt(0)
	v_add_f32_e32 v20, v20, v196
	v_add_f32_e32 v21, v21, v197
	v_add_f32_e32 v24, v24, v200
	v_add_f32_e32 v25, v25, v201
	v_mul_f32_e32 v20, 0xbfb8aa3b, v20
	v_mul_f32_e32 v21, 0xbfb8aa3b, v21
	v_mul_f32_e32 v24, 0xbfb8aa3b, v24
	v_mul_f32_e32 v25, 0xbfb8aa3b, v25
	v_exp_f32_e32 v20, v20
	v_exp_f32_e32 v21, v21
	v_exp_f32_e32 v24, v24
	v_exp_f32_e32 v25, v25
	v_add_f32_e32 v20, 1.0, v20
	v_add_f32_e32 v21, 1.0, v21
	v_add_f32_e32 v24, 1.0, v24
	v_add_f32_e32 v25, 1.0, v25
	v_rcp_f32_e32 v20, v20
	v_rcp_f32_e32 v21, v21
	v_rcp_f32_e32 v24, v24
	v_rcp_f32_e32 v25, v25
	v_pk_mul_f32 v[12:13], v[20:21], v[32:33]
	s_nop 0
	v_pk_add_f32 v[14:15], v[12:13], v[12:13]
	v_mul_f32_e32 v20, 0x3fb8aa3b, v12
	v_mul_f32_e32 v21, 0x3fb8aa3b, v13
	v_exp_f32_e32 v20, v20
	v_exp_f32_e32 v21, v21
	v_mul_f32_e32 v16, 0x3e800000, v14
	v_fma_f32 v17, v14, s5, 1.0
	v_mul_f32_e32 v18, 0x3eaaaaab, v14
	v_fma_f32 v16, v16, v17, 1.0
	v_mul_f32_e32 v17, 0.5, v14
	v_fma_f32 v18, v18, v16, 1.0
	v_fma_f32 v17, v17, v18, 1.0
	v_mul_f32_e64 v17, v17, -v14
	v_fma_f32 v16, -v20, v20, 1.0
	v_cmp_lt_f32_e32 vcc, s6, v14
	v_mul_f32_e32 v19, 0x3e800000, v15
	v_fma_f32 v12, v15, s5, 1.0
	v_cndmask_b32_e32 v16, v16, v17, vcc
	v_mul_f32_e32 v13, 0x3eaaaaab, v15
	v_fma_f32 v19, v19, v12, 1.0
	v_mul_f32_e32 v12, 0.5, v15
	v_fma_f32 v13, v13, v19, 1.0
	v_fma_f32 v12, v12, v13, 1.0
	v_mul_f32_e64 v12, v12, -v15
	v_fma_f32 v13, -v21, v21, 1.0
	v_cmp_lt_f32_e32 vcc, s6, v15
	v_sqrt_f32_e32 v16, v16
	s_nop 1
	v_cndmask_b32_e32 v17, v13, v12, vcc
	v_sqrt_f32_e32 v17, v17
	s_nop 0
	v_pk_mul_f32 v[24:25], v[24:25], v[16:17]
	s_nop 0
	v_pk_mul_f32 v[24:25], v[28:29], v[24:25]
	v_add_f32_e32 v22, v22, v198
	v_add_f32_e32 v23, v23, v199
	v_add_f32_e32 v26, v26, v202
	v_add_f32_e32 v27, v27, v203
	v_mul_f32_e32 v22, 0xbfb8aa3b, v22
	v_mul_f32_e32 v23, 0xbfb8aa3b, v23
	v_mul_f32_e32 v26, 0xbfb8aa3b, v26
	v_mul_f32_e32 v27, 0xbfb8aa3b, v27
	v_exp_f32_e32 v22, v22
	v_exp_f32_e32 v23, v23
	v_exp_f32_e32 v26, v26
	v_exp_f32_e32 v27, v27
	v_add_f32_e32 v22, 1.0, v22
	v_add_f32_e32 v23, 1.0, v23
	v_add_f32_e32 v26, 1.0, v26
	v_add_f32_e32 v27, 1.0, v27
	v_rcp_f32_e32 v22, v22
	v_rcp_f32_e32 v23, v23
	v_rcp_f32_e32 v26, v26
	v_rcp_f32_e32 v27, v27
	v_pk_mul_f32 v[12:13], v[22:23], v[34:35]
	s_nop 0
	v_pk_add_f32 v[14:15], v[12:13], v[12:13]
	v_mul_f32_e32 v22, 0x3fb8aa3b, v12
	v_mul_f32_e32 v23, 0x3fb8aa3b, v13
	v_exp_f32_e32 v22, v22
	v_exp_f32_e32 v23, v23
	v_mul_f32_e32 v16, 0x3e800000, v14
	v_fma_f32 v17, v14, s5, 1.0
	v_mul_f32_e32 v18, 0x3eaaaaab, v14
	v_fma_f32 v16, v16, v17, 1.0
	v_mul_f32_e32 v17, 0.5, v14
	v_fma_f32 v18, v18, v16, 1.0
	v_fma_f32 v17, v17, v18, 1.0
	v_mul_f32_e64 v17, v17, -v14
	v_fma_f32 v16, -v22, v22, 1.0
	v_cmp_lt_f32_e32 vcc, s6, v14
	v_mul_f32_e32 v19, 0x3e800000, v15
	v_fma_f32 v12, v15, s5, 1.0
	v_cndmask_b32_e32 v16, v16, v17, vcc
	v_mul_f32_e32 v13, 0x3eaaaaab, v15
	v_fma_f32 v19, v19, v12, 1.0
	v_mul_f32_e32 v12, 0.5, v15
	v_fma_f32 v13, v13, v19, 1.0
	v_fma_f32 v12, v12, v13, 1.0
	v_mul_f32_e64 v12, v12, -v15
	v_fma_f32 v13, -v23, v23, 1.0
	v_cmp_lt_f32_e32 vcc, s6, v15
	v_sqrt_f32_e32 v16, v16
	s_nop 1
	v_cndmask_b32_e32 v17, v13, v12, vcc
	v_sqrt_f32_e32 v17, v17
	s_nop 0
	v_pk_mul_f32 v[26:27], v[26:27], v[16:17]
	s_nop 0
	v_pk_mul_f32 v[26:27], v[30:31], v[26:27]
	ds_write_b128 v204, v[20:23] offset:38400
	ds_write_b128 v204, v[24:27] offset:54784
	ds_read_b128 v[12:15], v229 offset:29696
	ds_read_b128 v[16:19], v229 offset:29760
	ds_read_b128 v[28:31], v230 offset:16896
	s_waitcnt lgkmcnt(1)
	v_mfma_f32_16x16x32_bf16 v[20:23], v[180:183], v[12:15], 0
	v_mfma_f32_16x16x32_bf16 v[24:27], v[188:191], v[12:15], 0
	v_mfma_f32_16x16x32_bf16 v[20:23], v[184:187], v[16:19], v[20:23]
	v_mfma_f32_16x16x32_bf16 v[24:27], v[192:195], v[16:19], v[24:27]
	s_nop 7
	s_nop 3
	s_waitcnt lgkmcnt(0)
	v_add_f32_e32 v20, v20, v196
	v_add_f32_e32 v21, v21, v197
	v_add_f32_e32 v24, v24, v200
	v_add_f32_e32 v25, v25, v201
	v_mul_f32_e32 v20, 0xbfb8aa3b, v20
	v_mul_f32_e32 v21, 0xbfb8aa3b, v21
	v_mul_f32_e32 v24, 0xbfb8aa3b, v24
	v_mul_f32_e32 v25, 0xbfb8aa3b, v25
	v_exp_f32_e32 v20, v20
	v_exp_f32_e32 v21, v21
	v_exp_f32_e32 v24, v24
	v_exp_f32_e32 v25, v25
	v_add_f32_e32 v20, 1.0, v20
	v_add_f32_e32 v21, 1.0, v21
	v_add_f32_e32 v24, 1.0, v24
	v_add_f32_e32 v25, 1.0, v25
	v_rcp_f32_e32 v20, v20
	v_rcp_f32_e32 v21, v21
	v_rcp_f32_e32 v24, v24
	v_rcp_f32_e32 v25, v25
	v_pk_mul_f32 v[12:13], v[20:21], v[32:33]
	s_nop 0
	v_pk_add_f32 v[14:15], v[12:13], v[12:13]
	v_mul_f32_e32 v20, 0x3fb8aa3b, v12
	v_mul_f32_e32 v21, 0x3fb8aa3b, v13
	v_exp_f32_e32 v20, v20
	v_exp_f32_e32 v21, v21
	v_mul_f32_e32 v16, 0x3e800000, v14
	v_fma_f32 v17, v14, s5, 1.0
	v_mul_f32_e32 v18, 0x3eaaaaab, v14
	v_fma_f32 v16, v16, v17, 1.0
	v_mul_f32_e32 v17, 0.5, v14
	v_fma_f32 v18, v18, v16, 1.0
	v_fma_f32 v17, v17, v18, 1.0
	v_mul_f32_e64 v17, v17, -v14
	v_fma_f32 v16, -v20, v20, 1.0
	v_cmp_lt_f32_e32 vcc, s6, v14
	v_mul_f32_e32 v19, 0x3e800000, v15
	v_fma_f32 v12, v15, s5, 1.0
	v_cndmask_b32_e32 v16, v16, v17, vcc
	v_mul_f32_e32 v13, 0x3eaaaaab, v15
	v_fma_f32 v19, v19, v12, 1.0
	v_mul_f32_e32 v12, 0.5, v15
	v_fma_f32 v13, v13, v19, 1.0
	v_fma_f32 v12, v12, v13, 1.0
	v_mul_f32_e64 v12, v12, -v15
	v_fma_f32 v13, -v21, v21, 1.0
	v_cmp_lt_f32_e32 vcc, s6, v15
	v_sqrt_f32_e32 v16, v16
	s_nop 1
	v_cndmask_b32_e32 v17, v13, v12, vcc
; __device__ __forceinline__ float sigmoidf_(float x) { return __builtin_amdgcn_rcpf(1.0f + __expf(-x)); }
; template <bool FINAL>
; __device__ void phase_lru(const Params& p, int l, unsigned char* smem) {
;     ...
;         for (int et = 0; et < 4; ++et) {
;           f32x4 ar = {0.f, 0.f, 0.f, 0.f}, ai = {0.f, 0.f, 0.f, 0.f};
;           const u16* wr = p.WLRU + ((((size_t)(l * 2 + d) * 2 + 0) * 8 + nb) * 64 + et * 16 + l15) * 64 + g * 8;
;           const u16* wi = p.WLRU + ((((size_t)(l * 2 + d) * 2 + 1) * 8 + nb) * 64 + et * 16 + l15) * 64 + g * 8;
; #pragma unroll
;           for (int ks = 0; ks < 2; ++ks) {
;             ar = mfma16(*(const bf16x8*)(wr + ks * 32), uf[ks], ar);
;             ai = mfma16(*(const bf16x8*)(wi + ks * 32), uf[ks], ai);
;           }
;           const int e0 = et * 16 + 4 * g, ch0 = nb * 64 + e0;
;           const float4 ba4 = *(const float4*)(p.ba + (l * 2 + d) * 512 + ch0);
;           const float4 bx4 = *(const float4*)(p.bx + (l * 2 + d) * 512 + ch0);
;           const float4 sp4 = *(const float4*)(p.SP8 + (l * 2 + d) * 512 + ch0);
;           const float4 uu = *(const float4*)(u32 + t * 64 + e0);
;           const float* bap = (const float*)&ba4; const float* bxp = (const float*)&bx4;
;           const float* spp = (const float*)&sp4; const float* uup = (const float*)&uu;
;           f32x4 av, bv;
; #pragma unroll
;           for (int j = 0; j < 4; ++j) {
;             float r = sigmoidf_(ar[j] + bap[j]);
;             float ig = sigmoidf_(ai[j] + bxp[j]);
;             float la = spp[j] * r;
;             float av_ = __expf(la);
;             float t2 = 2.0f * la;
;             float ser = -t2 * (1.f + t2 * 0.5f * (1.f + t2 * (1.f / 3.f) * (1.f + t2 * 0.25f * (1.f + t2 * 0.2f))));
;             float om = (t2 > -0.25f) ? ser : (1.0f - av_ * av_);
;             av[j] = av_;
;             bv[j] = __builtin_amdgcn_sqrtf(om) * ig * uup[j];
;           }
;           *(f32x4*)(sa + t * 64 + e0) = av;
;           *(f32x4*)(sb + t * 64 + e0) = bv;
;         }
;       }
;       __syncthreads();
	v_sqrt_f32_e32 v17, v17
	s_nop 0
	v_pk_mul_f32 v[24:25], v[24:25], v[16:17]
	s_nop 0
	v_pk_mul_f32 v[24:25], v[28:29], v[24:25]
	v_add_f32_e32 v22, v22, v198
	v_add_f32_e32 v23, v23, v199
	v_add_f32_e32 v26, v26, v202
	v_add_f32_e32 v27, v27, v203
	v_mul_f32_e32 v22, 0xbfb8aa3b, v22
	v_mul_f32_e32 v23, 0xbfb8aa3b, v23
	v_mul_f32_e32 v26, 0xbfb8aa3b, v26
	v_mul_f32_e32 v27, 0xbfb8aa3b, v27
	v_exp_f32_e32 v22, v22
	v_exp_f32_e32 v23, v23
	v_exp_f32_e32 v26, v26
	v_exp_f32_e32 v27, v27
	v_add_f32_e32 v22, 1.0, v22
	v_add_f32_e32 v23, 1.0, v23
	v_add_f32_e32 v26, 1.0, v26
	v_add_f32_e32 v27, 1.0, v27
	v_rcp_f32_e32 v22, v22
	v_rcp_f32_e32 v23, v23
	v_rcp_f32_e32 v26, v26
	v_rcp_f32_e32 v27, v27
	v_pk_mul_f32 v[12:13], v[22:23], v[34:35]
	s_nop 0
	v_pk_add_f32 v[14:15], v[12:13], v[12:13]
	v_mul_f32_e32 v22, 0x3fb8aa3b, v12
	v_mul_f32_e32 v23, 0x3fb8aa3b, v13
	v_exp_f32_e32 v22, v22
	v_exp_f32_e32 v23, v23
	v_mul_f32_e32 v16, 0x3e800000, v14
	v_fma_f32 v17, v14, s5, 1.0
	v_mul_f32_e32 v18, 0x3eaaaaab, v14
	v_fma_f32 v16, v16, v17, 1.0
	v_mul_f32_e32 v17, 0.5, v14
	v_fma_f32 v18, v18, v16, 1.0
	v_fma_f32 v17, v17, v18, 1.0
	v_mul_f32_e64 v17, v17, -v14
	v_fma_f32 v16, -v22, v22, 1.0
	v_cmp_lt_f32_e32 vcc, s6, v14
	v_mul_f32_e32 v19, 0x3e800000, v15
	v_fma_f32 v12, v15, s5, 1.0
	v_cndmask_b32_e32 v16, v16, v17, vcc
	v_mul_f32_e32 v13, 0x3eaaaaab, v15
	v_fma_f32 v19, v19, v12, 1.0
	v_mul_f32_e32 v12, 0.5, v15
	v_fma_f32 v13, v13, v19, 1.0
	v_fma_f32 v12, v12, v13, 1.0
	v_mul_f32_e64 v12, v12, -v15
	v_fma_f32 v13, -v23, v23, 1.0
	v_cmp_lt_f32_e32 vcc, s6, v15
	v_sqrt_f32_e32 v16, v16
	s_nop 1
	v_cndmask_b32_e32 v17, v13, v12, vcc
	v_sqrt_f32_e32 v17, v17
	s_nop 0
	v_pk_mul_f32 v[26:27], v[26:27], v[16:17]
	s_nop 0
	v_pk_mul_f32 v[26:27], v[30:31], v[26:27]
	ds_write_b128 v204, v[20:23] offset:42496
	ds_write_b128 v204, v[24:27] offset:58880
	ds_read_b128 v[12:15], v229 offset:32000
	ds_read_b128 v[16:19], v229 offset:32064
	ds_read_b128 v[28:31], v230 offset:20992
	s_waitcnt lgkmcnt(1)
	v_mfma_f32_16x16x32_bf16 v[20:23], v[180:183], v[12:15], 0
	v_mfma_f32_16x16x32_bf16 v[24:27], v[188:191], v[12:15], 0
	v_mfma_f32_16x16x32_bf16 v[20:23], v[184:187], v[16:19], v[20:23]
	v_mfma_f32_16x16x32_bf16 v[24:27], v[192:195], v[16:19], v[24:27]
	s_nop 7
	s_nop 3
	s_waitcnt lgkmcnt(0)
	v_add_f32_e32 v20, v20, v196
	v_add_f32_e32 v21, v21, v197
	v_add_f32_e32 v24, v24, v200
	v_add_f32_e32 v25, v25, v201
	v_mul_f32_e32 v20, 0xbfb8aa3b, v20
	v_mul_f32_e32 v21, 0xbfb8aa3b, v21
	v_mul_f32_e32 v24, 0xbfb8aa3b, v24
	v_mul_f32_e32 v25, 0xbfb8aa3b, v25
	v_exp_f32_e32 v20, v20
	v_exp_f32_e32 v21, v21
	v_exp_f32_e32 v24, v24
	v_exp_f32_e32 v25, v25
	v_add_f32_e32 v20, 1.0, v20
	v_add_f32_e32 v21, 1.0, v21
	v_add_f32_e32 v24, 1.0, v24
	v_add_f32_e32 v25, 1.0, v25
	v_rcp_f32_e32 v20, v20
	v_rcp_f32_e32 v21, v21
	v_rcp_f32_e32 v24, v24
	v_rcp_f32_e32 v25, v25
	v_pk_mul_f32 v[12:13], v[20:21], v[32:33]
	s_nop 0
	v_pk_add_f32 v[14:15], v[12:13], v[12:13]
	v_mul_f32_e32 v20, 0x3fb8aa3b, v12
	v_mul_f32_e32 v21, 0x3fb8aa3b, v13
	v_exp_f32_e32 v20, v20
	v_exp_f32_e32 v21, v21
	v_mul_f32_e32 v16, 0x3e800000, v14
	v_fma_f32 v17, v14, s5, 1.0
	v_mul_f32_e32 v18, 0x3eaaaaab, v14
	v_fma_f32 v16, v16, v17, 1.0
	v_mul_f32_e32 v17, 0.5, v14
	v_fma_f32 v18, v18, v16, 1.0
	v_fma_f32 v17, v17, v18, 1.0
	v_mul_f32_e64 v17, v17, -v14
	v_fma_f32 v16, -v20, v20, 1.0
	v_cmp_lt_f32_e32 vcc, s6, v14
	v_mul_f32_e32 v19, 0x3e800000, v15
	v_fma_f32 v12, v15, s5, 1.0
	v_cndmask_b32_e32 v16, v16, v17, vcc
	v_mul_f32_e32 v13, 0x3eaaaaab, v15
	v_fma_f32 v19, v19, v12, 1.0
	v_mul_f32_e32 v12, 0.5, v15
	v_fma_f32 v13, v13, v19, 1.0
	v_fma_f32 v12, v12, v13, 1.0
	v_mul_f32_e64 v12, v12, -v15
	v_fma_f32 v13, -v21, v21, 1.0
	v_cmp_lt_f32_e32 vcc, s6, v15
	v_sqrt_f32_e32 v16, v16
	s_nop 1
	v_cndmask_b32_e32 v17, v13, v12, vcc
	v_sqrt_f32_e32 v17, v17
	s_nop 0
	v_pk_mul_f32 v[24:25], v[24:25], v[16:17]
	s_nop 0
	v_pk_mul_f32 v[24:25], v[28:29], v[24:25]
	v_add_f32_e32 v22, v22, v198
	v_add_f32_e32 v23, v23, v199
	v_add_f32_e32 v26, v26, v202
	v_add_f32_e32 v27, v27, v203
	v_mul_f32_e32 v22, 0xbfb8aa3b, v22
	v_mul_f32_e32 v23, 0xbfb8aa3b, v23
	v_mul_f32_e32 v26, 0xbfb8aa3b, v26
	v_mul_f32_e32 v27, 0xbfb8aa3b, v27
	v_exp_f32_e32 v22, v22
	v_exp_f32_e32 v23, v23
	v_exp_f32_e32 v26, v26
	v_exp_f32_e32 v27, v27
	v_add_f32_e32 v22, 1.0, v22
	v_add_f32_e32 v23, 1.0, v23
	v_add_f32_e32 v26, 1.0, v26
	v_add_f32_e32 v27, 1.0, v27
	v_rcp_f32_e32 v22, v22
	v_rcp_f32_e32 v23, v23
	v_rcp_f32_e32 v26, v26
	v_rcp_f32_e32 v27, v27
	v_pk_mul_f32 v[12:13], v[22:23], v[34:35]
	s_nop 0
	v_pk_add_f32 v[14:15], v[12:13], v[12:13]
	v_mul_f32_e32 v22, 0x3fb8aa3b, v12
	v_mul_f32_e32 v23, 0x3fb8aa3b, v13
	v_exp_f32_e32 v22, v22
	v_exp_f32_e32 v23, v23
	v_mul_f32_e32 v16, 0x3e800000, v14
	v_fma_f32 v17, v14, s5, 1.0
	v_mul_f32_e32 v18, 0x3eaaaaab, v14
	v_fma_f32 v16, v16, v17, 1.0
	v_mul_f32_e32 v17, 0.5, v14
	v_fma_f32 v18, v18, v16, 1.0
	v_fma_f32 v17, v17, v18, 1.0
	v_mul_f32_e64 v17, v17, -v14
	v_fma_f32 v16, -v22, v22, 1.0
	v_cmp_lt_f32_e32 vcc, s6, v14
	v_mul_f32_e32 v19, 0x3e800000, v15
	v_fma_f32 v12, v15, s5, 1.0
	v_cndmask_b32_e32 v16, v16, v17, vcc
	v_mul_f32_e32 v13, 0x3eaaaaab, v15
	v_fma_f32 v19, v19, v12, 1.0
	v_mul_f32_e32 v12, 0.5, v15
	v_fma_f32 v13, v13, v19, 1.0
	v_fma_f32 v12, v12, v13, 1.0
	v_mul_f32_e64 v12, v12, -v15
	v_fma_f32 v13, -v23, v23, 1.0
	v_cmp_lt_f32_e32 vcc, s6, v15
	v_sqrt_f32_e32 v16, v16
	s_nop 1
	v_cndmask_b32_e32 v17, v13, v12, vcc
	v_sqrt_f32_e32 v17, v17
	s_nop 0
	v_pk_mul_f32 v[26:27], v[26:27], v[16:17]
	s_nop 0
	v_pk_mul_f32 v[26:27], v[30:31], v[26:27]
	ds_write_b128 v204, v[20:23] offset:46592
	ds_write_b128 v204, v[24:27] offset:62976
	s_waitcnt lgkmcnt(0)
	s_barrier
; template <bool FINAL>
; __device__ void phase_lru(const Params& p, int l, unsigned char* smem) {
;     ...
;       {
;         float A = 1.f, B = 0.f;
;         if (d == 0) {
; #pragma unroll
;           for (int tt = 0; tt < 16; ++tt) { int t = qd * 16 + tt; float a = sa[t * 64 + e_], b = sb[t * 64 + e_]; B = a * B + b; A *= a; }
;         } else {
; #pragma unroll
;     ...
;         }
;         part[(0 * 4 + qd) * 64 + e_] = A;
;         part[(1 * 4 + qd) * 64 + e_] = B;
;       }
;       __syncthreads();
;     ...
;         float h = d ? cin1 : cin0;
;         if (d == 0) {
; #pragma unroll
;           for (int q = 0; q < 4; ++q) if (q < qd) h = part[q * 64 + e_] * h + part[(4 + q) * 64 + e_];
	ds_read2st64_b32 v[12:13], v59 offset0:134 offset1:198
	ds_read2st64_b32 v[14:15], v118 offset0:134 offset1:198
	ds_read2st64_b32 v[16:17], v119 offset0:134 offset1:198
	ds_read2st64_b32 v[64:65], v129 offset0:134 offset1:198
	ds_read2st64_b32 v[66:67], v130 offset0:134 offset1:198
	s_waitcnt lgkmcnt(4)
	v_fmac_f32_e32 v13, 0, v12
	s_waitcnt lgkmcnt(3)
	v_mul_f32_e32 v18, v12, v14
	s_waitcnt lgkmcnt(2)
	v_mul_f32_e32 v20, v18, v16
	ds_read2st64_b32 v[18:19], v120 offset0:134 offset1:198
	v_fmac_f32_e32 v15, v14, v13
	v_fmac_f32_e32 v17, v16, v15
	ds_read2st64_b32 v[68:69], v131 offset0:134 offset1:198
	ds_read2st64_b32 v[70:71], v132 offset0:134 offset1:198
	s_waitcnt lgkmcnt(2)
	v_mul_f32_e32 v22, v20, v18
	ds_read2st64_b32 v[20:21], v121 offset0:134 offset1:198
	v_fmac_f32_e32 v19, v18, v17
	s_waitcnt lgkmcnt(0)
	v_mul_f32_e32 v24, v22, v20
	ds_read2st64_b32 v[22:23], v122 offset0:134 offset1:198
	v_fmac_f32_e32 v21, v20, v19
	s_waitcnt lgkmcnt(0)
	v_mul_f32_e32 v26, v24, v22
	ds_read2st64_b32 v[24:25], v123 offset0:134 offset1:198
	v_fmac_f32_e32 v23, v22, v21
	s_waitcnt lgkmcnt(0)
	v_mul_f32_e32 v28, v26, v24
	ds_read2st64_b32 v[26:27], v124 offset0:134 offset1:198
	v_fmac_f32_e32 v25, v24, v23
	s_waitcnt lgkmcnt(0)
	v_mul_f32_e32 v30, v28, v26
	ds_read2st64_b32 v[28:29], v125 offset0:134 offset1:198
	v_fmac_f32_e32 v27, v26, v25
	s_waitcnt lgkmcnt(0)
	v_mul_f32_e32 v32, v30, v28
	ds_read2st64_b32 v[30:31], v126 offset0:134 offset1:198
	v_fmac_f32_e32 v29, v28, v27
	s_waitcnt lgkmcnt(0)
	v_mul_f32_e32 v34, v32, v30
	ds_read2st64_b32 v[32:33], v127 offset0:134 offset1:198
	v_fmac_f32_e32 v31, v30, v29
	s_waitcnt lgkmcnt(0)
	v_mul_f32_e32 v63, v34, v32
	ds_read2st64_b32 v[34:35], v128 offset0:134 offset1:198
	v_fmac_f32_e32 v33, v32, v31
	s_waitcnt lgkmcnt(0)
	v_mul_f32_e32 v63, v63, v34
	v_mul_f32_e32 v63, v63, v64
	v_fmac_f32_e32 v35, v34, v33
	v_mul_f32_e32 v63, v63, v66
	v_fmac_f32_e32 v65, v64, v35
	v_mul_f32_e32 v63, v63, v68
	v_fmac_f32_e32 v67, v66, v65
	v_mul_f32_e32 v63, v63, v70
	v_fmac_f32_e32 v69, v68, v67
	v_fmac_f32_e32 v71, v70, v69
	ds_write_b32 v98, v63
	ds_write_b32 v100, v71 offset:1024
	s_waitcnt lgkmcnt(0)
	s_barrier
	s_and_saveexec_b64 s[56:57], s[22:23]
	s_cbranch_execnz .LBB0_218
	s_or_b64 exec, exec, s[56:57]
	s_and_saveexec_b64 s[56:57], s[24:25]
	s_cbranch_execnz .LBB0_219

; __device__ __forceinline__ float sigmoidf_(float x) { return __builtin_amdgcn_rcpf(1.0f + __expf(-x)); }
; template <bool FINAL>
; __device__ void phase_lru(const Params& p, int l, unsigned char* smem) {
;     ...
;         for (int et = 0; et < 4; ++et) {
;           f32x4 ar = {0.f, 0.f, 0.f, 0.f}, ai = {0.f, 0.f, 0.f, 0.f};
;           const u16* wr = p.WLRU + ((((size_t)(l * 2 + d) * 2 + 0) * 8 + nb) * 64 + et * 16 + l15) * 64 + g * 8;
;           const u16* wi = p.WLRU + ((((size_t)(l * 2 + d) * 2 + 1) * 8 + nb) * 64 + et * 16 + l15) * 64 + g * 8;
; #pragma unroll
;           for (int ks = 0; ks < 2; ++ks) {
;             ar = mfma16(*(const bf16x8*)(wr + ks * 32), uf[ks], ar);
;             ai = mfma16(*(const bf16x8*)(wi + ks * 32), uf[ks], ai);
;           }
;           const int e0 = et * 16 + 4 * g, ch0 = nb * 64 + e0;
;           const float4 ba4 = *(const float4*)(p.ba + (l * 2 + d) * 512 + ch0);
;           const float4 bx4 = *(const float4*)(p.bx + (l * 2 + d) * 512 + ch0);
;           const float4 sp4 = *(const float4*)(p.SP8 + (l * 2 + d) * 512 + ch0);
;           const float4 uu = *(const float4*)(u32 + t * 64 + e0);
;           const float* bap = (const float*)&ba4; const float* bxp = (const float*)&bx4;
;           const float* spp = (const float*)&sp4; const float* uup = (const float*)&uu;
;           f32x4 av, bv;
; #pragma unroll
;           for (int j = 0; j < 4; ++j) {
;             float r = sigmoidf_(ar[j] + bap[j]);
;             float ig = sigmoidf_(ai[j] + bxp[j]);
;             float la = spp[j] * r;
;             float av_ = __expf(la);
;             float t2 = 2.0f * la;
;             float ser = -t2 * (1.f + t2 * 0.5f * (1.f + t2 * (1.f / 3.f) * (1.f + t2 * 0.25f * (1.f + t2 * 0.2f))));
;             float om = (t2 > -0.25f) ? ser : (1.0f - av_ * av_);
;             av[j] = av_;
;             bv[j] = __builtin_amdgcn_sqrtf(om) * ig * uup[j];
;           }
;           *(f32x4*)(sa + t * 64 + e0) = av;
;           *(f32x4*)(sb + t * 64 + e0) = bv;
;         }
;     ...
;         float h = d ? cin1 : cin0;
;         if (d == 0) {
; #pragma unroll
;           for (int q = 0; q < 4; ++q) if (q < qd) h = part[q * 64 + e_] * h + part[(4 + q) * 64 + e_];
; #pragma unroll
;           for (int tt = 0; tt < 16; ++tt) { int t = qd * 16 + tt; h = sa[t * 64 + e_] * h + sb[t * 64 + e_]; hsum[tt] += h; }
.LBB0_214:
	s_or_b64 exec, exec, s[56:57]
	v_lshl_add_u64 v[20:21], s[64:65], 0, v[144:145]
	v_mov_b32_e32 v63, v145
	v_lshl_add_u64 v[28:29], v[20:21], 0, v[62:63]
	ds_read2st64_b32 v[94:95], v59 offset0:134 offset1:198
	ds_read2st64_b32 v[92:93], v118 offset0:134 offset1:198
	ds_read2st64_b32 v[90:91], v119 offset0:134 offset1:198
	ds_read2st64_b32 v[88:89], v120 offset0:134 offset1:198
	ds_read2st64_b32 v[86:87], v121 offset0:134 offset1:198
	ds_read2st64_b32 v[84:85], v122 offset0:134 offset1:198
	ds_read2st64_b32 v[82:83], v123 offset0:134 offset1:198
	ds_read2st64_b32 v[80:81], v124 offset0:134 offset1:198
	ds_read2st64_b32 v[78:79], v125 offset0:134 offset1:198
	ds_read2st64_b32 v[76:77], v126 offset0:134 offset1:198
	ds_read2st64_b32 v[74:75], v127 offset0:134 offset1:198
	ds_read2st64_b32 v[72:73], v128 offset0:134 offset1:198
	ds_read2st64_b32 v[70:71], v129 offset0:134 offset1:198
	ds_read2st64_b32 v[68:69], v130 offset0:134 offset1:198
	ds_read2st64_b32 v[64:65], v131 offset0:134 offset1:198
	ds_read2st64_b32 v[66:67], v132 offset0:134 offset1:198
	s_waitcnt lgkmcnt(0)
	s_barrier
	s_mov_b32 s5, 0x3e4ccccd
	global_load_dwordx4 v[196:199], v231, s[66:67]
	global_load_dwordx4 v[200:203], v231, s[68:69]
	global_load_dwordx4 v[32:35], v231, s[72:73]
	ds_read_b128 v[12:15], v229 offset:25088
	ds_read_b128 v[16:19], v229 offset:25152
	ds_read_b128 v[28:31], v230 offset:8704
	s_waitcnt lgkmcnt(1)
	v_mfma_f32_16x16x32_bf16 v[20:23], v[232:235], v[12:15], 0
	v_mfma_f32_16x16x32_bf16 v[24:27], v[240:243], v[12:15], 0
	v_mfma_f32_16x16x32_bf16 v[20:23], v[236:239], v[16:19], v[20:23]
	v_mfma_f32_16x16x32_bf16 v[24:27], v[244:247], v[16:19], v[24:27]
	s_waitcnt vmcnt(0)
	s_nop 7
	s_nop 3
	s_waitcnt lgkmcnt(0)
	v_add_f32_e32 v20, v20, v196
	v_add_f32_e32 v21, v21, v197
	v_add_f32_e32 v24, v24, v200
	v_add_f32_e32 v25, v25, v201
	v_mul_f32_e32 v20, 0xbfb8aa3b, v20
	v_mul_f32_e32 v21, 0xbfb8aa3b, v21
	v_mul_f32_e32 v24, 0xbfb8aa3b, v24
	v_mul_f32_e32 v25, 0xbfb8aa3b, v25
	v_exp_f32_e32 v20, v20
	v_exp_f32_e32 v21, v21
	v_exp_f32_e32 v24, v24
	v_exp_f32_e32 v25, v25
	v_add_f32_e32 v20, 1.0, v20
	v_add_f32_e32 v21, 1.0, v21
	v_add_f32_e32 v24, 1.0, v24
	v_add_f32_e32 v25, 1.0, v25
	v_rcp_f32_e32 v20, v20
	v_rcp_f32_e32 v21, v21
	v_rcp_f32_e32 v24, v24
	v_rcp_f32_e32 v25, v25
	v_pk_mul_f32 v[12:13], v[20:21], v[32:33]
	s_nop 0
	v_pk_add_f32 v[14:15], v[12:13], v[12:13]
	v_mul_f32_e32 v20, 0x3fb8aa3b, v12
	v_mul_f32_e32 v21, 0x3fb8aa3b, v13
	v_exp_f32_e32 v20, v20
	v_exp_f32_e32 v21, v21
	v_mul_f32_e32 v16, 0x3e800000, v14
	v_fma_f32 v17, v14, s5, 1.0
	v_mul_f32_e32 v18, 0x3eaaaaab, v14
	v_fma_f32 v16, v16, v17, 1.0
	v_mul_f32_e32 v17, 0.5, v14
	v_fma_f32 v18, v18, v16, 1.0
	v_fma_f32 v17, v17, v18, 1.0
	v_mul_f32_e64 v17, v17, -v14
	v_fma_f32 v16, -v20, v20, 1.0
	v_cmp_lt_f32_e32 vcc, s6, v14
	v_mul_f32_e32 v19, 0x3e800000, v15
	v_fma_f32 v12, v15, s5, 1.0
	v_cndmask_b32_e32 v16, v16, v17, vcc
	v_mul_f32_e32 v13, 0x3eaaaaab, v15
	v_fma_f32 v19, v19, v12, 1.0
	v_mul_f32_e32 v12, 0.5, v15
	v_fma_f32 v13, v13, v19, 1.0
	v_fma_f32 v12, v12, v13, 1.0
	v_mul_f32_e64 v12, v12, -v15
	v_fma_f32 v13, -v21, v21, 1.0
	v_cmp_lt_f32_e32 vcc, s6, v15
	v_sqrt_f32_e32 v16, v16
	s_nop 1
	v_cndmask_b32_e32 v17, v13, v12, vcc
	v_sqrt_f32_e32 v17, v17
	s_nop 0
	v_pk_mul_f32 v[24:25], v[24:25], v[16:17]
	s_nop 0
	v_pk_mul_f32 v[24:25], v[28:29], v[24:25]
	v_add_f32_e32 v22, v22, v198
	v_add_f32_e32 v23, v23, v199
	v_add_f32_e32 v26, v26, v202
	v_add_f32_e32 v27, v27, v203
	v_mul_f32_e32 v22, 0xbfb8aa3b, v22
	v_mul_f32_e32 v23, 0xbfb8aa3b, v23
	v_mul_f32_e32 v26, 0xbfb8aa3b, v26
	v_mul_f32_e32 v27, 0xbfb8aa3b, v27
	v_exp_f32_e32 v22, v22
	v_exp_f32_e32 v23, v23
	v_exp_f32_e32 v26, v26
	v_exp_f32_e32 v27, v27
	v_add_f32_e32 v22, 1.0, v22
	v_add_f32_e32 v23, 1.0, v23
	v_add_f32_e32 v26, 1.0, v26
	v_add_f32_e32 v27, 1.0, v27
	v_rcp_f32_e32 v22, v22
	v_rcp_f32_e32 v23, v23
	v_rcp_f32_e32 v26, v26
	v_rcp_f32_e32 v27, v27
	v_pk_mul_f32 v[12:13], v[22:23], v[34:35]
	s_nop 0
	v_pk_add_f32 v[14:15], v[12:13], v[12:13]
	v_mul_f32_e32 v22, 0x3fb8aa3b, v12
	v_mul_f32_e32 v23, 0x3fb8aa3b, v13
	v_exp_f32_e32 v22, v22
	v_exp_f32_e32 v23, v23
	v_mul_f32_e32 v16, 0x3e800000, v14
	v_fma_f32 v17, v14, s5, 1.0
	v_mul_f32_e32 v18, 0x3eaaaaab, v14
	v_fma_f32 v16, v16, v17, 1.0
	v_mul_f32_e32 v17, 0.5, v14
	v_fma_f32 v18, v18, v16, 1.0
	v_fma_f32 v17, v17, v18, 1.0
	v_mul_f32_e64 v17, v17, -v14
	v_fma_f32 v16, -v22, v22, 1.0
	v_cmp_lt_f32_e32 vcc, s6, v14
	v_mul_f32_e32 v19, 0x3e800000, v15
	v_fma_f32 v12, v15, s5, 1.0
	v_cndmask_b32_e32 v16, v16, v17, vcc
	v_mul_f32_e32 v13, 0x3eaaaaab, v15
	v_fma_f32 v19, v19, v12, 1.0
	v_mul_f32_e32 v12, 0.5, v15
	v_fma_f32 v13, v13, v19, 1.0
	v_fma_f32 v12, v12, v13, 1.0
	v_mul_f32_e64 v12, v12, -v15
	v_fma_f32 v13, -v23, v23, 1.0
	v_cmp_lt_f32_e32 vcc, s6, v15
	v_sqrt_f32_e32 v16, v16
	s_nop 1
	v_cndmask_b32_e32 v17, v13, v12, vcc
	v_sqrt_f32_e32 v17, v17
	s_nop 0
	v_pk_mul_f32 v[26:27], v[26:27], v[16:17]
	s_nop 0
	v_pk_mul_f32 v[26:27], v[30:31], v[26:27]
	ds_write_b128 v204, v[20:23] offset:34304
	ds_write_b128 v204, v[24:27] offset:50688
	ds_read_b128 v[12:15], v229 offset:27392
	ds_read_b128 v[16:19], v229 offset:27456
	ds_read_b128 v[28:31], v230 offset:12800
	s_waitcnt lgkmcnt(1)
	v_mfma_f32_16x16x32_bf16 v[20:23], v[232:235], v[12:15], 0
	v_mfma_f32_16x16x32_bf16 v[24:27], v[240:243], v[12:15], 0
	v_mfma_f32_16x16x32_bf16 v[20:23], v[236:239], v[16:19], v[20:23]
	v_mfma_f32_16x16x32_bf16 v[24:27], v[244:247], v[16:19], v[24:27]
	s_nop 7
	s_nop 3
	s_waitcnt lgkmcnt(0)
; __device__ __forceinline__ float sigmoidf_(float x) { return __builtin_amdgcn_rcpf(1.0f + __expf(-x)); }
; template <bool FINAL>
; __device__ void phase_lru(const Params& p, int l, unsigned char* smem) {
;     ...
;         for (int et = 0; et < 4; ++et) {
;           f32x4 ar = {0.f, 0.f, 0.f, 0.f}, ai = {0.f, 0.f, 0.f, 0.f};
;           const u16* wr = p.WLRU + ((((size_t)(l * 2 + d) * 2 + 0) * 8 + nb) * 64 + et * 16 + l15) * 64 + g * 8;
;           const u16* wi = p.WLRU + ((((size_t)(l * 2 + d) * 2 + 1) * 8 + nb) * 64 + et * 16 + l15) * 64 + g * 8;
; #pragma unroll
;           for (int ks = 0; ks < 2; ++ks) {
;             ar = mfma16(*(const bf16x8*)(wr + ks * 32), uf[ks], ar);
;             ai = mfma16(*(const bf16x8*)(wi + ks * 32), uf[ks], ai);
;           }
;           const int e0 = et * 16 + 4 * g, ch0 = nb * 64 + e0;
;           const float4 ba4 = *(const float4*)(p.ba + (l * 2 + d) * 512 + ch0);
;           const float4 bx4 = *(const float4*)(p.bx + (l * 2 + d) * 512 + ch0);
;           const float4 sp4 = *(const float4*)(p.SP8 + (l * 2 + d) * 512 + ch0);
;           const float4 uu = *(const float4*)(u32 + t * 64 + e0);
;           const float* bap = (const float*)&ba4; const float* bxp = (const float*)&bx4;
;           const float* spp = (const float*)&sp4; const float* uup = (const float*)&uu;
;           f32x4 av, bv;
; #pragma unroll
;           for (int j = 0; j < 4; ++j) {
;             float r = sigmoidf_(ar[j] + bap[j]);
;             float ig = sigmoidf_(ai[j] + bxp[j]);
;             float la = spp[j] * r;
;             float av_ = __expf(la);
;             float t2 = 2.0f * la;
;             float ser = -t2 * (1.f + t2 * 0.5f * (1.f + t2 * (1.f / 3.f) * (1.f + t2 * 0.25f * (1.f + t2 * 0.2f))));
;             float om = (t2 > -0.25f) ? ser : (1.0f - av_ * av_);
;             av[j] = av_;
;             bv[j] = __builtin_amdgcn_sqrtf(om) * ig * uup[j];
;           }
;           *(f32x4*)(sa + t * 64 + e0) = av;
;           *(f32x4*)(sb + t * 64 + e0) = bv;
;         }
	v_add_f32_e32 v20, v20, v196
	v_add_f32_e32 v21, v21, v197
	v_add_f32_e32 v24, v24, v200
	v_add_f32_e32 v25, v25, v201
	v_mul_f32_e32 v20, 0xbfb8aa3b, v20
	v_mul_f32_e32 v21, 0xbfb8aa3b, v21
	v_mul_f32_e32 v24, 0xbfb8aa3b, v24
	v_mul_f32_e32 v25, 0xbfb8aa3b, v25
	v_exp_f32_e32 v20, v20
	v_exp_f32_e32 v21, v21
	v_exp_f32_e32 v24, v24
	v_exp_f32_e32 v25, v25
	v_add_f32_e32 v20, 1.0, v20
	v_add_f32_e32 v21, 1.0, v21
	v_add_f32_e32 v24, 1.0, v24
	v_add_f32_e32 v25, 1.0, v25
	v_rcp_f32_e32 v20, v20
	v_rcp_f32_e32 v21, v21
	v_rcp_f32_e32 v24, v24
	v_rcp_f32_e32 v25, v25
	v_pk_mul_f32 v[12:13], v[20:21], v[32:33]
	s_nop 0
	v_pk_add_f32 v[14:15], v[12:13], v[12:13]
	v_mul_f32_e32 v20, 0x3fb8aa3b, v12
	v_mul_f32_e32 v21, 0x3fb8aa3b, v13
	v_exp_f32_e32 v20, v20
	v_exp_f32_e32 v21, v21
	v_mul_f32_e32 v16, 0x3e800000, v14
	v_fma_f32 v17, v14, s5, 1.0
	v_mul_f32_e32 v18, 0x3eaaaaab, v14
	v_fma_f32 v16, v16, v17, 1.0
	v_mul_f32_e32 v17, 0.5, v14
	v_fma_f32 v18, v18, v16, 1.0
	v_fma_f32 v17, v17, v18, 1.0
	v_mul_f32_e64 v17, v17, -v14
	v_fma_f32 v16, -v20, v20, 1.0
	v_cmp_lt_f32_e32 vcc, s6, v14
	v_mul_f32_e32 v19, 0x3e800000, v15
	v_fma_f32 v12, v15, s5, 1.0
	v_cndmask_b32_e32 v16, v16, v17, vcc
	v_mul_f32_e32 v13, 0x3eaaaaab, v15
	v_fma_f32 v19, v19, v12, 1.0
	v_mul_f32_e32 v12, 0.5, v15
	v_fma_f32 v13, v13, v19, 1.0
	v_fma_f32 v12, v12, v13, 1.0
	v_mul_f32_e64 v12, v12, -v15
	v_fma_f32 v13, -v21, v21, 1.0
	v_cmp_lt_f32_e32 vcc, s6, v15
	v_sqrt_f32_e32 v16, v16
	s_nop 1
	v_cndmask_b32_e32 v17, v13, v12, vcc
	v_sqrt_f32_e32 v17, v17
	s_nop 0
	v_pk_mul_f32 v[24:25], v[24:25], v[16:17]
	s_nop 0
	v_pk_mul_f32 v[24:25], v[28:29], v[24:25]
	v_add_f32_e32 v22, v22, v198
	v_add_f32_e32 v23, v23, v199
	v_add_f32_e32 v26, v26, v202
	v_add_f32_e32 v27, v27, v203
	v_mul_f32_e32 v22, 0xbfb8aa3b, v22
	v_mul_f32_e32 v23, 0xbfb8aa3b, v23
	v_mul_f32_e32 v26, 0xbfb8aa3b, v26
	v_mul_f32_e32 v27, 0xbfb8aa3b, v27
	v_exp_f32_e32 v22, v22
	v_exp_f32_e32 v23, v23
	v_exp_f32_e32 v26, v26
	v_exp_f32_e32 v27, v27
	v_add_f32_e32 v22, 1.0, v22
	v_add_f32_e32 v23, 1.0, v23
	v_add_f32_e32 v26, 1.0, v26
	v_add_f32_e32 v27, 1.0, v27
	v_rcp_f32_e32 v22, v22
	v_rcp_f32_e32 v23, v23
	v_rcp_f32_e32 v26, v26
	v_rcp_f32_e32 v27, v27
	v_pk_mul_f32 v[12:13], v[22:23], v[34:35]
	s_nop 0
	v_pk_add_f32 v[14:15], v[12:13], v[12:13]
	v_mul_f32_e32 v22, 0x3fb8aa3b, v12
	v_mul_f32_e32 v23, 0x3fb8aa3b, v13
	v_exp_f32_e32 v22, v22
	v_exp_f32_e32 v23, v23
	v_mul_f32_e32 v16, 0x3e800000, v14
	v_fma_f32 v17, v14, s5, 1.0
	v_mul_f32_e32 v18, 0x3eaaaaab, v14
	v_fma_f32 v16, v16, v17, 1.0
	v_mul_f32_e32 v17, 0.5, v14
	v_fma_f32 v18, v18, v16, 1.0
	v_fma_f32 v17, v17, v18, 1.0
	v_mul_f32_e64 v17, v17, -v14
	v_fma_f32 v16, -v22, v22, 1.0
	v_cmp_lt_f32_e32 vcc, s6, v14
	v_mul_f32_e32 v19, 0x3e800000, v15
	v_fma_f32 v12, v15, s5, 1.0
	v_cndmask_b32_e32 v16, v16, v17, vcc
	v_mul_f32_e32 v13, 0x3eaaaaab, v15
	v_fma_f32 v19, v19, v12, 1.0
	v_mul_f32_e32 v12, 0.5, v15
	v_fma_f32 v13, v13, v19, 1.0
	v_fma_f32 v12, v12, v13, 1.0
	v_mul_f32_e64 v12, v12, -v15
	v_fma_f32 v13, -v23, v23, 1.0
	v_cmp_lt_f32_e32 vcc, s6, v15
	v_sqrt_f32_e32 v16, v16
	s_nop 1
	v_cndmask_b32_e32 v17, v13, v12, vcc
	v_sqrt_f32_e32 v17, v17
	s_nop 0
	v_pk_mul_f32 v[26:27], v[26:27], v[16:17]
	s_nop 0
	v_pk_mul_f32 v[26:27], v[30:31], v[26:27]
	ds_write_b128 v204, v[20:23] offset:38400
	ds_write_b128 v204, v[24:27] offset:54784
	ds_read_b128 v[12:15], v229 offset:29696
	ds_read_b128 v[16:19], v229 offset:29760
	ds_read_b128 v[28:31], v230 offset:16896
	s_waitcnt lgkmcnt(1)
	v_mfma_f32_16x16x32_bf16 v[20:23], v[232:235], v[12:15], 0
	v_mfma_f32_16x16x32_bf16 v[24:27], v[240:243], v[12:15], 0
	v_mfma_f32_16x16x32_bf16 v[20:23], v[236:239], v[16:19], v[20:23]
	v_mfma_f32_16x16x32_bf16 v[24:27], v[244:247], v[16:19], v[24:27]
	s_nop 7
	s_nop 3
	s_waitcnt lgkmcnt(0)
	v_add_f32_e32 v20, v20, v196
	v_add_f32_e32 v21, v21, v197
	v_add_f32_e32 v24, v24, v200
	v_add_f32_e32 v25, v25, v201
	v_mul_f32_e32 v20, 0xbfb8aa3b, v20
	v_mul_f32_e32 v21, 0xbfb8aa3b, v21
	v_mul_f32_e32 v24, 0xbfb8aa3b, v24
	v_mul_f32_e32 v25, 0xbfb8aa3b, v25
	v_exp_f32_e32 v20, v20
	v_exp_f32_e32 v21, v21
	v_exp_f32_e32 v24, v24
	v_exp_f32_e32 v25, v25
	v_add_f32_e32 v20, 1.0, v20
	v_add_f32_e32 v21, 1.0, v21
	v_add_f32_e32 v24, 1.0, v24
	v_add_f32_e32 v25, 1.0, v25
	v_rcp_f32_e32 v20, v20
	v_rcp_f32_e32 v21, v21
	v_rcp_f32_e32 v24, v24
	v_rcp_f32_e32 v25, v25
	v_pk_mul_f32 v[12:13], v[20:21], v[32:33]
	s_nop 0
	v_pk_add_f32 v[14:15], v[12:13], v[12:13]
	v_mul_f32_e32 v20, 0x3fb8aa3b, v12
	v_mul_f32_e32 v21, 0x3fb8aa3b, v13
	v_exp_f32_e32 v20, v20
	v_exp_f32_e32 v21, v21
	v_mul_f32_e32 v16, 0x3e800000, v14
	v_fma_f32 v17, v14, s5, 1.0
	v_mul_f32_e32 v18, 0x3eaaaaab, v14
	v_fma_f32 v16, v16, v17, 1.0
	v_mul_f32_e32 v17, 0.5, v14
	v_fma_f32 v18, v18, v16, 1.0
	v_fma_f32 v17, v17, v18, 1.0
	v_mul_f32_e64 v17, v17, -v14
	v_fma_f32 v16, -v20, v20, 1.0
	v_cmp_lt_f32_e32 vcc, s6, v14
	v_mul_f32_e32 v19, 0x3e800000, v15
	v_fma_f32 v12, v15, s5, 1.0
	v_cndmask_b32_e32 v16, v16, v17, vcc
	v_mul_f32_e32 v13, 0x3eaaaaab, v15
	v_fma_f32 v19, v19, v12, 1.0
	v_mul_f32_e32 v12, 0.5, v15
	v_fma_f32 v13, v13, v19, 1.0
	v_fma_f32 v12, v12, v13, 1.0
	v_mul_f32_e64 v12, v12, -v15
	v_fma_f32 v13, -v21, v21, 1.0
	v_cmp_lt_f32_e32 vcc, s6, v15
	v_sqrt_f32_e32 v16, v16
	s_nop 1
	v_cndmask_b32_e32 v17, v13, v12, vcc
	v_sqrt_f32_e32 v17, v17
	s_nop 0
	v_pk_mul_f32 v[24:25], v[24:25], v[16:17]
	s_nop 0
	v_pk_mul_f32 v[24:25], v[28:29], v[24:25]
	v_add_f32_e32 v22, v22, v198
	v_add_f32_e32 v23, v23, v199
	v_add_f32_e32 v26, v26, v202
	v_add_f32_e32 v27, v27, v203
	v_mul_f32_e32 v22, 0xbfb8aa3b, v22
; __device__ __forceinline__ float sigmoidf_(float x) { return __builtin_amdgcn_rcpf(1.0f + __expf(-x)); }
; template <bool FINAL>
; __device__ void phase_lru(const Params& p, int l, unsigned char* smem) {
;     ...
;         for (int et = 0; et < 4; ++et) {
;           f32x4 ar = {0.f, 0.f, 0.f, 0.f}, ai = {0.f, 0.f, 0.f, 0.f};
;           const u16* wr = p.WLRU + ((((size_t)(l * 2 + d) * 2 + 0) * 8 + nb) * 64 + et * 16 + l15) * 64 + g * 8;
;           const u16* wi = p.WLRU + ((((size_t)(l * 2 + d) * 2 + 1) * 8 + nb) * 64 + et * 16 + l15) * 64 + g * 8;
; #pragma unroll
;           for (int ks = 0; ks < 2; ++ks) {
;             ar = mfma16(*(const bf16x8*)(wr + ks * 32), uf[ks], ar);
;             ai = mfma16(*(const bf16x8*)(wi + ks * 32), uf[ks], ai);
;           }
;           const int e0 = et * 16 + 4 * g, ch0 = nb * 64 + e0;
;           const float4 ba4 = *(const float4*)(p.ba + (l * 2 + d) * 512 + ch0);
;           const float4 bx4 = *(const float4*)(p.bx + (l * 2 + d) * 512 + ch0);
;           const float4 sp4 = *(const float4*)(p.SP8 + (l * 2 + d) * 512 + ch0);
;           const float4 uu = *(const float4*)(u32 + t * 64 + e0);
;           const float* bap = (const float*)&ba4; const float* bxp = (const float*)&bx4;
;           const float* spp = (const float*)&sp4; const float* uup = (const float*)&uu;
;           f32x4 av, bv;
; #pragma unroll
;           for (int j = 0; j < 4; ++j) {
;             float r = sigmoidf_(ar[j] + bap[j]);
;             float ig = sigmoidf_(ai[j] + bxp[j]);
;             float la = spp[j] * r;
;             float av_ = __expf(la);
;             float t2 = 2.0f * la;
;             float ser = -t2 * (1.f + t2 * 0.5f * (1.f + t2 * (1.f / 3.f) * (1.f + t2 * 0.25f * (1.f + t2 * 0.2f))));
;             float om = (t2 > -0.25f) ? ser : (1.0f - av_ * av_);
;             av[j] = av_;
;             bv[j] = __builtin_amdgcn_sqrtf(om) * ig * uup[j];
;           }
;           *(f32x4*)(sa + t * 64 + e0) = av;
;           *(f32x4*)(sb + t * 64 + e0) = bv;
;         }
;       }
;       __syncthreads();
	v_mul_f32_e32 v23, 0xbfb8aa3b, v23
	v_mul_f32_e32 v26, 0xbfb8aa3b, v26
	v_mul_f32_e32 v27, 0xbfb8aa3b, v27
	v_exp_f32_e32 v22, v22
	v_exp_f32_e32 v23, v23
	v_exp_f32_e32 v26, v26
	v_exp_f32_e32 v27, v27
	v_add_f32_e32 v22, 1.0, v22
	v_add_f32_e32 v23, 1.0, v23
	v_add_f32_e32 v26, 1.0, v26
	v_add_f32_e32 v27, 1.0, v27
	v_rcp_f32_e32 v22, v22
	v_rcp_f32_e32 v23, v23
	v_rcp_f32_e32 v26, v26
	v_rcp_f32_e32 v27, v27
	v_pk_mul_f32 v[12:13], v[22:23], v[34:35]
	s_nop 0
	v_pk_add_f32 v[14:15], v[12:13], v[12:13]
	v_mul_f32_e32 v22, 0x3fb8aa3b, v12
	v_mul_f32_e32 v23, 0x3fb8aa3b, v13
	v_exp_f32_e32 v22, v22
	v_exp_f32_e32 v23, v23
	v_mul_f32_e32 v16, 0x3e800000, v14
	v_fma_f32 v17, v14, s5, 1.0
	v_mul_f32_e32 v18, 0x3eaaaaab, v14
	v_fma_f32 v16, v16, v17, 1.0
	v_mul_f32_e32 v17, 0.5, v14
	v_fma_f32 v18, v18, v16, 1.0
	v_fma_f32 v17, v17, v18, 1.0
	v_mul_f32_e64 v17, v17, -v14
	v_fma_f32 v16, -v22, v22, 1.0
	v_cmp_lt_f32_e32 vcc, s6, v14
	v_mul_f32_e32 v19, 0x3e800000, v15
	v_fma_f32 v12, v15, s5, 1.0
	v_cndmask_b32_e32 v16, v16, v17, vcc
	v_mul_f32_e32 v13, 0x3eaaaaab, v15
	v_fma_f32 v19, v19, v12, 1.0
	v_mul_f32_e32 v12, 0.5, v15
	v_fma_f32 v13, v13, v19, 1.0
	v_fma_f32 v12, v12, v13, 1.0
	v_mul_f32_e64 v12, v12, -v15
	v_fma_f32 v13, -v23, v23, 1.0
	v_cmp_lt_f32_e32 vcc, s6, v15
	v_sqrt_f32_e32 v16, v16
	s_nop 1
	v_cndmask_b32_e32 v17, v13, v12, vcc
	v_sqrt_f32_e32 v17, v17
	s_nop 0
	v_pk_mul_f32 v[26:27], v[26:27], v[16:17]
	s_nop 0
	v_pk_mul_f32 v[26:27], v[30:31], v[26:27]
	ds_write_b128 v204, v[20:23] offset:42496
	ds_write_b128 v204, v[24:27] offset:58880
	ds_read_b128 v[12:15], v229 offset:32000
	ds_read_b128 v[16:19], v229 offset:32064
	ds_read_b128 v[28:31], v230 offset:20992
	s_waitcnt lgkmcnt(1)
	v_mfma_f32_16x16x32_bf16 v[20:23], v[232:235], v[12:15], 0
	v_mfma_f32_16x16x32_bf16 v[24:27], v[240:243], v[12:15], 0
	v_mfma_f32_16x16x32_bf16 v[20:23], v[236:239], v[16:19], v[20:23]
	v_mfma_f32_16x16x32_bf16 v[24:27], v[244:247], v[16:19], v[24:27]
	s_nop 7
	s_nop 3
	s_waitcnt lgkmcnt(0)
	v_add_f32_e32 v20, v20, v196
	v_add_f32_e32 v21, v21, v197
	v_add_f32_e32 v24, v24, v200
	v_add_f32_e32 v25, v25, v201
	v_mul_f32_e32 v20, 0xbfb8aa3b, v20
	v_mul_f32_e32 v21, 0xbfb8aa3b, v21
	v_mul_f32_e32 v24, 0xbfb8aa3b, v24
	v_mul_f32_e32 v25, 0xbfb8aa3b, v25
	v_exp_f32_e32 v20, v20
	v_exp_f32_e32 v21, v21
	v_exp_f32_e32 v24, v24
	v_exp_f32_e32 v25, v25
	v_add_f32_e32 v20, 1.0, v20
	v_add_f32_e32 v21, 1.0, v21
	v_add_f32_e32 v24, 1.0, v24
	v_add_f32_e32 v25, 1.0, v25
	v_rcp_f32_e32 v20, v20
	v_rcp_f32_e32 v21, v21
	v_rcp_f32_e32 v24, v24
	v_rcp_f32_e32 v25, v25
	v_pk_mul_f32 v[12:13], v[20:21], v[32:33]
	s_nop 0
	v_pk_add_f32 v[14:15], v[12:13], v[12:13]
	v_mul_f32_e32 v20, 0x3fb8aa3b, v12
	v_mul_f32_e32 v21, 0x3fb8aa3b, v13
	v_exp_f32_e32 v20, v20
	v_exp_f32_e32 v21, v21
	v_mul_f32_e32 v16, 0x3e800000, v14
	v_fma_f32 v17, v14, s5, 1.0
	v_mul_f32_e32 v18, 0x3eaaaaab, v14
	v_fma_f32 v16, v16, v17, 1.0
	v_mul_f32_e32 v17, 0.5, v14
	v_fma_f32 v18, v18, v16, 1.0
	v_fma_f32 v17, v17, v18, 1.0
	v_mul_f32_e64 v17, v17, -v14
	v_fma_f32 v16, -v20, v20, 1.0
	v_cmp_lt_f32_e32 vcc, s6, v14
	v_mul_f32_e32 v19, 0x3e800000, v15
	v_fma_f32 v12, v15, s5, 1.0
	v_cndmask_b32_e32 v16, v16, v17, vcc
	v_mul_f32_e32 v13, 0x3eaaaaab, v15
	v_fma_f32 v19, v19, v12, 1.0
	v_mul_f32_e32 v12, 0.5, v15
	v_fma_f32 v13, v13, v19, 1.0
	v_fma_f32 v12, v12, v13, 1.0
	v_mul_f32_e64 v12, v12, -v15
	v_fma_f32 v13, -v21, v21, 1.0
	v_cmp_lt_f32_e32 vcc, s6, v15
	v_sqrt_f32_e32 v16, v16
	s_nop 1
	v_cndmask_b32_e32 v17, v13, v12, vcc
	v_sqrt_f32_e32 v17, v17
	s_nop 0
	v_pk_mul_f32 v[24:25], v[24:25], v[16:17]
	s_nop 0
	v_pk_mul_f32 v[24:25], v[28:29], v[24:25]
	v_add_f32_e32 v22, v22, v198
	v_add_f32_e32 v23, v23, v199
	v_add_f32_e32 v26, v26, v202
	v_add_f32_e32 v27, v27, v203
	v_mul_f32_e32 v22, 0xbfb8aa3b, v22
	v_mul_f32_e32 v23, 0xbfb8aa3b, v23
	v_mul_f32_e32 v26, 0xbfb8aa3b, v26
	v_mul_f32_e32 v27, 0xbfb8aa3b, v27
	v_exp_f32_e32 v22, v22
	v_exp_f32_e32 v23, v23
	v_exp_f32_e32 v26, v26
	v_exp_f32_e32 v27, v27
	v_add_f32_e32 v22, 1.0, v22
	v_add_f32_e32 v23, 1.0, v23
	v_add_f32_e32 v26, 1.0, v26
	v_add_f32_e32 v27, 1.0, v27
	v_rcp_f32_e32 v22, v22
	v_rcp_f32_e32 v23, v23
	v_rcp_f32_e32 v26, v26
	v_rcp_f32_e32 v27, v27
	v_pk_mul_f32 v[12:13], v[22:23], v[34:35]
	s_nop 0
	v_pk_add_f32 v[14:15], v[12:13], v[12:13]
	v_mul_f32_e32 v22, 0x3fb8aa3b, v12
	v_mul_f32_e32 v23, 0x3fb8aa3b, v13
	v_exp_f32_e32 v22, v22
	v_exp_f32_e32 v23, v23
	v_mul_f32_e32 v16, 0x3e800000, v14
	v_fma_f32 v17, v14, s5, 1.0
	v_mul_f32_e32 v18, 0x3eaaaaab, v14
	v_fma_f32 v16, v16, v17, 1.0
	v_mul_f32_e32 v17, 0.5, v14
	v_fma_f32 v18, v18, v16, 1.0
	v_fma_f32 v17, v17, v18, 1.0
	v_mul_f32_e64 v17, v17, -v14
	v_fma_f32 v16, -v22, v22, 1.0
	v_cmp_lt_f32_e32 vcc, s6, v14
	v_mul_f32_e32 v19, 0x3e800000, v15
	v_fma_f32 v12, v15, s5, 1.0
	v_cndmask_b32_e32 v16, v16, v17, vcc
	v_mul_f32_e32 v13, 0x3eaaaaab, v15
	v_fma_f32 v19, v19, v12, 1.0
	v_mul_f32_e32 v12, 0.5, v15
	v_fma_f32 v13, v13, v19, 1.0
	v_fma_f32 v12, v12, v13, 1.0
	v_mul_f32_e64 v12, v12, -v15
	v_fma_f32 v13, -v23, v23, 1.0
	v_cmp_lt_f32_e32 vcc, s6, v15
	v_sqrt_f32_e32 v16, v16
	s_nop 1
	v_cndmask_b32_e32 v17, v13, v12, vcc
	v_sqrt_f32_e32 v17, v17
	s_nop 0
	v_pk_mul_f32 v[26:27], v[26:27], v[16:17]
	s_nop 0
	v_pk_mul_f32 v[26:27], v[30:31], v[26:27]
	ds_write_b128 v204, v[20:23] offset:46592
	ds_write_b128 v204, v[24:27] offset:62976
	s_waitcnt lgkmcnt(0)
	s_barrier
; template <bool FINAL>
; __device__ void phase_lru(const Params& p, int l, unsigned char* smem) {
;     ...
;       {
;         float A = 1.f, B = 0.f;
;         if (d == 0) {
; #pragma unroll
;           for (int tt = 0; tt < 16; ++tt) { int t = qd * 16 + tt; float a = sa[t * 64 + e_], b = sb[t * 64 + e_]; B = a * B + b; A *= a; }
;         } else {
; #pragma unroll
;     ...
;         }
;         part[(0 * 4 + qd) * 64 + e_] = A;
;         part[(1 * 4 + qd) * 64 + e_] = B;
;       }
;       __syncthreads();
;     ...
; #pragma unroll
;           for (int q = 3; q >= 0; --q) if (q > qd) h = part[q * 64 + e_] * h + part[(4 + q) * 64 + e_];
	ds_read2st64_b32 v[12:13], v132 offset0:134 offset1:198
	ds_read2st64_b32 v[14:15], v131 offset0:134 offset1:198
	ds_read2st64_b32 v[16:17], v130 offset0:134 offset1:198
	ds_read2st64_b32 v[62:63], v120 offset0:134 offset1:198
	ds_read2st64_b32 v[164:165], v119 offset0:134 offset1:198
	s_waitcnt lgkmcnt(4)
	v_fmac_f32_e32 v13, 0, v12
	s_waitcnt lgkmcnt(3)
	v_mul_f32_e32 v18, v12, v14
	s_waitcnt lgkmcnt(2)
	v_mul_f32_e32 v20, v18, v16
	ds_read2st64_b32 v[18:19], v129 offset0:134 offset1:198
	v_fmac_f32_e32 v15, v14, v13
	v_fmac_f32_e32 v17, v16, v15
	ds_read2st64_b32 v[166:167], v118 offset0:134 offset1:198
	ds_read2st64_b32 v[168:169], v59 offset0:134 offset1:198
	s_waitcnt lgkmcnt(2)
	v_mul_f32_e32 v22, v20, v18
	ds_read2st64_b32 v[20:21], v128 offset0:134 offset1:198
	v_fmac_f32_e32 v19, v18, v17
	s_waitcnt lgkmcnt(0)
	v_mul_f32_e32 v24, v22, v20
	ds_read2st64_b32 v[22:23], v127 offset0:134 offset1:198
	v_fmac_f32_e32 v21, v20, v19
	s_waitcnt lgkmcnt(0)
	v_mul_f32_e32 v26, v24, v22
	ds_read2st64_b32 v[24:25], v126 offset0:134 offset1:198
	v_fmac_f32_e32 v23, v22, v21
	s_waitcnt lgkmcnt(0)
	v_mul_f32_e32 v28, v26, v24
	ds_read2st64_b32 v[26:27], v125 offset0:134 offset1:198
	v_fmac_f32_e32 v25, v24, v23
	s_waitcnt lgkmcnt(0)
	v_mul_f32_e32 v30, v28, v26
	ds_read2st64_b32 v[28:29], v124 offset0:134 offset1:198
	v_fmac_f32_e32 v27, v26, v25
	s_waitcnt lgkmcnt(0)
	v_mul_f32_e32 v32, v30, v28
	ds_read2st64_b32 v[30:31], v123 offset0:134 offset1:198
	v_fmac_f32_e32 v29, v28, v27
	s_waitcnt lgkmcnt(0)
	v_mul_f32_e32 v34, v32, v30
	ds_read2st64_b32 v[32:33], v122 offset0:134 offset1:198
	v_fmac_f32_e32 v31, v30, v29
	s_waitcnt lgkmcnt(0)
	v_mul_f32_e32 v61, v34, v32
	ds_read2st64_b32 v[34:35], v121 offset0:134 offset1:198
	v_fmac_f32_e32 v33, v32, v31
	s_waitcnt lgkmcnt(0)
	v_mul_f32_e32 v61, v61, v34
	v_mul_f32_e32 v61, v61, v62
	v_fmac_f32_e32 v35, v34, v33
	v_mul_f32_e32 v61, v61, v164
	v_fmac_f32_e32 v63, v62, v35
	v_mul_f32_e32 v61, v61, v166
	v_fmac_f32_e32 v165, v164, v63
	v_mul_f32_e32 v61, v61, v168
	v_fmac_f32_e32 v167, v166, v165
	v_fmac_f32_e32 v169, v168, v167
	ds_write_b32 v98, v61
	ds_write_b32 v100, v169 offset:1024
	s_waitcnt lgkmcnt(0)
	s_barrier
	s_and_saveexec_b64 s[56:57], s[48:49]
	s_cbranch_execnz .LBB0_221
	s_or_b64 exec, exec, s[56:57]
	s_and_saveexec_b64 s[56:57], s[50:51]
	s_cbranch_execnz .LBB0_222

; __device__ __forceinline__ int TIDX() { int t = threadIdx.x; asm volatile("" : "+v"(t)); return t; }
; __device__ __forceinline__ int BIDX() { int b = blockIdx.x; asm volatile("" : "+s"(b)); return b; }
; template <bool FINAL>
; __device__ void phase_lru(const Params& p, int l, unsigned char* smem) {
;   u16* xs = (u16*)smem;
;   float* u32 = (float*)(smem + 8704);
;   u16* ub = (u16*)(smem + 25088);
;   float* sa = (float*)(smem + 34304);
;   float* sb = (float*)(smem + 50688);
;   float* part = (float*)(smem + 67072);
;   const int tid = TIDX(), lane = tid & 63, w = tid >> 6, l15 = lane & 15, g = lane >> 4;
;   const int e_ = tid & 63, qd = tid >> 6;
;   const int NIT = NCHUNK * 8;
;   const int step = gridDim.x;
;   int it = BIDX();
;   uint4 x0 = make_uint4(0, 0, 0, 0), x1 = x0, x2 = x0;
;   auto load_x = [&](int item, uint4& a0, uint4& a1, uint4& a2) {
;     const int ci = item >> 3, nb = item & 7;
;     const int tb = ci * 64, pos0 = tok_pos(tb), S = tok_len(tb);
;     const u16* zb = p.Z + (long)(tb - 2) * DIN + C_LX + nb * 64;
;     { int idx = tid, r = idx >> 3, ch = idx & 7, pp = pos0 - 2 + r;
;       a0 = (pp >= 0 && pp < S) ? *(const uint4*)(zb + (long)r * DIN + ch * 8) : make_uint4(0, 0, 0, 0); }
;     { int idx = tid + 256, r = idx >> 3, ch = idx & 7, pp = pos0 - 2 + r;
;       a1 = (pp >= 0 && pp < S) ? *(const uint4*)(zb + (long)r * DIN + ch * 8) : make_uint4(0, 0, 0, 0); }
;     { int idx = tid + 512, r = idx >> 3, ch = idx & 7, pp = pos0 - 2 + r;
;       a2 = (idx < 67 * 8 && pp >= 0 && pp < S) ? *(const uint4*)(zb + (long)r * DIN + ch * 8) : make_uint4(0, 0, 0, 0); }
;   };
;   if (it < NIT) load_x(it, x0, x1, x2);
;     ...
;       {
;         float A = 1.f, B = 0.f;
;         if (d == 0) {
; #pragma unroll
;           for (int tt = 0; tt < 16; ++tt) { int t = qd * 16 + tt; float a = sa[t * 64 + e_], b = sb[t * 64 + e_]; B = a * B + b; A *= a; }
;         } else {
; #pragma unroll
;     ...
;         }
;         part[(0 * 4 + qd) * 64 + e_] = A;
;         part[(1 * 4 + qd) * 64 + e_] = B;
.LBB0_373:
	s_or_b64 exec, exec, s[40:41]
	v_and_b32_e32 v59, 63, v45
	v_and_b32_e32 v12, 0x7fffffc0, v12
	v_ashrrev_i32_e32 v13, 6, v45
	v_lshlrev_b32_e32 v16, 1, v59
	v_lshlrev_b32_e32 v12, 1, v12
	v_lshlrev_b32_e32 v18, 1, v144
	v_and_b32_e32 v60, 15, v45
	v_add_u32_e32 v17, 0, v16
	v_add3_u32 v61, 0, v12, v18
	v_lshlrev_b32_e32 v18, 4, v13
	v_add_u32_e32 v62, v17, v16
	v_or_b32_e32 v16, v18, v60
	v_mul_lo_u32 v19, v16, s28
	v_and_b32_e32 v20, 48, v45
	v_bfe_u32 v14, v45, 4, 2
	v_add3_u32 v46, 0, v19, v20
	v_and_b32_e32 v19, 0x3fffffc0, v45
	s_lshl_b32 s36, s72, 6
	s_and_b32 s30, 0xffff, s42
	v_lshlrev_b32_e32 v44, 3, v14
	v_lshlrev_b32_e32 v63, 2, v14
	v_lshlrev_b32_e32 v14, 2, v45
	v_readlane_b32 s4, v248, 16
	v_lshlrev_b32_e32 v19, 2, v19
	v_lshlrev_b32_e32 v20, 2, v59
	s_cmp_lg_u32 s30, 0
	v_add_u32_e32 v64, s4, v14
	v_add3_u32 v65, s4, v19, v20
	s_movk_i32 s4, 0x70
	s_cselect_b64 s[42:43], -1, 0
	v_mad_u64_u32 v[48:49], s[46:47], v16, s4, v[46:47]
	v_readlane_b32 s4, v248, 17
	s_cmp_lg_u64 s[42:43], 0
	v_mad_i64_i32 v[40:41], s[30:31], v47, s26, 0
	v_mad_i64_i32 v[42:43], s[30:31], v57, s26, 0
	v_add_u32_e32 v97, s4, v14
	v_readlane_b32 s4, v248, 18
	s_addc_u32 s62, s58, 0
	s_lshl_b32 s30, s22, 1
	v_add_u32_e32 v98, s4, v14
	v_readlane_b32 s4, v248, 19
	s_or_b32 s50, s30, 1
	s_ashr_i32 s31, s30, 31
	v_add_u32_e32 v99, s4, v14
	v_readlane_b32 s4, v248, 20
	s_lshl_b32 s44, s22, 10
	s_lshl_b32 s52, s50, 9
	v_add_u32_e32 v100, s4, v14
	v_readlane_b32 s4, v250, 5
	s_lshl_b32 s63, s22, 11
	s_lshl_b32 s64, s22, 9
	s_ashr_i32 s45, s44, 31
	s_ashr_i32 s51, s50, 31
	s_ashr_i32 s53, s52, 31
	s_lshl_b64 s[30:31], s[30:31], 17
	v_readlane_b32 s10, v250, 11
	v_or_b32_e32 v18, 1, v18
	v_readlane_b32 s11, v250, 12
	v_readlane_b32 s16, v250, 17
	v_readlane_b32 s17, v250, 18
	v_readlane_b32 s18, v250, 19
	v_readlane_b32 s19, v250, 20
	s_add_u32 s94, s10, s30
	v_lshlrev_b32_e32 v12, 11, v13
	v_lshlrev_b32_e32 v66, 12, v13
	v_mul_lo_u32 v13, v13, s27
	v_lshlrev_b32_e32 v67, 8, v18
	v_mul_lo_u32 v18, v18, s28
	s_mov_b32 s98, s22
	s_addc_u32 s95, s11, s31
	v_readlane_b32 s16, v250, 37
	s_lshl_b64 s[48:49], s[44:45], 2
	v_readlane_b32 s24, v250, 45
	v_readlane_b32 s25, v250, 46
	s_add_u32 s44, s24, s48
	v_readlane_b32 s28, v250, 49
	s_addc_u32 s45, s25, s49
	v_or_b32_e32 v16, v66, v20
	v_readlane_b32 s29, v250, 50
	s_add_u32 s46, s28, s48
	v_or_b32_e32 v68, 0x200, v66
	v_add_u32_e32 v49, 0, v16
	v_or_b32_e32 v16, v67, v20
	v_readlane_b32 s14, v250, 15
	s_addc_u32 s47, s29, s49
	v_or_b32_e32 v69, 0x300, v66
	v_add_u32_e32 v82, 0, v16
	v_or_b32_e32 v16, v68, v20
	v_readlane_b32 s15, v250, 16
	s_add_u32 s48, s14, s48
	v_or_b32_e32 v70, 0x400, v66
	v_add_u32_e32 v83, 0, v16
	v_or_b32_e32 v16, v69, v20
	s_addc_u32 s49, s15, s49
	s_lshl_b64 s[50:51], s[50:51], 17
	v_or_b32_e32 v71, 0x500, v66
	v_add_u32_e32 v84, 0, v16
	v_or_b32_e32 v16, v70, v20
	s_add_u32 s50, s10, s50
	v_or_b32_e32 v72, 0x600, v66
	v_add_u32_e32 v85, 0, v16
	v_or_b32_e32 v16, v71, v20
	s_addc_u32 s51, s11, s51
	s_lshl_b64 s[56:57], s[52:53], 2
	v_or_b32_e32 v73, 0x700, v66
	v_add_u32_e32 v86, 0, v16
	v_or_b32_e32 v16, v72, v20
	s_add_u32 s52, s24, s56
	v_or_b32_e32 v74, 0x800, v66
	v_add_u32_e32 v87, 0, v16
	v_or_b32_e32 v16, v73, v20
	s_addc_u32 s53, s25, s57
	v_or_b32_e32 v75, 0x900, v66
	v_add_u32_e32 v88, 0, v16
	v_or_b32_e32 v16, v74, v20
	s_add_u32 s54, s28, s56
	v_or_b32_e32 v76, 0xa00, v66
	v_add_u32_e32 v89, 0, v16
	v_or_b32_e32 v16, v75, v20
	s_addc_u32 s55, s29, s57
	v_or_b32_e32 v77, 0xb00, v66
	v_add_u32_e32 v90, 0, v16
	v_or_b32_e32 v16, v76, v20
; __device__ __forceinline__ int TIDX() { int t = threadIdx.x; asm volatile("" : "+v"(t)); return t; }
; __device__ __forceinline__ int BIDX() { int b = blockIdx.x; asm volatile("" : "+s"(b)); return b; }
; template <bool FINAL>
; __device__ void phase_lru(const Params& p, int l, unsigned char* smem) {
;   u16* xs = (u16*)smem;
;   float* u32 = (float*)(smem + 8704);
;   u16* ub = (u16*)(smem + 25088);
;   float* sa = (float*)(smem + 34304);
;   float* sb = (float*)(smem + 50688);
;   float* part = (float*)(smem + 67072);
;   const int tid = TIDX(), lane = tid & 63, w = tid >> 6, l15 = lane & 15, g = lane >> 4;
;   const int e_ = tid & 63, qd = tid >> 6;
;   const int NIT = NCHUNK * 8;
;   const int step = gridDim.x;
;   int it = BIDX();
;   uint4 x0 = make_uint4(0, 0, 0, 0), x1 = x0, x2 = x0;
;   auto load_x = [&](int item, uint4& a0, uint4& a1, uint4& a2) {
;     const int ci = item >> 3, nb = item & 7;
;     const int tb = ci * 64, pos0 = tok_pos(tb), S = tok_len(tb);
;     const u16* zb = p.Z + (long)(tb - 2) * DIN + C_LX + nb * 64;
;     { int idx = tid, r = idx >> 3, ch = idx & 7, pp = pos0 - 2 + r;
;       a0 = (pp >= 0 && pp < S) ? *(const uint4*)(zb + (long)r * DIN + ch * 8) : make_uint4(0, 0, 0, 0); }
;     { int idx = tid + 256, r = idx >> 3, ch = idx & 7, pp = pos0 - 2 + r;
;       a1 = (pp >= 0 && pp < S) ? *(const uint4*)(zb + (long)r * DIN + ch * 8) : make_uint4(0, 0, 0, 0); }
;     { int idx = tid + 512, r = idx >> 3, ch = idx & 7, pp = pos0 - 2 + r;
;       a2 = (idx < 67 * 8 && pp >= 0 && pp < S) ? *(const uint4*)(zb + (long)r * DIN + ch * 8) : make_uint4(0, 0, 0, 0); }
;   };
;   if (it < NIT) load_x(it, x0, x1, x2);
;     ...
;           const float4 ba4 = *(const float4*)(p.ba + (l * 2 + d) * 512 + ch0);
;           const float4 bx4 = *(const float4*)(p.bx + (l * 2 + d) * 512 + ch0);
;           const float4 sp4 = *(const float4*)(p.SP8 + (l * 2 + d) * 512 + ch0);
	s_add_u32 s56, s14, s56
	v_or_b32_e32 v78, 0xc00, v66
	v_add_u32_e32 v91, 0, v16
	v_or_b32_e32 v16, v77, v20
	s_addc_u32 s57, s15, s57
	s_lshl_b32 s65, s62, 6
	v_or_b32_e32 v79, 0xd00, v66
	v_add_u32_e32 v92, 0, v16
	v_or_b32_e32 v16, v78, v20
	s_cmp_lg_u64 s[42:43], 0
	v_cndmask_b32_e64 v15, 0, 1, s[42:43]
	v_or_b32_e32 v80, 0xe00, v66
	v_add_u32_e32 v93, 0, v16
	v_or_b32_e32 v16, v79, v20
	s_addc_u32 s42, s72, s58
	v_or_b32_e32 v81, 0xf00, v66
	v_add_u32_e32 v94, 0, v16
	v_or_b32_e32 v16, v80, v20
	s_lshl_b32 s66, s42, 3
	v_readfirstlane_b32 s42, v15
	v_add_u32_e32 v95, 0, v16
	v_or_b32_e32 v16, v81, v20
	s_lshl_b32 s68, s58, 6
	s_lshl_b32 s42, s42, 6
	v_cmp_gt_u32_e64 s[40:41], 64, v45
	v_add_u32_e32 v96, 0, v16
	s_lshl_b32 s67, s62, 3
	s_add_i32 s68, s68, s42
	v_add_u32_e32 v101, v17, v12
	v_add_u32_e32 v102, v17, v13
	v_add_u32_e32 v103, v17, v18
	v_readlane_b32 s5, v250, 6
	v_readlane_b32 s6, v250, 7
	v_readlane_b32 s7, v250, 8
	v_readlane_b32 s8, v250, 9
	v_readlane_b32 s9, v250, 10
	v_readlane_b32 s12, v250, 13
	v_readlane_b32 s13, v250, 14
	v_readlane_b32 s17, v250, 38
	v_readlane_b32 s18, v250, 39
	v_readlane_b32 s19, v250, 40
	v_readlane_b32 s20, v250, 41
	v_readlane_b32 s21, v250, 42
	v_readlane_b32 s22, v250, 43
	v_readlane_b32 s23, v250, 44
	v_readlane_b32 s26, v250, 47
	v_readlane_b32 s27, v250, 48
	v_readlane_b32 s30, v250, 51
	v_readlane_b32 s31, v250, 52
	s_and_b32 s32, s36, 0x1c0
	v_lshrrev_b32_e32 v12, 6, v147
	v_and_b32_e32 v22, 15, v147
	v_lshlrev_b32_e32 v13, 4, v12
	v_or_b32_e32 v13, v13, v22
	v_or_b32_e32 v13, s32, v13
	v_lshlrev_b32_e32 v14, 7, v13
	v_mov_b32_e32 v15, v145
	v_bfe_u32 v16, v147, 4, 2
	v_lshlrev_b32_e32 v17, 4, v16
	v_add_u32_e32 v14, v14, v17
	v_lshl_add_u64 v[18:19], s[94:95], 0, v[14:15]
	global_load_dwordx4 v[180:183], v[18:19], off
	global_load_dwordx4 v[184:187], v[18:19], off offset:64
	v_add_co_u32_e32 v20, vcc, 0x10000, v18
	s_nop 0
	v_addc_co_u32_e32 v21, vcc, 0, v19, vcc
	global_load_dwordx4 v[188:191], v[20:21], off
	global_load_dwordx4 v[192:195], v[20:21], off offset:64
	v_lshl_add_u64 v[18:19], s[50:51], 0, v[14:15]
	global_load_dwordx4 v[232:235], v[18:19], off
	global_load_dwordx4 v[236:239], v[18:19], off offset:64
	v_add_co_u32_e32 v20, vcc, 0x10000, v18
	s_nop 0
	v_addc_co_u32_e32 v21, vcc, 0, v19, vcc
	global_load_dwordx4 v[240:243], v[20:21], off
	global_load_dwordx4 v[244:247], v[20:21], off offset:64
	v_mul_u32_u24_e32 v229, 0x90, v22
	v_add_u32_e32 v229, v229, v17
	v_lshlrev_b32_e32 v230, 8, v22
	v_add_u32_e32 v230, v230, v17
	v_lshl_add_u32 v230, v12, 6, v230
	v_lshlrev_b32_e32 v231, 4, v12
	v_lshl_add_u32 v231, v16, 2, v231
	v_or_b32_e32 v231, s32, v231
	v_lshlrev_b32_e32 v231, 2, v231
	v_lshl_add_u32 v204, v12, 2, v16
	v_xor_b32_e32 v204, v204, v22
	v_lshlrev_b32_e32 v204, 4, v204
	v_lshl_add_u32 v204, v22, 8, v204
	v_xor_b32_e32 v82, 0x10, v82
	v_xor_b32_e32 v83, 0x20, v83
	v_xor_b32_e32 v84, 0x30, v84
	v_xor_b32_e32 v85, 0x40, v85
	v_xor_b32_e32 v86, 0x50, v86
	v_xor_b32_e32 v87, 0x60, v87
	v_xor_b32_e32 v88, 0x70, v88
	v_xor_b32_e32 v89, 0x80, v89
	v_xor_b32_e32 v90, 0x90, v90
	v_xor_b32_e32 v91, 0xa0, v91
	v_xor_b32_e32 v92, 0xb0, v92
	v_xor_b32_e32 v93, 0xc0, v93
	v_xor_b32_e32 v94, 0xd0, v94
	v_xor_b32_e32 v95, 0xe0, v95
	v_xor_b32_e32 v96, 0xf0, v96
	global_load_dwordx4 v[122:125], v231, s[44:45]
	global_load_dwordx4 v[126:129], v231, s[46:47]
	global_load_dwordx4 v[130:133], v231, s[48:49]
	global_load_dwordx4 v[134:137], v231, s[52:53]
	global_load_dwordx4 v[138:141], v231, s[54:55]
	global_load_dwordx4 v[150:153], v231, s[56:57]
	s_branch .LBB0_375

; __device__ __forceinline__ float bf2f(unsigned h) { return __uint_as_float(h << 16); }
; template <bool FINAL>
; __device__ void phase_lru(const Params& p, int l, unsigned char* smem) {
;     ...
;     {
;       const int ch = nb * 64 + e_;
;       const float cw0 = p.conv_w[(l * 4 + 0) * 512 + ch], cw1 = p.conv_w[(l * 4 + 1) * 512 + ch],
;                   cw2 = p.conv_w[(l * 4 + 2) * 512 + ch], cw3 = p.conv_w[(l * 4 + 3) * 512 + ch];
;       const float cb = p.conv_b[l * 512 + ch];
;       float xv[19];
; #pragma unroll
;       for (int k = 0; k < 19; ++k) xv[k] = bf2f(xs[(qd * 16 + k) * 64 + e_]);
; #pragma unroll
;       for (int tt = 0; tt < 16; ++tt) {
;         const int t = qd * 16 + tt;
;         const float u = cb + xv[tt] * cw0 + xv[tt + 1] * cw1 + xv[tt + 2] * cw2 + xv[tt + 3] * cw3;
;         u32[t * 64 + e_] = u;
;         ub[t * 72 + e_] = (u16)f2bf(u);
;       }
;     }
.LBB0_385:
	s_and_b32 s60, s36, 0x1c0
	v_or_b32_e32 v18, s60, v59
	v_or_b32_e32 v12, s63, v18
	v_readlane_b32 s4, v250, 37
	v_ashrrev_i32_e32 v13, 31, v12
	v_readlane_b32 s6, v250, 39
	v_readlane_b32 s7, v250, 40
	v_readlane_b32 s8, v250, 41
	v_readlane_b32 s9, v250, 42
	v_lshl_add_u64 v[14:15], v[12:13], 2, s[6:7]
	v_add_co_u32_e32 v16, vcc, 0x1000, v14
	global_load_dword v13, v[14:15], off
	global_load_dword v12, v[14:15], off offset:2048
	v_addc_co_u32_e32 v17, vcc, 0, v15, vcc
	global_load_dword v15, v[16:17], off
	global_load_dword v14, v[16:17], off offset:2048
	v_or_b32_e32 v16, s64, v18
	v_ashrrev_i32_e32 v17, 31, v16
	v_lshl_add_u64 v[16:17], v[16:17], 2, s[8:9]
	global_load_dword v16, v[16:17], off
	ds_read_u16 v17, v101
	ds_read_u16 v18, v101 offset:128
	ds_read_u16 v19, v101 offset:256
	ds_read_u16 v20, v101 offset:384
	ds_read_u16 v21, v101 offset:512
	ds_read_u16 v22, v101 offset:640
	ds_read_u16 v23, v101 offset:768
	ds_read_u16 v24, v101 offset:896
	s_waitcnt lgkmcnt(7)
	v_lshlrev_b32_e32 v17, 16, v17
	s_waitcnt lgkmcnt(6)
	v_lshlrev_b32_e32 v18, 16, v18
	s_waitcnt lgkmcnt(5)
	v_lshlrev_b32_e32 v19, 16, v19
	s_waitcnt lgkmcnt(4)
	v_lshlrev_b32_e32 v20, 16, v20
	v_add_u32_e32 v50, v62, v66
	ds_read_u16 v25, v101 offset:1024
	ds_read_u16 v26, v101 offset:1152
	ds_read_u16 v27, v101 offset:1280
	ds_read_u16 v28, v101 offset:1408
	ds_read_u16 v29, v101 offset:1536
	ds_read_u16 v30, v101 offset:1664
	ds_read_u16 v31, v101 offset:1792
	ds_read_u16 v32, v101 offset:1920
	ds_read_u16 v33, v101 offset:2048
	ds_read_u16 v34, v101 offset:2176
	ds_read_u16 v35, v101 offset:2304
	s_waitcnt lgkmcnt(14)
	v_lshlrev_b32_e32 v21, 16, v21
	s_waitcnt lgkmcnt(13)
	v_lshlrev_b32_e32 v22, 16, v22
	s_waitcnt lgkmcnt(12)
	v_lshlrev_b32_e32 v23, 16, v23
	s_waitcnt lgkmcnt(11)
	v_lshlrev_b32_e32 v24, 16, v24
	s_waitcnt lgkmcnt(10)
	v_lshlrev_b32_e32 v25, 16, v25
	s_waitcnt lgkmcnt(9)
	v_lshlrev_b32_e32 v26, 16, v26
	s_waitcnt lgkmcnt(8)
	v_lshlrev_b32_e32 v27, 16, v27
	s_waitcnt lgkmcnt(7)
	v_lshlrev_b32_e32 v28, 16, v28
	s_waitcnt lgkmcnt(6)
	v_lshlrev_b32_e32 v29, 16, v29
	s_waitcnt lgkmcnt(5)
	v_lshlrev_b32_e32 v30, 16, v30
	s_waitcnt lgkmcnt(4)
	v_lshlrev_b32_e32 v31, 16, v31
	s_waitcnt lgkmcnt(3)
	v_lshlrev_b32_e32 v32, 16, v32
	s_waitcnt lgkmcnt(2)
	v_lshlrev_b32_e32 v33, 16, v33
	s_ashr_i32 s42, s72, 3
	s_ashr_i32 s43, s42, 31
	s_waitcnt lgkmcnt(1)
	v_lshlrev_b32_e32 v34, 16, v34
	s_lshl_b64 s[42:43], s[42:43], 10
	v_add_u32_e32 v144, s60, v45
	s_waitcnt lgkmcnt(0)
	v_lshlrev_b32_e32 v35, 16, v35
	v_lshlrev_b32_e32 v54, 1, v44
	v_mov_b32_e32 v55, v145
	v_readlane_b32 s5, v250, 38
	s_mov_b64 s[4:5], 0x10000
	v_or_b32_e32 v56, s60, v63
	v_lshlrev_b32_e32 v104, 2, v56
	s_mov_b32 s6, 0xbe800000
	s_mov_b64 s[8:9], 0x10800
	v_readlane_b32 s10, v250, 43
	v_readlane_b32 s11, v250, 44
	v_readlane_b32 s12, v250, 45
	v_readlane_b32 s13, v250, 46
	v_readlane_b32 s14, v250, 47
	v_readlane_b32 s15, v250, 48
	v_readlane_b32 s16, v250, 49
	v_readlane_b32 s17, v250, 50
	v_readlane_b32 s18, v250, 51
	v_readlane_b32 s19, v250, 52
	s_waitcnt vmcnt(0)
	v_fma_f32 v17, v13, v17, v16
	v_fmac_f32_e32 v17, v12, v18
	v_fmac_f32_e32 v17, v15, v19
	v_fmac_f32_e32 v17, v14, v20
	ds_write_b32 v50, v17 offset:8704
	v_cvt_pk_bf16_f32 v17, v17, s0
	ds_write_b16 v102, v17 offset:25088
	v_fma_f32 v17, v13, v18, v16
	v_fmac_f32_e32 v17, v12, v19
	v_fmac_f32_e32 v17, v15, v20
	v_fmac_f32_e32 v17, v14, v21
	v_add_u32_e32 v18, v62, v67
	ds_write_b32 v18, v17 offset:8704
	v_cvt_pk_bf16_f32 v17, v17, s0
	ds_write_b16 v103, v17 offset:25088
	v_fma_f32 v17, v13, v19, v16
	v_fmac_f32_e32 v17, v12, v20
	v_fmac_f32_e32 v17, v15, v21
	v_fmac_f32_e32 v17, v14, v22
	v_add_u32_e32 v18, v62, v68
	ds_write_b32 v18, v17 offset:8704
	v_cvt_pk_bf16_f32 v17, v17, s0
	ds_write_b16 v103, v17 offset:25232
	v_fma_f32 v17, v13, v20, v16
	v_fmac_f32_e32 v17, v12, v21
	v_fmac_f32_e32 v17, v15, v22
	v_fmac_f32_e32 v17, v14, v23
	v_add_u32_e32 v18, v62, v69
	ds_write_b32 v18, v17 offset:8704
	v_cvt_pk_bf16_f32 v17, v17, s0
	ds_write_b16 v103, v17 offset:25376
	v_fma_f32 v17, v13, v21, v16
	v_fmac_f32_e32 v17, v12, v22
	v_fmac_f32_e32 v17, v15, v23
	v_fmac_f32_e32 v17, v14, v24
	v_add_u32_e32 v18, v62, v70
	ds_write_b32 v18, v17 offset:8704
	v_cvt_pk_bf16_f32 v17, v17, s0
	ds_write_b16 v103, v17 offset:25520
	v_fma_f32 v17, v13, v22, v16
	v_fmac_f32_e32 v17, v12, v23
	v_fmac_f32_e32 v17, v15, v24
	v_fmac_f32_e32 v17, v14, v25
	v_add_u32_e32 v18, v62, v71
	ds_write_b32 v18, v17 offset:8704
	v_cvt_pk_bf16_f32 v17, v17, s0
	ds_write_b16 v103, v17 offset:25664
	v_fma_f32 v17, v13, v23, v16
	v_fmac_f32_e32 v17, v12, v24
	v_fmac_f32_e32 v17, v15, v25
	v_fmac_f32_e32 v17, v14, v26
	v_add_u32_e32 v18, v62, v72
	ds_write_b32 v18, v17 offset:8704
	v_cvt_pk_bf16_f32 v17, v17, s0
	ds_write_b16 v103, v17 offset:25808
	v_fma_f32 v17, v13, v24, v16
	v_fmac_f32_e32 v17, v12, v25
	v_fmac_f32_e32 v17, v15, v26
	v_fmac_f32_e32 v17, v14, v27
	v_add_u32_e32 v18, v62, v73
	ds_write_b32 v18, v17 offset:8704
	v_cvt_pk_bf16_f32 v17, v17, s0
	ds_write_b16 v103, v17 offset:25952
	v_fma_f32 v17, v13, v25, v16
	v_fmac_f32_e32 v17, v12, v26
	v_fmac_f32_e32 v17, v15, v27
	v_fmac_f32_e32 v17, v14, v28
	v_add_u32_e32 v18, v62, v74
	ds_write_b32 v18, v17 offset:8704
	v_cvt_pk_bf16_f32 v17, v17, s0
	ds_write_b16 v103, v17 offset:26096
	v_fma_f32 v17, v13, v26, v16
	v_fmac_f32_e32 v17, v12, v27
	v_fmac_f32_e32 v17, v15, v28
	v_fmac_f32_e32 v17, v14, v29
	v_add_u32_e32 v18, v62, v75
	ds_write_b32 v18, v17 offset:8704
	v_cvt_pk_bf16_f32 v17, v17, s0
	ds_write_b16 v103, v17 offset:26240
	v_fma_f32 v17, v13, v27, v16
	v_fmac_f32_e32 v17, v12, v28
; __device__ __forceinline__ float sigmoidf_(float x) { return __builtin_amdgcn_rcpf(1.0f + __expf(-x)); }
; template <bool FINAL>
; __device__ void phase_lru(const Params& p, int l, unsigned char* smem) {
;     ...
;       for (int tt = 0; tt < 16; ++tt) {
;         const int t = qd * 16 + tt;
;         const float u = cb + xv[tt] * cw0 + xv[tt + 1] * cw1 + xv[tt + 2] * cw2 + xv[tt + 3] * cw3;
;         u32[t * 64 + e_] = u;
;         ub[t * 72 + e_] = (u16)f2bf(u);
;       }
;     }
;     __syncthreads();
;     ...
;         for (int et = 0; et < 4; ++et) {
;           f32x4 ar = {0.f, 0.f, 0.f, 0.f}, ai = {0.f, 0.f, 0.f, 0.f};
;           const u16* wr = p.WLRU + ((((size_t)(l * 2 + d) * 2 + 0) * 8 + nb) * 64 + et * 16 + l15) * 64 + g * 8;
;           const u16* wi = p.WLRU + ((((size_t)(l * 2 + d) * 2 + 1) * 8 + nb) * 64 + et * 16 + l15) * 64 + g * 8;
; #pragma unroll
;           for (int ks = 0; ks < 2; ++ks) {
;             ar = mfma16(*(const bf16x8*)(wr + ks * 32), uf[ks], ar);
;             ai = mfma16(*(const bf16x8*)(wi + ks * 32), uf[ks], ai);
;           }
;           const int e0 = et * 16 + 4 * g, ch0 = nb * 64 + e0;
;           const float4 ba4 = *(const float4*)(p.ba + (l * 2 + d) * 512 + ch0);
;           const float4 bx4 = *(const float4*)(p.bx + (l * 2 + d) * 512 + ch0);
;           const float4 sp4 = *(const float4*)(p.SP8 + (l * 2 + d) * 512 + ch0);
;           const float4 uu = *(const float4*)(u32 + t * 64 + e0);
;           const float* bap = (const float*)&ba4; const float* bxp = (const float*)&bx4;
;           const float* spp = (const float*)&sp4; const float* uup = (const float*)&uu;
;           f32x4 av, bv;
; #pragma unroll
;           for (int j = 0; j < 4; ++j) {
;             float r = sigmoidf_(ar[j] + bap[j]);
;             float ig = sigmoidf_(ai[j] + bxp[j]);
;             float la = spp[j] * r;
;             float av_ = __expf(la);
;             float t2 = 2.0f * la;
;             float ser = -t2 * (1.f + t2 * 0.5f * (1.f + t2 * (1.f / 3.f) * (1.f + t2 * 0.25f * (1.f + t2 * 0.2f))));
;             float om = (t2 > -0.25f) ? ser : (1.0f - av_ * av_);
;             av[j] = av_;
;             bv[j] = __builtin_amdgcn_sqrtf(om) * ig * uup[j];
;           }
;           *(f32x4*)(sa + t * 64 + e0) = av;
;           *(f32x4*)(sb + t * 64 + e0) = bv;
;         }
	v_fmac_f32_e32 v17, v15, v29
	v_fmac_f32_e32 v17, v14, v30
	v_add_u32_e32 v18, v62, v76
	ds_write_b32 v18, v17 offset:8704
	v_cvt_pk_bf16_f32 v17, v17, s0
	ds_write_b16 v103, v17 offset:26384
	v_fma_f32 v17, v13, v28, v16
	v_fmac_f32_e32 v17, v12, v29
	v_fmac_f32_e32 v17, v15, v30
	v_fmac_f32_e32 v17, v14, v31
	v_add_u32_e32 v18, v62, v77
	ds_write_b32 v18, v17 offset:8704
	v_cvt_pk_bf16_f32 v17, v17, s0
	ds_write_b16 v103, v17 offset:26528
	v_fma_f32 v17, v13, v29, v16
	v_fmac_f32_e32 v17, v12, v30
	v_fmac_f32_e32 v17, v15, v31
	v_fmac_f32_e32 v17, v14, v32
	v_add_u32_e32 v18, v62, v78
	ds_write_b32 v18, v17 offset:8704
	v_cvt_pk_bf16_f32 v17, v17, s0
	ds_write_b16 v103, v17 offset:26672
	v_fma_f32 v17, v13, v30, v16
	v_fmac_f32_e32 v17, v12, v31
	v_fmac_f32_e32 v17, v15, v32
	v_fmac_f32_e32 v17, v14, v33
	v_add_u32_e32 v18, v62, v79
	ds_write_b32 v18, v17 offset:8704
	v_cvt_pk_bf16_f32 v17, v17, s0
	ds_write_b16 v103, v17 offset:26816
	v_fma_f32 v17, v13, v31, v16
	v_fmac_f32_e32 v16, v13, v32
	v_fmac_f32_e32 v17, v12, v32
	v_fmac_f32_e32 v16, v12, v33
	v_or_b32_e32 v20, s60, v60
	v_fmac_f32_e32 v17, v15, v33
	v_fmac_f32_e32 v16, v15, v34
	v_lshl_add_u64 v[50:51], v[144:145], 0, s[42:43]
	v_lshlrev_b32_e32 v144, 7, v20
	v_fmac_f32_e32 v17, v14, v34
	v_add_u32_e32 v18, v62, v80
	v_fmac_f32_e32 v16, v14, v35
	v_add_u32_e32 v12, v62, v81
	v_lshl_add_u64 v[20:21], s[94:95], 0, v[144:145]
	ds_write_b32 v18, v17 offset:8704
	v_cvt_pk_bf16_f32 v17, v17, s0
	ds_write_b32 v12, v16 offset:8704
	v_cvt_pk_bf16_f32 v12, v16, s0
	v_lshl_add_u64 v[28:29], v[20:21], 0, v[54:55]
	ds_write_b16 v103, v17 offset:26960
	ds_write_b16 v103, v12 offset:27104
	s_waitcnt lgkmcnt(0)
	s_barrier
	s_mov_b32 s5, 0x3e4ccccd
	ds_read_b128 v[12:15], v229 offset:25088
	ds_read_b128 v[16:19], v229 offset:25152
	ds_read_b128 v[28:31], v230 offset:8704
	s_waitcnt lgkmcnt(1)
	v_mfma_f32_16x16x32_bf16 v[20:23], v[180:183], v[12:15], 0
	v_mfma_f32_16x16x32_bf16 v[24:27], v[188:191], v[12:15], 0
	v_mfma_f32_16x16x32_bf16 v[20:23], v[184:187], v[16:19], v[20:23]
	v_mfma_f32_16x16x32_bf16 v[24:27], v[192:195], v[16:19], v[24:27]
	s_nop 7
	s_nop 3
	s_waitcnt lgkmcnt(0)
	v_add_f32_e32 v20, v20, v122
	v_add_f32_e32 v21, v21, v123
	v_add_f32_e32 v24, v24, v126
	v_add_f32_e32 v25, v25, v127
	v_mul_f32_e32 v20, 0xbfb8aa3b, v20
	v_mul_f32_e32 v21, 0xbfb8aa3b, v21
	v_mul_f32_e32 v24, 0xbfb8aa3b, v24
	v_mul_f32_e32 v25, 0xbfb8aa3b, v25
	v_exp_f32_e32 v20, v20
	v_exp_f32_e32 v21, v21
	v_exp_f32_e32 v24, v24
	v_exp_f32_e32 v25, v25
	v_add_f32_e32 v20, 1.0, v20
	v_add_f32_e32 v21, 1.0, v21
	v_add_f32_e32 v24, 1.0, v24
	v_add_f32_e32 v25, 1.0, v25
	v_rcp_f32_e32 v20, v20
	v_rcp_f32_e32 v21, v21
	v_rcp_f32_e32 v24, v24
	v_rcp_f32_e32 v25, v25
	v_pk_mul_f32 v[12:13], v[20:21], v[130:131]
	s_nop 0
	v_pk_add_f32 v[14:15], v[12:13], v[12:13]
	v_mul_f32_e32 v20, 0x3fb8aa3b, v12
	v_mul_f32_e32 v21, 0x3fb8aa3b, v13
	v_exp_f32_e32 v20, v20
	v_exp_f32_e32 v21, v21
	v_mul_f32_e32 v16, 0x3e800000, v14
	v_fma_f32 v17, v14, s5, 1.0
	v_mul_f32_e32 v18, 0x3eaaaaab, v14
	v_fma_f32 v16, v16, v17, 1.0
	v_mul_f32_e32 v17, 0.5, v14
	v_fma_f32 v18, v18, v16, 1.0
	v_fma_f32 v17, v17, v18, 1.0
	v_mul_f32_e64 v17, v17, -v14
	v_fma_f32 v16, -v20, v20, 1.0
	v_cmp_lt_f32_e32 vcc, s6, v14
	v_mul_f32_e32 v19, 0x3e800000, v15
	v_fma_f32 v12, v15, s5, 1.0
	v_cndmask_b32_e32 v16, v16, v17, vcc
	v_mul_f32_e32 v13, 0x3eaaaaab, v15
	v_fma_f32 v19, v19, v12, 1.0
	v_mul_f32_e32 v12, 0.5, v15
	v_fma_f32 v13, v13, v19, 1.0
	v_fma_f32 v12, v12, v13, 1.0
	v_mul_f32_e64 v12, v12, -v15
	v_fma_f32 v13, -v21, v21, 1.0
	v_cmp_lt_f32_e32 vcc, s6, v15
	v_sqrt_f32_e32 v16, v16
	s_nop 1
	v_cndmask_b32_e32 v17, v13, v12, vcc
	v_sqrt_f32_e32 v17, v17
	s_nop 0
	v_pk_mul_f32 v[24:25], v[24:25], v[16:17]
	s_nop 0
	v_pk_mul_f32 v[24:25], v[28:29], v[24:25]
	v_add_f32_e32 v22, v22, v124
	v_add_f32_e32 v23, v23, v125
	v_add_f32_e32 v26, v26, v128
	v_add_f32_e32 v27, v27, v129
	v_mul_f32_e32 v22, 0xbfb8aa3b, v22
	v_mul_f32_e32 v23, 0xbfb8aa3b, v23
	v_mul_f32_e32 v26, 0xbfb8aa3b, v26
	v_mul_f32_e32 v27, 0xbfb8aa3b, v27
	v_exp_f32_e32 v22, v22
	v_exp_f32_e32 v23, v23
	v_exp_f32_e32 v26, v26
	v_exp_f32_e32 v27, v27
	v_add_f32_e32 v22, 1.0, v22
	v_add_f32_e32 v23, 1.0, v23
	v_add_f32_e32 v26, 1.0, v26
	v_add_f32_e32 v27, 1.0, v27
	v_rcp_f32_e32 v22, v22
	v_rcp_f32_e32 v23, v23
	v_rcp_f32_e32 v26, v26
	v_rcp_f32_e32 v27, v27
	v_pk_mul_f32 v[12:13], v[22:23], v[132:133]
	s_nop 0
	v_pk_add_f32 v[14:15], v[12:13], v[12:13]
	v_mul_f32_e32 v22, 0x3fb8aa3b, v12
	v_mul_f32_e32 v23, 0x3fb8aa3b, v13
	v_exp_f32_e32 v22, v22
	v_exp_f32_e32 v23, v23
	v_mul_f32_e32 v16, 0x3e800000, v14
	v_fma_f32 v17, v14, s5, 1.0
	v_mul_f32_e32 v18, 0x3eaaaaab, v14
	v_fma_f32 v16, v16, v17, 1.0
	v_mul_f32_e32 v17, 0.5, v14
	v_fma_f32 v18, v18, v16, 1.0
	v_fma_f32 v17, v17, v18, 1.0
	v_mul_f32_e64 v17, v17, -v14
	v_fma_f32 v16, -v22, v22, 1.0
	v_cmp_lt_f32_e32 vcc, s6, v14
	v_mul_f32_e32 v19, 0x3e800000, v15
	v_fma_f32 v12, v15, s5, 1.0
	v_cndmask_b32_e32 v16, v16, v17, vcc
	v_mul_f32_e32 v13, 0x3eaaaaab, v15
	v_fma_f32 v19, v19, v12, 1.0
	v_mul_f32_e32 v12, 0.5, v15
	v_fma_f32 v13, v13, v19, 1.0
	v_fma_f32 v12, v12, v13, 1.0
	v_mul_f32_e64 v12, v12, -v15
	v_fma_f32 v13, -v23, v23, 1.0
	v_cmp_lt_f32_e32 vcc, s6, v15
	v_sqrt_f32_e32 v16, v16
	s_nop 1
	v_cndmask_b32_e32 v17, v13, v12, vcc
	v_sqrt_f32_e32 v17, v17
	s_nop 0
	v_pk_mul_f32 v[26:27], v[26:27], v[16:17]
	s_nop 0
	v_pk_mul_f32 v[26:27], v[30:31], v[26:27]
	ds_write_b128 v204, v[20:23] offset:34304
	ds_write_b128 v204, v[24:27] offset:50688
	ds_read_b128 v[12:15], v229 offset:27392
	ds_read_b128 v[16:19], v229 offset:27456
	ds_read_b128 v[28:31], v230 offset:12800
	s_waitcnt lgkmcnt(1)
; __device__ __forceinline__ float sigmoidf_(float x) { return __builtin_amdgcn_rcpf(1.0f + __expf(-x)); }
; template <bool FINAL>
; __device__ void phase_lru(const Params& p, int l, unsigned char* smem) {
;     ...
;         for (int et = 0; et < 4; ++et) {
;           f32x4 ar = {0.f, 0.f, 0.f, 0.f}, ai = {0.f, 0.f, 0.f, 0.f};
;           const u16* wr = p.WLRU + ((((size_t)(l * 2 + d) * 2 + 0) * 8 + nb) * 64 + et * 16 + l15) * 64 + g * 8;
;           const u16* wi = p.WLRU + ((((size_t)(l * 2 + d) * 2 + 1) * 8 + nb) * 64 + et * 16 + l15) * 64 + g * 8;
; #pragma unroll
;           for (int ks = 0; ks < 2; ++ks) {
;             ar = mfma16(*(const bf16x8*)(wr + ks * 32), uf[ks], ar);
;             ai = mfma16(*(const bf16x8*)(wi + ks * 32), uf[ks], ai);
;           }
;           const int e0 = et * 16 + 4 * g, ch0 = nb * 64 + e0;
;           const float4 ba4 = *(const float4*)(p.ba + (l * 2 + d) * 512 + ch0);
;           const float4 bx4 = *(const float4*)(p.bx + (l * 2 + d) * 512 + ch0);
;           const float4 sp4 = *(const float4*)(p.SP8 + (l * 2 + d) * 512 + ch0);
;           const float4 uu = *(const float4*)(u32 + t * 64 + e0);
;           const float* bap = (const float*)&ba4; const float* bxp = (const float*)&bx4;
;           const float* spp = (const float*)&sp4; const float* uup = (const float*)&uu;
;           f32x4 av, bv;
; #pragma unroll
;           for (int j = 0; j < 4; ++j) {
;             float r = sigmoidf_(ar[j] + bap[j]);
;             float ig = sigmoidf_(ai[j] + bxp[j]);
;             float la = spp[j] * r;
;             float av_ = __expf(la);
;             float t2 = 2.0f * la;
;             float ser = -t2 * (1.f + t2 * 0.5f * (1.f + t2 * (1.f / 3.f) * (1.f + t2 * 0.25f * (1.f + t2 * 0.2f))));
;             float om = (t2 > -0.25f) ? ser : (1.0f - av_ * av_);
;             av[j] = av_;
;             bv[j] = __builtin_amdgcn_sqrtf(om) * ig * uup[j];
;           }
;           *(f32x4*)(sa + t * 64 + e0) = av;
;           *(f32x4*)(sb + t * 64 + e0) = bv;
;         }
	v_mfma_f32_16x16x32_bf16 v[20:23], v[180:183], v[12:15], 0
	v_mfma_f32_16x16x32_bf16 v[24:27], v[188:191], v[12:15], 0
	v_mfma_f32_16x16x32_bf16 v[20:23], v[184:187], v[16:19], v[20:23]
	v_mfma_f32_16x16x32_bf16 v[24:27], v[192:195], v[16:19], v[24:27]
	s_nop 7
	s_nop 3
	s_waitcnt lgkmcnt(0)
	v_add_f32_e32 v20, v20, v122
	v_add_f32_e32 v21, v21, v123
	v_add_f32_e32 v24, v24, v126
	v_add_f32_e32 v25, v25, v127
	v_mul_f32_e32 v20, 0xbfb8aa3b, v20
	v_mul_f32_e32 v21, 0xbfb8aa3b, v21
	v_mul_f32_e32 v24, 0xbfb8aa3b, v24
	v_mul_f32_e32 v25, 0xbfb8aa3b, v25
	v_exp_f32_e32 v20, v20
	v_exp_f32_e32 v21, v21
	v_exp_f32_e32 v24, v24
	v_exp_f32_e32 v25, v25
	v_add_f32_e32 v20, 1.0, v20
	v_add_f32_e32 v21, 1.0, v21
	v_add_f32_e32 v24, 1.0, v24
	v_add_f32_e32 v25, 1.0, v25
	v_rcp_f32_e32 v20, v20
	v_rcp_f32_e32 v21, v21
	v_rcp_f32_e32 v24, v24
	v_rcp_f32_e32 v25, v25
	v_pk_mul_f32 v[12:13], v[20:21], v[130:131]
	s_nop 0
	v_pk_add_f32 v[14:15], v[12:13], v[12:13]
	v_mul_f32_e32 v20, 0x3fb8aa3b, v12
	v_mul_f32_e32 v21, 0x3fb8aa3b, v13
	v_exp_f32_e32 v20, v20
	v_exp_f32_e32 v21, v21
	v_mul_f32_e32 v16, 0x3e800000, v14
	v_fma_f32 v17, v14, s5, 1.0
	v_mul_f32_e32 v18, 0x3eaaaaab, v14
	v_fma_f32 v16, v16, v17, 1.0
	v_mul_f32_e32 v17, 0.5, v14
	v_fma_f32 v18, v18, v16, 1.0
	v_fma_f32 v17, v17, v18, 1.0
	v_mul_f32_e64 v17, v17, -v14
	v_fma_f32 v16, -v20, v20, 1.0
	v_cmp_lt_f32_e32 vcc, s6, v14
	v_mul_f32_e32 v19, 0x3e800000, v15
	v_fma_f32 v12, v15, s5, 1.0
	v_cndmask_b32_e32 v16, v16, v17, vcc
	v_mul_f32_e32 v13, 0x3eaaaaab, v15
	v_fma_f32 v19, v19, v12, 1.0
	v_mul_f32_e32 v12, 0.5, v15
	v_fma_f32 v13, v13, v19, 1.0
	v_fma_f32 v12, v12, v13, 1.0
	v_mul_f32_e64 v12, v12, -v15
	v_fma_f32 v13, -v21, v21, 1.0
	v_cmp_lt_f32_e32 vcc, s6, v15
	v_sqrt_f32_e32 v16, v16
	s_nop 1
	v_cndmask_b32_e32 v17, v13, v12, vcc
	v_sqrt_f32_e32 v17, v17
	s_nop 0
	v_pk_mul_f32 v[24:25], v[24:25], v[16:17]
	s_nop 0
	v_pk_mul_f32 v[24:25], v[28:29], v[24:25]
	v_add_f32_e32 v22, v22, v124
	v_add_f32_e32 v23, v23, v125
	v_add_f32_e32 v26, v26, v128
	v_add_f32_e32 v27, v27, v129
	v_mul_f32_e32 v22, 0xbfb8aa3b, v22
	v_mul_f32_e32 v23, 0xbfb8aa3b, v23
	v_mul_f32_e32 v26, 0xbfb8aa3b, v26
	v_mul_f32_e32 v27, 0xbfb8aa3b, v27
	v_exp_f32_e32 v22, v22
	v_exp_f32_e32 v23, v23
	v_exp_f32_e32 v26, v26
	v_exp_f32_e32 v27, v27
	v_add_f32_e32 v22, 1.0, v22
	v_add_f32_e32 v23, 1.0, v23
	v_add_f32_e32 v26, 1.0, v26
	v_add_f32_e32 v27, 1.0, v27
	v_rcp_f32_e32 v22, v22
	v_rcp_f32_e32 v23, v23
	v_rcp_f32_e32 v26, v26
	v_rcp_f32_e32 v27, v27
	v_pk_mul_f32 v[12:13], v[22:23], v[132:133]
	s_nop 0
	v_pk_add_f32 v[14:15], v[12:13], v[12:13]
	v_mul_f32_e32 v22, 0x3fb8aa3b, v12
	v_mul_f32_e32 v23, 0x3fb8aa3b, v13
	v_exp_f32_e32 v22, v22
	v_exp_f32_e32 v23, v23
	v_mul_f32_e32 v16, 0x3e800000, v14
	v_fma_f32 v17, v14, s5, 1.0
	v_mul_f32_e32 v18, 0x3eaaaaab, v14
	v_fma_f32 v16, v16, v17, 1.0
	v_mul_f32_e32 v17, 0.5, v14
	v_fma_f32 v18, v18, v16, 1.0
	v_fma_f32 v17, v17, v18, 1.0
	v_mul_f32_e64 v17, v17, -v14
	v_fma_f32 v16, -v22, v22, 1.0
	v_cmp_lt_f32_e32 vcc, s6, v14
	v_mul_f32_e32 v19, 0x3e800000, v15
	v_fma_f32 v12, v15, s5, 1.0
	v_cndmask_b32_e32 v16, v16, v17, vcc
	v_mul_f32_e32 v13, 0x3eaaaaab, v15
	v_fma_f32 v19, v19, v12, 1.0
	v_mul_f32_e32 v12, 0.5, v15
	v_fma_f32 v13, v13, v19, 1.0
	v_fma_f32 v12, v12, v13, 1.0
	v_mul_f32_e64 v12, v12, -v15
	v_fma_f32 v13, -v23, v23, 1.0
	v_cmp_lt_f32_e32 vcc, s6, v15
	v_sqrt_f32_e32 v16, v16
	s_nop 1
	v_cndmask_b32_e32 v17, v13, v12, vcc
	v_sqrt_f32_e32 v17, v17
	s_nop 0
	v_pk_mul_f32 v[26:27], v[26:27], v[16:17]
	s_nop 0
	v_pk_mul_f32 v[26:27], v[30:31], v[26:27]
	ds_write_b128 v204, v[20:23] offset:38400
	ds_write_b128 v204, v[24:27] offset:54784
	ds_read_b128 v[12:15], v229 offset:29696
	ds_read_b128 v[16:19], v229 offset:29760
	ds_read_b128 v[28:31], v230 offset:16896
	s_waitcnt lgkmcnt(1)
	v_mfma_f32_16x16x32_bf16 v[20:23], v[180:183], v[12:15], 0
	v_mfma_f32_16x16x32_bf16 v[24:27], v[188:191], v[12:15], 0
	v_mfma_f32_16x16x32_bf16 v[20:23], v[184:187], v[16:19], v[20:23]
	v_mfma_f32_16x16x32_bf16 v[24:27], v[192:195], v[16:19], v[24:27]
	s_nop 7
	s_nop 3
	s_waitcnt lgkmcnt(0)
	v_add_f32_e32 v20, v20, v122
	v_add_f32_e32 v21, v21, v123
	v_add_f32_e32 v24, v24, v126
	v_add_f32_e32 v25, v25, v127
	v_mul_f32_e32 v20, 0xbfb8aa3b, v20
	v_mul_f32_e32 v21, 0xbfb8aa3b, v21
	v_mul_f32_e32 v24, 0xbfb8aa3b, v24
	v_mul_f32_e32 v25, 0xbfb8aa3b, v25
	v_exp_f32_e32 v20, v20
	v_exp_f32_e32 v21, v21
	v_exp_f32_e32 v24, v24
	v_exp_f32_e32 v25, v25
	v_add_f32_e32 v20, 1.0, v20
	v_add_f32_e32 v21, 1.0, v21
	v_add_f32_e32 v24, 1.0, v24
	v_add_f32_e32 v25, 1.0, v25
	v_rcp_f32_e32 v20, v20
	v_rcp_f32_e32 v21, v21
	v_rcp_f32_e32 v24, v24
	v_rcp_f32_e32 v25, v25
	v_pk_mul_f32 v[12:13], v[20:21], v[130:131]
	s_nop 0
	v_pk_add_f32 v[14:15], v[12:13], v[12:13]
	v_mul_f32_e32 v20, 0x3fb8aa3b, v12
	v_mul_f32_e32 v21, 0x3fb8aa3b, v13
	v_exp_f32_e32 v20, v20
	v_exp_f32_e32 v21, v21
	v_mul_f32_e32 v16, 0x3e800000, v14
	v_fma_f32 v17, v14, s5, 1.0
	v_mul_f32_e32 v18, 0x3eaaaaab, v14
	v_fma_f32 v16, v16, v17, 1.0
	v_mul_f32_e32 v17, 0.5, v14
	v_fma_f32 v18, v18, v16, 1.0
	v_fma_f32 v17, v17, v18, 1.0
	v_mul_f32_e64 v17, v17, -v14
	v_fma_f32 v16, -v20, v20, 1.0
	v_cmp_lt_f32_e32 vcc, s6, v14
	v_mul_f32_e32 v19, 0x3e800000, v15
	v_fma_f32 v12, v15, s5, 1.0
	v_cndmask_b32_e32 v16, v16, v17, vcc
	v_mul_f32_e32 v13, 0x3eaaaaab, v15
	v_fma_f32 v19, v19, v12, 1.0
	v_mul_f32_e32 v12, 0.5, v15
	v_fma_f32 v13, v13, v19, 1.0
	v_fma_f32 v12, v12, v13, 1.0
	v_mul_f32_e64 v12, v12, -v15
	v_fma_f32 v13, -v21, v21, 1.0
	v_cmp_lt_f32_e32 vcc, s6, v15
	v_sqrt_f32_e32 v16, v16
	s_nop 1
	v_cndmask_b32_e32 v17, v13, v12, vcc
; __device__ __forceinline__ float sigmoidf_(float x) { return __builtin_amdgcn_rcpf(1.0f + __expf(-x)); }
; template <bool FINAL>
; __device__ void phase_lru(const Params& p, int l, unsigned char* smem) {
;     ...
;         for (int et = 0; et < 4; ++et) {
;           f32x4 ar = {0.f, 0.f, 0.f, 0.f}, ai = {0.f, 0.f, 0.f, 0.f};
;           const u16* wr = p.WLRU + ((((size_t)(l * 2 + d) * 2 + 0) * 8 + nb) * 64 + et * 16 + l15) * 64 + g * 8;
;           const u16* wi = p.WLRU + ((((size_t)(l * 2 + d) * 2 + 1) * 8 + nb) * 64 + et * 16 + l15) * 64 + g * 8;
; #pragma unroll
;           for (int ks = 0; ks < 2; ++ks) {
;             ar = mfma16(*(const bf16x8*)(wr + ks * 32), uf[ks], ar);
;             ai = mfma16(*(const bf16x8*)(wi + ks * 32), uf[ks], ai);
;           }
;           const int e0 = et * 16 + 4 * g, ch0 = nb * 64 + e0;
;           const float4 ba4 = *(const float4*)(p.ba + (l * 2 + d) * 512 + ch0);
;           const float4 bx4 = *(const float4*)(p.bx + (l * 2 + d) * 512 + ch0);
;           const float4 sp4 = *(const float4*)(p.SP8 + (l * 2 + d) * 512 + ch0);
;           const float4 uu = *(const float4*)(u32 + t * 64 + e0);
;           const float* bap = (const float*)&ba4; const float* bxp = (const float*)&bx4;
;           const float* spp = (const float*)&sp4; const float* uup = (const float*)&uu;
;           f32x4 av, bv;
; #pragma unroll
;           for (int j = 0; j < 4; ++j) {
;             float r = sigmoidf_(ar[j] + bap[j]);
;             float ig = sigmoidf_(ai[j] + bxp[j]);
;             float la = spp[j] * r;
;             float av_ = __expf(la);
;             float t2 = 2.0f * la;
;             float ser = -t2 * (1.f + t2 * 0.5f * (1.f + t2 * (1.f / 3.f) * (1.f + t2 * 0.25f * (1.f + t2 * 0.2f))));
;             float om = (t2 > -0.25f) ? ser : (1.0f - av_ * av_);
;             av[j] = av_;
;             bv[j] = __builtin_amdgcn_sqrtf(om) * ig * uup[j];
;           }
;           *(f32x4*)(sa + t * 64 + e0) = av;
;           *(f32x4*)(sb + t * 64 + e0) = bv;
;         }
;       }
;       __syncthreads();
	v_sqrt_f32_e32 v17, v17
	s_nop 0
	v_pk_mul_f32 v[24:25], v[24:25], v[16:17]
	s_nop 0
	v_pk_mul_f32 v[24:25], v[28:29], v[24:25]
	v_add_f32_e32 v22, v22, v124
	v_add_f32_e32 v23, v23, v125
	v_add_f32_e32 v26, v26, v128
	v_add_f32_e32 v27, v27, v129
	v_mul_f32_e32 v22, 0xbfb8aa3b, v22
	v_mul_f32_e32 v23, 0xbfb8aa3b, v23
	v_mul_f32_e32 v26, 0xbfb8aa3b, v26
	v_mul_f32_e32 v27, 0xbfb8aa3b, v27
	v_exp_f32_e32 v22, v22
	v_exp_f32_e32 v23, v23
	v_exp_f32_e32 v26, v26
	v_exp_f32_e32 v27, v27
	v_add_f32_e32 v22, 1.0, v22
	v_add_f32_e32 v23, 1.0, v23
	v_add_f32_e32 v26, 1.0, v26
	v_add_f32_e32 v27, 1.0, v27
	v_rcp_f32_e32 v22, v22
	v_rcp_f32_e32 v23, v23
	v_rcp_f32_e32 v26, v26
	v_rcp_f32_e32 v27, v27
	v_pk_mul_f32 v[12:13], v[22:23], v[132:133]
	s_nop 0
	v_pk_add_f32 v[14:15], v[12:13], v[12:13]
	v_mul_f32_e32 v22, 0x3fb8aa3b, v12
	v_mul_f32_e32 v23, 0x3fb8aa3b, v13
	v_exp_f32_e32 v22, v22
	v_exp_f32_e32 v23, v23
	v_mul_f32_e32 v16, 0x3e800000, v14
	v_fma_f32 v17, v14, s5, 1.0
	v_mul_f32_e32 v18, 0x3eaaaaab, v14
	v_fma_f32 v16, v16, v17, 1.0
	v_mul_f32_e32 v17, 0.5, v14
	v_fma_f32 v18, v18, v16, 1.0
	v_fma_f32 v17, v17, v18, 1.0
	v_mul_f32_e64 v17, v17, -v14
	v_fma_f32 v16, -v22, v22, 1.0
	v_cmp_lt_f32_e32 vcc, s6, v14
	v_mul_f32_e32 v19, 0x3e800000, v15
	v_fma_f32 v12, v15, s5, 1.0
	v_cndmask_b32_e32 v16, v16, v17, vcc
	v_mul_f32_e32 v13, 0x3eaaaaab, v15
	v_fma_f32 v19, v19, v12, 1.0
	v_mul_f32_e32 v12, 0.5, v15
	v_fma_f32 v13, v13, v19, 1.0
	v_fma_f32 v12, v12, v13, 1.0
	v_mul_f32_e64 v12, v12, -v15
	v_fma_f32 v13, -v23, v23, 1.0
	v_cmp_lt_f32_e32 vcc, s6, v15
	v_sqrt_f32_e32 v16, v16
	s_nop 1
	v_cndmask_b32_e32 v17, v13, v12, vcc
	v_sqrt_f32_e32 v17, v17
	s_nop 0
	v_pk_mul_f32 v[26:27], v[26:27], v[16:17]
	s_nop 0
	v_pk_mul_f32 v[26:27], v[30:31], v[26:27]
	ds_write_b128 v204, v[20:23] offset:42496
	ds_write_b128 v204, v[24:27] offset:58880
	ds_read_b128 v[12:15], v229 offset:32000
	ds_read_b128 v[16:19], v229 offset:32064
	ds_read_b128 v[28:31], v230 offset:20992
	s_waitcnt lgkmcnt(1)
	v_mfma_f32_16x16x32_bf16 v[20:23], v[180:183], v[12:15], 0
	v_mfma_f32_16x16x32_bf16 v[24:27], v[188:191], v[12:15], 0
	v_mfma_f32_16x16x32_bf16 v[20:23], v[184:187], v[16:19], v[20:23]
	v_mfma_f32_16x16x32_bf16 v[24:27], v[192:195], v[16:19], v[24:27]
	s_nop 7
	s_nop 3
	s_waitcnt lgkmcnt(0)
	v_add_f32_e32 v20, v20, v122
	v_add_f32_e32 v21, v21, v123
	v_add_f32_e32 v24, v24, v126
	v_add_f32_e32 v25, v25, v127
	v_mul_f32_e32 v20, 0xbfb8aa3b, v20
	v_mul_f32_e32 v21, 0xbfb8aa3b, v21
	v_mul_f32_e32 v24, 0xbfb8aa3b, v24
	v_mul_f32_e32 v25, 0xbfb8aa3b, v25
	v_exp_f32_e32 v20, v20
	v_exp_f32_e32 v21, v21
	v_exp_f32_e32 v24, v24
	v_exp_f32_e32 v25, v25
	v_add_f32_e32 v20, 1.0, v20
	v_add_f32_e32 v21, 1.0, v21
	v_add_f32_e32 v24, 1.0, v24
	v_add_f32_e32 v25, 1.0, v25
	v_rcp_f32_e32 v20, v20
	v_rcp_f32_e32 v21, v21
	v_rcp_f32_e32 v24, v24
	v_rcp_f32_e32 v25, v25
	v_pk_mul_f32 v[12:13], v[20:21], v[130:131]
	s_nop 0
	v_pk_add_f32 v[14:15], v[12:13], v[12:13]
	v_mul_f32_e32 v20, 0x3fb8aa3b, v12
	v_mul_f32_e32 v21, 0x3fb8aa3b, v13
	v_exp_f32_e32 v20, v20
	v_exp_f32_e32 v21, v21
	v_mul_f32_e32 v16, 0x3e800000, v14
	v_fma_f32 v17, v14, s5, 1.0
	v_mul_f32_e32 v18, 0x3eaaaaab, v14
	v_fma_f32 v16, v16, v17, 1.0
	v_mul_f32_e32 v17, 0.5, v14
	v_fma_f32 v18, v18, v16, 1.0
	v_fma_f32 v17, v17, v18, 1.0
	v_mul_f32_e64 v17, v17, -v14
	v_fma_f32 v16, -v20, v20, 1.0
	v_cmp_lt_f32_e32 vcc, s6, v14
	v_mul_f32_e32 v19, 0x3e800000, v15
	v_fma_f32 v12, v15, s5, 1.0
	v_cndmask_b32_e32 v16, v16, v17, vcc
	v_mul_f32_e32 v13, 0x3eaaaaab, v15
	v_fma_f32 v19, v19, v12, 1.0
	v_mul_f32_e32 v12, 0.5, v15
	v_fma_f32 v13, v13, v19, 1.0
	v_fma_f32 v12, v12, v13, 1.0
	v_mul_f32_e64 v12, v12, -v15
	v_fma_f32 v13, -v21, v21, 1.0
	v_cmp_lt_f32_e32 vcc, s6, v15
	v_sqrt_f32_e32 v16, v16
	s_nop 1
	v_cndmask_b32_e32 v17, v13, v12, vcc
	v_sqrt_f32_e32 v17, v17
	s_nop 0
	v_pk_mul_f32 v[24:25], v[24:25], v[16:17]
	s_nop 0
	v_pk_mul_f32 v[24:25], v[28:29], v[24:25]
	v_add_f32_e32 v22, v22, v124
	v_add_f32_e32 v23, v23, v125
	v_add_f32_e32 v26, v26, v128
	v_add_f32_e32 v27, v27, v129
	v_mul_f32_e32 v22, 0xbfb8aa3b, v22
	v_mul_f32_e32 v23, 0xbfb8aa3b, v23
	v_mul_f32_e32 v26, 0xbfb8aa3b, v26
	v_mul_f32_e32 v27, 0xbfb8aa3b, v27
	v_exp_f32_e32 v22, v22
	v_exp_f32_e32 v23, v23
	v_exp_f32_e32 v26, v26
	v_exp_f32_e32 v27, v27
	v_add_f32_e32 v22, 1.0, v22
	v_add_f32_e32 v23, 1.0, v23
	v_add_f32_e32 v26, 1.0, v26
	v_add_f32_e32 v27, 1.0, v27
	v_rcp_f32_e32 v22, v22
	v_rcp_f32_e32 v23, v23
	v_rcp_f32_e32 v26, v26
	v_rcp_f32_e32 v27, v27
	v_pk_mul_f32 v[12:13], v[22:23], v[132:133]
	s_nop 0
	v_pk_add_f32 v[14:15], v[12:13], v[12:13]
	v_mul_f32_e32 v22, 0x3fb8aa3b, v12
	v_mul_f32_e32 v23, 0x3fb8aa3b, v13
	v_exp_f32_e32 v22, v22
	v_exp_f32_e32 v23, v23
	v_mul_f32_e32 v16, 0x3e800000, v14
	v_fma_f32 v17, v14, s5, 1.0
	v_mul_f32_e32 v18, 0x3eaaaaab, v14
	v_fma_f32 v16, v16, v17, 1.0
	v_mul_f32_e32 v17, 0.5, v14
	v_fma_f32 v18, v18, v16, 1.0
	v_fma_f32 v17, v17, v18, 1.0
	v_mul_f32_e64 v17, v17, -v14
	v_fma_f32 v16, -v22, v22, 1.0
	v_cmp_lt_f32_e32 vcc, s6, v14
	v_mul_f32_e32 v19, 0x3e800000, v15
	v_fma_f32 v12, v15, s5, 1.0
	v_cndmask_b32_e32 v16, v16, v17, vcc
	v_mul_f32_e32 v13, 0x3eaaaaab, v15
	v_fma_f32 v19, v19, v12, 1.0
	v_mul_f32_e32 v12, 0.5, v15
	v_fma_f32 v13, v13, v19, 1.0
	v_fma_f32 v12, v12, v13, 1.0
	v_mul_f32_e64 v12, v12, -v15
	v_fma_f32 v13, -v23, v23, 1.0
	v_cmp_lt_f32_e32 vcc, s6, v15
	v_sqrt_f32_e32 v16, v16
	s_nop 1
	v_cndmask_b32_e32 v17, v13, v12, vcc
	v_sqrt_f32_e32 v17, v17
	s_nop 0
	v_pk_mul_f32 v[26:27], v[26:27], v[16:17]
	s_nop 0
	v_pk_mul_f32 v[26:27], v[30:31], v[26:27]
	ds_write_b128 v204, v[20:23] offset:46592
	ds_write_b128 v204, v[24:27] offset:62976
	s_waitcnt lgkmcnt(0)
	s_barrier
; template <bool FINAL>
; __device__ void phase_lru(const Params& p, int l, unsigned char* smem) {
;     ...
;       {
;         bf16x8 uf[2];
;         uf[0] = *(const bf16x8*)(ub + (16 * w + l15) * 72 + g * 8);
;         uf[1] = *(const bf16x8*)(ub + (16 * w + l15) * 72 + 32 + g * 8);
;         const int t = 16 * w + l15;
; #pragma unroll
;         for (int et = 0; et < 4; ++et) {
;           f32x4 ar = {0.f, 0.f, 0.f, 0.f}, ai = {0.f, 0.f, 0.f, 0.f};
;           const u16* wr = p.WLRU + ((((size_t)(l * 2 + d) * 2 + 0) * 8 + nb) * 64 + et * 16 + l15) * 64 + g * 8;
;           const u16* wi = p.WLRU + ((((size_t)(l * 2 + d) * 2 + 1) * 8 + nb) * 64 + et * 16 + l15) * 64 + g * 8;
; #pragma unroll
;           for (int ks = 0; ks < 2; ++ks) {
;             ar = mfma16(*(const bf16x8*)(wr + ks * 32), uf[ks], ar);
;             ai = mfma16(*(const bf16x8*)(wi + ks * 32), uf[ks], ai);
;           }
;           const int e0 = et * 16 + 4 * g, ch0 = nb * 64 + e0;
;           const float4 ba4 = *(const float4*)(p.ba + (l * 2 + d) * 512 + ch0);
;           const float4 bx4 = *(const float4*)(p.bx + (l * 2 + d) * 512 + ch0);
;           const float4 sp4 = *(const float4*)(p.SP8 + (l * 2 + d) * 512 + ch0);
;           const float4 uu = *(const float4*)(u32 + t * 64 + e0);
;           const float* bap = (const float*)&ba4; const float* bxp = (const float*)&bx4;
;     ...
;       {
;         float A = 1.f, B = 0.f;
;         if (d == 0) {
; #pragma unroll
;           for (int tt = 0; tt < 16; ++tt) { int t = qd * 16 + tt; float a = sa[t * 64 + e_], b = sb[t * 64 + e_]; B = a * B + b; A *= a; }
;         } else {
; #pragma unroll
;     ...
;         }
;         part[(0 * 4 + qd) * 64 + e_] = A;
;         part[(1 * 4 + qd) * 64 + e_] = B;
;       }
;       __syncthreads();
;       if (!FINAL) {
;         if (qd == 0) {
;           float A = 1.f, B = 0.f;
;           if (d == 0) {
; #pragma unroll
;             for (int q = 0; q < 4; ++q) { float aq = part[q * 64 + e_], bq = part[(4 + q) * 64 + e_]; B = aq * B + bq; A *= aq; }
;           } else {
; #pragma unroll
;             for (int q = 3; q >= 0; --q) { float aq = part[q * 64 + e_], bq = part[(4 + q) * 64 + e_]; B = aq * B + bq; A *= aq; }
;           }
;           const size_t cidx = ((size_t)ci * 2 + d) * 512 + nb * 64 + e_;
;           p.CA[cidx] = A; p.CB[cidx] = B;
;         }
	ds_read2st64_b32 v[12:13], v49 offset0:134 offset1:198
	ds_read2st64_b32 v[14:15], v82 offset0:134 offset1:198
	ds_read2st64_b32 v[16:17], v83 offset0:134 offset1:198
	s_waitcnt lgkmcnt(2)
	v_fmac_f32_e32 v13, 0, v12
	s_waitcnt lgkmcnt(1)
	v_mul_f32_e32 v18, v12, v14
	s_waitcnt lgkmcnt(0)
	v_mul_f32_e32 v20, v18, v16
	ds_read2st64_b32 v[18:19], v84 offset0:134 offset1:198
	v_fmac_f32_e32 v15, v14, v13
	v_fmac_f32_e32 v17, v16, v15
	v_lshlrev_b64 v[12:13], 2, v[50:51]
	v_lshl_add_u64 v[50:51], s[86:87], 0, v[12:13]
	s_waitcnt lgkmcnt(0)
	v_mul_f32_e32 v22, v20, v18
	ds_read2st64_b32 v[20:21], v85 offset0:134 offset1:198
	v_fmac_f32_e32 v19, v18, v17
	s_waitcnt lgkmcnt(0)
	v_mul_f32_e32 v24, v22, v20
	ds_read2st64_b32 v[22:23], v86 offset0:134 offset1:198
	v_fmac_f32_e32 v21, v20, v19
	s_waitcnt lgkmcnt(0)
	v_mul_f32_e32 v26, v24, v22
	ds_read2st64_b32 v[24:25], v87 offset0:134 offset1:198
	v_fmac_f32_e32 v23, v22, v21
	s_waitcnt lgkmcnt(0)
	v_mul_f32_e32 v28, v26, v24
	ds_read2st64_b32 v[26:27], v88 offset0:134 offset1:198
	v_fmac_f32_e32 v25, v24, v23
	s_waitcnt lgkmcnt(0)
	v_mul_f32_e32 v30, v28, v26
	ds_read2st64_b32 v[28:29], v89 offset0:134 offset1:198
	v_fmac_f32_e32 v27, v26, v25
	s_waitcnt lgkmcnt(0)
	v_mul_f32_e32 v32, v30, v28
	ds_read2st64_b32 v[30:31], v90 offset0:134 offset1:198
	v_fmac_f32_e32 v29, v28, v27
	s_waitcnt lgkmcnt(0)
	v_mul_f32_e32 v34, v32, v30
	ds_read2st64_b32 v[32:33], v91 offset0:134 offset1:198
	v_fmac_f32_e32 v31, v30, v29
	s_waitcnt lgkmcnt(0)
	v_mul_f32_e32 v52, v34, v32
	ds_read2st64_b32 v[34:35], v92 offset0:134 offset1:198
	v_fmac_f32_e32 v33, v32, v31
	s_waitcnt lgkmcnt(0)
	v_mul_f32_e32 v104, v52, v34
	ds_read2st64_b32 v[52:53], v93 offset0:134 offset1:198
	v_fmac_f32_e32 v35, v34, v33
	s_waitcnt lgkmcnt(0)
	v_mul_f32_e32 v106, v104, v52
	ds_read2st64_b32 v[104:105], v94 offset0:134 offset1:198
	v_fmac_f32_e32 v53, v52, v35
	s_waitcnt lgkmcnt(0)
	v_mul_f32_e32 v108, v106, v104
	ds_read2st64_b32 v[106:107], v95 offset0:134 offset1:198
	v_fmac_f32_e32 v105, v104, v53
	v_lshl_add_u64 v[52:53], s[88:89], 0, v[12:13]
	s_waitcnt lgkmcnt(0)
	v_mul_f32_e32 v110, v108, v106
	ds_read2st64_b32 v[108:109], v96 offset0:134 offset1:198
	v_fmac_f32_e32 v107, v106, v105
	s_waitcnt lgkmcnt(0)
	v_mul_f32_e32 v110, v110, v108
	v_fmac_f32_e32 v109, v108, v107
	ds_write_b32 v64, v110
	ds_write_b32 v65, v109 offset:1024
	s_waitcnt lgkmcnt(0)
	s_barrier
	s_and_saveexec_b64 s[42:43], s[40:41]
	s_cbranch_execz .LBB0_387
	ds_read2st64_b32 v[12:13], v64 offset1:1
	ds_read2st64_b32 v[14:15], v64 offset0:2 offset1:3
	s_waitcnt lgkmcnt(1)
	v_mul_f32_e32 v16, v12, v13
	s_waitcnt lgkmcnt(0)
	v_mul_f32_e32 v16, v16, v14
	v_mul_f32_e32 v18, v16, v15
	ds_read2st64_b32 v[16:17], v64 offset0:4 offset1:5
	s_waitcnt lgkmcnt(0)
	v_fma_f32 v12, 0, v12, v16
	v_fmac_f32_e32 v17, v13, v12
	ds_read2st64_b32 v[12:13], v64 offset0:6 offset1:7
	s_waitcnt lgkmcnt(0)
	v_fma_f32 v12, v14, v17, v12
	v_fmac_f32_e32 v13, v15, v12
	global_store_dword v[50:51], v18, off
	global_store_dword v[52:53], v13, off
.LBB0_387:
	s_or_b64 exec, exec, s[42:43]
	v_lshl_add_u64 v[20:21], s[50:51], 0, v[144:145]
	v_lshl_add_u64 v[28:29], v[20:21], 0, v[54:55]
	s_barrier
	s_mov_b32 s5, 0x3e4ccccd
	ds_read_b128 v[12:15], v229 offset:25088
	ds_read_b128 v[16:19], v229 offset:25152
	ds_read_b128 v[28:31], v230 offset:8704
	s_waitcnt lgkmcnt(1)
	v_mfma_f32_16x16x32_bf16 v[20:23], v[232:235], v[12:15], 0
	v_mfma_f32_16x16x32_bf16 v[24:27], v[240:243], v[12:15], 0
	v_mfma_f32_16x16x32_bf16 v[20:23], v[236:239], v[16:19], v[20:23]
	v_mfma_f32_16x16x32_bf16 v[24:27], v[244:247], v[16:19], v[24:27]
	s_nop 7
	s_nop 3
	s_waitcnt lgkmcnt(0)
	v_add_f32_e32 v20, v20, v134
	v_add_f32_e32 v21, v21, v135
	v_add_f32_e32 v24, v24, v138
	v_add_f32_e32 v25, v25, v139
	v_mul_f32_e32 v20, 0xbfb8aa3b, v20
	v_mul_f32_e32 v21, 0xbfb8aa3b, v21
	v_mul_f32_e32 v24, 0xbfb8aa3b, v24
	v_mul_f32_e32 v25, 0xbfb8aa3b, v25
	v_exp_f32_e32 v20, v20
	v_exp_f32_e32 v21, v21
	v_exp_f32_e32 v24, v24
	v_exp_f32_e32 v25, v25
	v_add_f32_e32 v20, 1.0, v20
	v_add_f32_e32 v21, 1.0, v21
	v_add_f32_e32 v24, 1.0, v24
	v_add_f32_e32 v25, 1.0, v25
	v_rcp_f32_e32 v20, v20
	v_rcp_f32_e32 v21, v21
	v_rcp_f32_e32 v24, v24
	v_rcp_f32_e32 v25, v25
	v_pk_mul_f32 v[12:13], v[20:21], v[150:151]
	s_nop 0
	v_pk_add_f32 v[14:15], v[12:13], v[12:13]
	v_mul_f32_e32 v20, 0x3fb8aa3b, v12
	v_mul_f32_e32 v21, 0x3fb8aa3b, v13
	v_exp_f32_e32 v20, v20
	v_exp_f32_e32 v21, v21
	v_mul_f32_e32 v16, 0x3e800000, v14
	v_fma_f32 v17, v14, s5, 1.0
	v_mul_f32_e32 v18, 0x3eaaaaab, v14
	v_fma_f32 v16, v16, v17, 1.0
	v_mul_f32_e32 v17, 0.5, v14
	v_fma_f32 v18, v18, v16, 1.0
	v_fma_f32 v17, v17, v18, 1.0
	v_mul_f32_e64 v17, v17, -v14
	v_fma_f32 v16, -v20, v20, 1.0
	v_cmp_lt_f32_e32 vcc, s6, v14
	v_mul_f32_e32 v19, 0x3e800000, v15
	v_fma_f32 v12, v15, s5, 1.0
	v_cndmask_b32_e32 v16, v16, v17, vcc
	v_mul_f32_e32 v13, 0x3eaaaaab, v15
	v_fma_f32 v19, v19, v12, 1.0
	v_mul_f32_e32 v12, 0.5, v15
	v_fma_f32 v13, v13, v19, 1.0
	v_fma_f32 v12, v12, v13, 1.0
	v_mul_f32_e64 v12, v12, -v15
	v_fma_f32 v13, -v21, v21, 1.0
	v_cmp_lt_f32_e32 vcc, s6, v15
	v_sqrt_f32_e32 v16, v16
	s_nop 1
	v_cndmask_b32_e32 v17, v13, v12, vcc
	v_sqrt_f32_e32 v17, v17
	s_nop 0
	v_pk_mul_f32 v[24:25], v[24:25], v[16:17]
	s_nop 0
	v_pk_mul_f32 v[24:25], v[28:29], v[24:25]
	v_add_f32_e32 v22, v22, v136
	v_add_f32_e32 v23, v23, v137
	v_add_f32_e32 v26, v26, v140
	v_add_f32_e32 v27, v27, v141
	v_mul_f32_e32 v22, 0xbfb8aa3b, v22
	v_mul_f32_e32 v23, 0xbfb8aa3b, v23
	v_mul_f32_e32 v26, 0xbfb8aa3b, v26
	v_mul_f32_e32 v27, 0xbfb8aa3b, v27
	v_exp_f32_e32 v22, v22
	v_exp_f32_e32 v23, v23
; __device__ __forceinline__ float sigmoidf_(float x) { return __builtin_amdgcn_rcpf(1.0f + __expf(-x)); }
; template <bool FINAL>
; __device__ void phase_lru(const Params& p, int l, unsigned char* smem) {
;     ...
; #pragma unroll
;         for (int et = 0; et < 4; ++et) {
;           f32x4 ar = {0.f, 0.f, 0.f, 0.f}, ai = {0.f, 0.f, 0.f, 0.f};
;           const u16* wr = p.WLRU + ((((size_t)(l * 2 + d) * 2 + 0) * 8 + nb) * 64 + et * 16 + l15) * 64 + g * 8;
;           const u16* wi = p.WLRU + ((((size_t)(l * 2 + d) * 2 + 1) * 8 + nb) * 64 + et * 16 + l15) * 64 + g * 8;
; #pragma unroll
;           for (int ks = 0; ks < 2; ++ks) {
;             ar = mfma16(*(const bf16x8*)(wr + ks * 32), uf[ks], ar);
;             ai = mfma16(*(const bf16x8*)(wi + ks * 32), uf[ks], ai);
;           }
;           const int e0 = et * 16 + 4 * g, ch0 = nb * 64 + e0;
;           const float4 ba4 = *(const float4*)(p.ba + (l * 2 + d) * 512 + ch0);
;           const float4 bx4 = *(const float4*)(p.bx + (l * 2 + d) * 512 + ch0);
;           const float4 sp4 = *(const float4*)(p.SP8 + (l * 2 + d) * 512 + ch0);
;           const float4 uu = *(const float4*)(u32 + t * 64 + e0);
;           const float* bap = (const float*)&ba4; const float* bxp = (const float*)&bx4;
;           const float* spp = (const float*)&sp4; const float* uup = (const float*)&uu;
;           f32x4 av, bv;
; #pragma unroll
;           for (int j = 0; j < 4; ++j) {
;             float r = sigmoidf_(ar[j] + bap[j]);
;             float ig = sigmoidf_(ai[j] + bxp[j]);
;             float la = spp[j] * r;
;             float av_ = __expf(la);
;             float t2 = 2.0f * la;
;             float ser = -t2 * (1.f + t2 * 0.5f * (1.f + t2 * (1.f / 3.f) * (1.f + t2 * 0.25f * (1.f + t2 * 0.2f))));
;             float om = (t2 > -0.25f) ? ser : (1.0f - av_ * av_);
;             av[j] = av_;
;             bv[j] = __builtin_amdgcn_sqrtf(om) * ig * uup[j];
;           }
;           *(f32x4*)(sa + t * 64 + e0) = av;
;           *(f32x4*)(sb + t * 64 + e0) = bv;
;         }
	v_exp_f32_e32 v26, v26
	v_exp_f32_e32 v27, v27
	v_add_f32_e32 v22, 1.0, v22
	v_add_f32_e32 v23, 1.0, v23
	v_add_f32_e32 v26, 1.0, v26
	v_add_f32_e32 v27, 1.0, v27
	v_rcp_f32_e32 v22, v22
	v_rcp_f32_e32 v23, v23
	v_rcp_f32_e32 v26, v26
	v_rcp_f32_e32 v27, v27
	v_pk_mul_f32 v[12:13], v[22:23], v[152:153]
	s_nop 0
	v_pk_add_f32 v[14:15], v[12:13], v[12:13]
	v_mul_f32_e32 v22, 0x3fb8aa3b, v12
	v_mul_f32_e32 v23, 0x3fb8aa3b, v13
	v_exp_f32_e32 v22, v22
	v_exp_f32_e32 v23, v23
	v_mul_f32_e32 v16, 0x3e800000, v14
	v_fma_f32 v17, v14, s5, 1.0
	v_mul_f32_e32 v18, 0x3eaaaaab, v14
	v_fma_f32 v16, v16, v17, 1.0
	v_mul_f32_e32 v17, 0.5, v14
	v_fma_f32 v18, v18, v16, 1.0
	v_fma_f32 v17, v17, v18, 1.0
	v_mul_f32_e64 v17, v17, -v14
	v_fma_f32 v16, -v22, v22, 1.0
	v_cmp_lt_f32_e32 vcc, s6, v14
	v_mul_f32_e32 v19, 0x3e800000, v15
	v_fma_f32 v12, v15, s5, 1.0
	v_cndmask_b32_e32 v16, v16, v17, vcc
	v_mul_f32_e32 v13, 0x3eaaaaab, v15
	v_fma_f32 v19, v19, v12, 1.0
	v_mul_f32_e32 v12, 0.5, v15
	v_fma_f32 v13, v13, v19, 1.0
	v_fma_f32 v12, v12, v13, 1.0
	v_mul_f32_e64 v12, v12, -v15
	v_fma_f32 v13, -v23, v23, 1.0
	v_cmp_lt_f32_e32 vcc, s6, v15
	v_sqrt_f32_e32 v16, v16
	s_nop 1
	v_cndmask_b32_e32 v17, v13, v12, vcc
	v_sqrt_f32_e32 v17, v17
	s_nop 0
	v_pk_mul_f32 v[26:27], v[26:27], v[16:17]
	s_nop 0
	v_pk_mul_f32 v[26:27], v[30:31], v[26:27]
	ds_write_b128 v204, v[20:23] offset:34304
	ds_write_b128 v204, v[24:27] offset:50688
	ds_read_b128 v[12:15], v229 offset:27392
	ds_read_b128 v[16:19], v229 offset:27456
	ds_read_b128 v[28:31], v230 offset:12800
	s_waitcnt lgkmcnt(1)
	v_mfma_f32_16x16x32_bf16 v[20:23], v[232:235], v[12:15], 0
	v_mfma_f32_16x16x32_bf16 v[24:27], v[240:243], v[12:15], 0
	v_mfma_f32_16x16x32_bf16 v[20:23], v[236:239], v[16:19], v[20:23]
	v_mfma_f32_16x16x32_bf16 v[24:27], v[244:247], v[16:19], v[24:27]
	s_nop 7
	s_nop 3
	s_waitcnt lgkmcnt(0)
	v_add_f32_e32 v20, v20, v134
	v_add_f32_e32 v21, v21, v135
	v_add_f32_e32 v24, v24, v138
	v_add_f32_e32 v25, v25, v139
	v_mul_f32_e32 v20, 0xbfb8aa3b, v20
	v_mul_f32_e32 v21, 0xbfb8aa3b, v21
	v_mul_f32_e32 v24, 0xbfb8aa3b, v24
	v_mul_f32_e32 v25, 0xbfb8aa3b, v25
	v_exp_f32_e32 v20, v20
	v_exp_f32_e32 v21, v21
	v_exp_f32_e32 v24, v24
	v_exp_f32_e32 v25, v25
	v_add_f32_e32 v20, 1.0, v20
	v_add_f32_e32 v21, 1.0, v21
	v_add_f32_e32 v24, 1.0, v24
	v_add_f32_e32 v25, 1.0, v25
	v_rcp_f32_e32 v20, v20
	v_rcp_f32_e32 v21, v21
	v_rcp_f32_e32 v24, v24
	v_rcp_f32_e32 v25, v25
	v_pk_mul_f32 v[12:13], v[20:21], v[150:151]
	s_nop 0
	v_pk_add_f32 v[14:15], v[12:13], v[12:13]
	v_mul_f32_e32 v20, 0x3fb8aa3b, v12
	v_mul_f32_e32 v21, 0x3fb8aa3b, v13
	v_exp_f32_e32 v20, v20
	v_exp_f32_e32 v21, v21
	v_mul_f32_e32 v16, 0x3e800000, v14
	v_fma_f32 v17, v14, s5, 1.0
	v_mul_f32_e32 v18, 0x3eaaaaab, v14
	v_fma_f32 v16, v16, v17, 1.0
	v_mul_f32_e32 v17, 0.5, v14
	v_fma_f32 v18, v18, v16, 1.0
	v_fma_f32 v17, v17, v18, 1.0
	v_mul_f32_e64 v17, v17, -v14
	v_fma_f32 v16, -v20, v20, 1.0
	v_cmp_lt_f32_e32 vcc, s6, v14
	v_mul_f32_e32 v19, 0x3e800000, v15
	v_fma_f32 v12, v15, s5, 1.0
	v_cndmask_b32_e32 v16, v16, v17, vcc
	v_mul_f32_e32 v13, 0x3eaaaaab, v15
	v_fma_f32 v19, v19, v12, 1.0
	v_mul_f32_e32 v12, 0.5, v15
	v_fma_f32 v13, v13, v19, 1.0
	v_fma_f32 v12, v12, v13, 1.0
	v_mul_f32_e64 v12, v12, -v15
	v_fma_f32 v13, -v21, v21, 1.0
	v_cmp_lt_f32_e32 vcc, s6, v15
	v_sqrt_f32_e32 v16, v16
	s_nop 1
	v_cndmask_b32_e32 v17, v13, v12, vcc
	v_sqrt_f32_e32 v17, v17
	s_nop 0
	v_pk_mul_f32 v[24:25], v[24:25], v[16:17]
	s_nop 0
	v_pk_mul_f32 v[24:25], v[28:29], v[24:25]
	v_add_f32_e32 v22, v22, v136
	v_add_f32_e32 v23, v23, v137
	v_add_f32_e32 v26, v26, v140
	v_add_f32_e32 v27, v27, v141
	v_mul_f32_e32 v22, 0xbfb8aa3b, v22
	v_mul_f32_e32 v23, 0xbfb8aa3b, v23
	v_mul_f32_e32 v26, 0xbfb8aa3b, v26
	v_mul_f32_e32 v27, 0xbfb8aa3b, v27
	v_exp_f32_e32 v22, v22
	v_exp_f32_e32 v23, v23
	v_exp_f32_e32 v26, v26
	v_exp_f32_e32 v27, v27
	v_add_f32_e32 v22, 1.0, v22
	v_add_f32_e32 v23, 1.0, v23
	v_add_f32_e32 v26, 1.0, v26
	v_add_f32_e32 v27, 1.0, v27
	v_rcp_f32_e32 v22, v22
	v_rcp_f32_e32 v23, v23
	v_rcp_f32_e32 v26, v26
	v_rcp_f32_e32 v27, v27
	v_pk_mul_f32 v[12:13], v[22:23], v[152:153]
	s_nop 0
	v_pk_add_f32 v[14:15], v[12:13], v[12:13]
	v_mul_f32_e32 v22, 0x3fb8aa3b, v12
	v_mul_f32_e32 v23, 0x3fb8aa3b, v13
	v_exp_f32_e32 v22, v22
	v_exp_f32_e32 v23, v23
	v_mul_f32_e32 v16, 0x3e800000, v14
	v_fma_f32 v17, v14, s5, 1.0
	v_mul_f32_e32 v18, 0x3eaaaaab, v14
	v_fma_f32 v16, v16, v17, 1.0
	v_mul_f32_e32 v17, 0.5, v14
	v_fma_f32 v18, v18, v16, 1.0
	v_fma_f32 v17, v17, v18, 1.0
	v_mul_f32_e64 v17, v17, -v14
	v_fma_f32 v16, -v22, v22, 1.0
	v_cmp_lt_f32_e32 vcc, s6, v14
	v_mul_f32_e32 v19, 0x3e800000, v15
	v_fma_f32 v12, v15, s5, 1.0
	v_cndmask_b32_e32 v16, v16, v17, vcc
	v_mul_f32_e32 v13, 0x3eaaaaab, v15
	v_fma_f32 v19, v19, v12, 1.0
	v_mul_f32_e32 v12, 0.5, v15
	v_fma_f32 v13, v13, v19, 1.0
	v_fma_f32 v12, v12, v13, 1.0
	v_mul_f32_e64 v12, v12, -v15
	v_fma_f32 v13, -v23, v23, 1.0
	v_cmp_lt_f32_e32 vcc, s6, v15
	v_sqrt_f32_e32 v16, v16
	s_nop 1
	v_cndmask_b32_e32 v17, v13, v12, vcc
	v_sqrt_f32_e32 v17, v17
	s_nop 0
	v_pk_mul_f32 v[26:27], v[26:27], v[16:17]
	s_nop 0
	v_pk_mul_f32 v[26:27], v[30:31], v[26:27]
	ds_write_b128 v204, v[20:23] offset:38400
	ds_write_b128 v204, v[24:27] offset:54784
	ds_read_b128 v[12:15], v229 offset:29696
	ds_read_b128 v[16:19], v229 offset:29760
	ds_read_b128 v[28:31], v230 offset:16896
	s_waitcnt lgkmcnt(1)
	v_mfma_f32_16x16x32_bf16 v[20:23], v[232:235], v[12:15], 0
	v_mfma_f32_16x16x32_bf16 v[24:27], v[240:243], v[12:15], 0
	v_mfma_f32_16x16x32_bf16 v[20:23], v[236:239], v[16:19], v[20:23]
	v_mfma_f32_16x16x32_bf16 v[24:27], v[244:247], v[16:19], v[24:27]
	s_nop 7
	s_nop 3
	s_waitcnt lgkmcnt(0)
; __device__ __forceinline__ float sigmoidf_(float x) { return __builtin_amdgcn_rcpf(1.0f + __expf(-x)); }
; template <bool FINAL>
; __device__ void phase_lru(const Params& p, int l, unsigned char* smem) {
;     ...
; #pragma unroll
;         for (int et = 0; et < 4; ++et) {
;           f32x4 ar = {0.f, 0.f, 0.f, 0.f}, ai = {0.f, 0.f, 0.f, 0.f};
;           const u16* wr = p.WLRU + ((((size_t)(l * 2 + d) * 2 + 0) * 8 + nb) * 64 + et * 16 + l15) * 64 + g * 8;
;           const u16* wi = p.WLRU + ((((size_t)(l * 2 + d) * 2 + 1) * 8 + nb) * 64 + et * 16 + l15) * 64 + g * 8;
; #pragma unroll
;           for (int ks = 0; ks < 2; ++ks) {
;             ar = mfma16(*(const bf16x8*)(wr + ks * 32), uf[ks], ar);
;             ai = mfma16(*(const bf16x8*)(wi + ks * 32), uf[ks], ai);
;           }
;           const int e0 = et * 16 + 4 * g, ch0 = nb * 64 + e0;
;           const float4 ba4 = *(const float4*)(p.ba + (l * 2 + d) * 512 + ch0);
;           const float4 bx4 = *(const float4*)(p.bx + (l * 2 + d) * 512 + ch0);
;           const float4 sp4 = *(const float4*)(p.SP8 + (l * 2 + d) * 512 + ch0);
;           const float4 uu = *(const float4*)(u32 + t * 64 + e0);
;           const float* bap = (const float*)&ba4; const float* bxp = (const float*)&bx4;
;           const float* spp = (const float*)&sp4; const float* uup = (const float*)&uu;
;           f32x4 av, bv;
; #pragma unroll
;           for (int j = 0; j < 4; ++j) {
;             float r = sigmoidf_(ar[j] + bap[j]);
;             float ig = sigmoidf_(ai[j] + bxp[j]);
;             float la = spp[j] * r;
;             float av_ = __expf(la);
;             float t2 = 2.0f * la;
;             float ser = -t2 * (1.f + t2 * 0.5f * (1.f + t2 * (1.f / 3.f) * (1.f + t2 * 0.25f * (1.f + t2 * 0.2f))));
;             float om = (t2 > -0.25f) ? ser : (1.0f - av_ * av_);
;             av[j] = av_;
;             bv[j] = __builtin_amdgcn_sqrtf(om) * ig * uup[j];
;           }
;           *(f32x4*)(sa + t * 64 + e0) = av;
;           *(f32x4*)(sb + t * 64 + e0) = bv;
;         }
	v_add_f32_e32 v20, v20, v134
	v_add_f32_e32 v21, v21, v135
	v_add_f32_e32 v24, v24, v138
	v_add_f32_e32 v25, v25, v139
	v_mul_f32_e32 v20, 0xbfb8aa3b, v20
	v_mul_f32_e32 v21, 0xbfb8aa3b, v21
	v_mul_f32_e32 v24, 0xbfb8aa3b, v24
	v_mul_f32_e32 v25, 0xbfb8aa3b, v25
	v_exp_f32_e32 v20, v20
	v_exp_f32_e32 v21, v21
	v_exp_f32_e32 v24, v24
	v_exp_f32_e32 v25, v25
	v_add_f32_e32 v20, 1.0, v20
	v_add_f32_e32 v21, 1.0, v21
	v_add_f32_e32 v24, 1.0, v24
	v_add_f32_e32 v25, 1.0, v25
	v_rcp_f32_e32 v20, v20
	v_rcp_f32_e32 v21, v21
	v_rcp_f32_e32 v24, v24
	v_rcp_f32_e32 v25, v25
	v_pk_mul_f32 v[12:13], v[20:21], v[150:151]
	s_nop 0
	v_pk_add_f32 v[14:15], v[12:13], v[12:13]
	v_mul_f32_e32 v20, 0x3fb8aa3b, v12
	v_mul_f32_e32 v21, 0x3fb8aa3b, v13
	v_exp_f32_e32 v20, v20
	v_exp_f32_e32 v21, v21
	v_mul_f32_e32 v16, 0x3e800000, v14
	v_fma_f32 v17, v14, s5, 1.0
	v_mul_f32_e32 v18, 0x3eaaaaab, v14
	v_fma_f32 v16, v16, v17, 1.0
	v_mul_f32_e32 v17, 0.5, v14
	v_fma_f32 v18, v18, v16, 1.0
	v_fma_f32 v17, v17, v18, 1.0
	v_mul_f32_e64 v17, v17, -v14
	v_fma_f32 v16, -v20, v20, 1.0
	v_cmp_lt_f32_e32 vcc, s6, v14
	v_mul_f32_e32 v19, 0x3e800000, v15
	v_fma_f32 v12, v15, s5, 1.0
	v_cndmask_b32_e32 v16, v16, v17, vcc
	v_mul_f32_e32 v13, 0x3eaaaaab, v15
	v_fma_f32 v19, v19, v12, 1.0
	v_mul_f32_e32 v12, 0.5, v15
	v_fma_f32 v13, v13, v19, 1.0
	v_fma_f32 v12, v12, v13, 1.0
	v_mul_f32_e64 v12, v12, -v15
	v_fma_f32 v13, -v21, v21, 1.0
	v_cmp_lt_f32_e32 vcc, s6, v15
	v_sqrt_f32_e32 v16, v16
	s_nop 1
	v_cndmask_b32_e32 v17, v13, v12, vcc
	v_sqrt_f32_e32 v17, v17
	s_nop 0
	v_pk_mul_f32 v[24:25], v[24:25], v[16:17]
	s_nop 0
	v_pk_mul_f32 v[24:25], v[28:29], v[24:25]
	v_add_f32_e32 v22, v22, v136
	v_add_f32_e32 v23, v23, v137
	v_add_f32_e32 v26, v26, v140
	v_add_f32_e32 v27, v27, v141
	v_mul_f32_e32 v22, 0xbfb8aa3b, v22
	v_mul_f32_e32 v23, 0xbfb8aa3b, v23
	v_mul_f32_e32 v26, 0xbfb8aa3b, v26
	v_mul_f32_e32 v27, 0xbfb8aa3b, v27
	v_exp_f32_e32 v22, v22
	v_exp_f32_e32 v23, v23
	v_exp_f32_e32 v26, v26
	v_exp_f32_e32 v27, v27
	v_add_f32_e32 v22, 1.0, v22
	v_add_f32_e32 v23, 1.0, v23
	v_add_f32_e32 v26, 1.0, v26
	v_add_f32_e32 v27, 1.0, v27
	v_rcp_f32_e32 v22, v22
	v_rcp_f32_e32 v23, v23
	v_rcp_f32_e32 v26, v26
	v_rcp_f32_e32 v27, v27
	v_pk_mul_f32 v[12:13], v[22:23], v[152:153]
	s_nop 0
	v_pk_add_f32 v[14:15], v[12:13], v[12:13]
	v_mul_f32_e32 v22, 0x3fb8aa3b, v12
	v_mul_f32_e32 v23, 0x3fb8aa3b, v13
	v_exp_f32_e32 v22, v22
	v_exp_f32_e32 v23, v23
	v_mul_f32_e32 v16, 0x3e800000, v14
	v_fma_f32 v17, v14, s5, 1.0
	v_mul_f32_e32 v18, 0x3eaaaaab, v14
	v_fma_f32 v16, v16, v17, 1.0
	v_mul_f32_e32 v17, 0.5, v14
	v_fma_f32 v18, v18, v16, 1.0
	v_fma_f32 v17, v17, v18, 1.0
	v_mul_f32_e64 v17, v17, -v14
	v_fma_f32 v16, -v22, v22, 1.0
	v_cmp_lt_f32_e32 vcc, s6, v14
	v_mul_f32_e32 v19, 0x3e800000, v15
	v_fma_f32 v12, v15, s5, 1.0
	v_cndmask_b32_e32 v16, v16, v17, vcc
	v_mul_f32_e32 v13, 0x3eaaaaab, v15
	v_fma_f32 v19, v19, v12, 1.0
	v_mul_f32_e32 v12, 0.5, v15
	v_fma_f32 v13, v13, v19, 1.0
	v_fma_f32 v12, v12, v13, 1.0
	v_mul_f32_e64 v12, v12, -v15
	v_fma_f32 v13, -v23, v23, 1.0
	v_cmp_lt_f32_e32 vcc, s6, v15
	v_sqrt_f32_e32 v16, v16
	s_nop 1
	v_cndmask_b32_e32 v17, v13, v12, vcc
	v_sqrt_f32_e32 v17, v17
	s_nop 0
	v_pk_mul_f32 v[26:27], v[26:27], v[16:17]
	s_nop 0
	v_pk_mul_f32 v[26:27], v[30:31], v[26:27]
	ds_write_b128 v204, v[20:23] offset:42496
	ds_write_b128 v204, v[24:27] offset:58880
	ds_read_b128 v[12:15], v229 offset:32000
	ds_read_b128 v[16:19], v229 offset:32064
	ds_read_b128 v[28:31], v230 offset:20992
	s_waitcnt lgkmcnt(1)
	v_mfma_f32_16x16x32_bf16 v[20:23], v[232:235], v[12:15], 0
	v_mfma_f32_16x16x32_bf16 v[24:27], v[240:243], v[12:15], 0
	v_mfma_f32_16x16x32_bf16 v[20:23], v[236:239], v[16:19], v[20:23]
	v_mfma_f32_16x16x32_bf16 v[24:27], v[244:247], v[16:19], v[24:27]
	s_nop 7
	s_nop 3
	s_waitcnt lgkmcnt(0)
; __device__ __forceinline__ float sigmoidf_(float x) { return __builtin_amdgcn_rcpf(1.0f + __expf(-x)); }
; template <bool FINAL>
; __device__ void phase_lru(const Params& p, int l, unsigned char* smem) {
;     ...
;           for (int j = 0; j < 4; ++j) {
;             float r = sigmoidf_(ar[j] + bap[j]);
;             float ig = sigmoidf_(ai[j] + bxp[j]);
;             float la = spp[j] * r;
;             float av_ = __expf(la);
;             float t2 = 2.0f * la;
;             float ser = -t2 * (1.f + t2 * 0.5f * (1.f + t2 * (1.f / 3.f) * (1.f + t2 * 0.25f * (1.f + t2 * 0.2f))));
;             float om = (t2 > -0.25f) ? ser : (1.0f - av_ * av_);
;             av[j] = av_;
;             bv[j] = __builtin_amdgcn_sqrtf(om) * ig * uup[j];
;           }
;           *(f32x4*)(sa + t * 64 + e0) = av;
;           *(f32x4*)(sb + t * 64 + e0) = bv;
;         }
;       }
;       __syncthreads();
;       {
;         float A = 1.f, B = 0.f;
;         if (d == 0) {
; #pragma unroll
;           for (int tt = 0; tt < 16; ++tt) { int t = qd * 16 + tt; float a = sa[t * 64 + e_], b = sb[t * 64 + e_]; B = a * B + b; A *= a; }
;         } else {
; #pragma unroll
;     ...
;         }
;         part[(0 * 4 + qd) * 64 + e_] = A;
;         part[(1 * 4 + qd) * 64 + e_] = B;
;       }
;       __syncthreads();
;       if (!FINAL) {
;         if (qd == 0) {
;           float A = 1.f, B = 0.f;
;           if (d == 0) {
; #pragma unroll
;             for (int q = 0; q < 4; ++q) { float aq = part[q * 64 + e_], bq = part[(4 + q) * 64 + e_]; B = aq * B + bq; A *= aq; }
;           } else {
; #pragma unroll
;             for (int q = 3; q >= 0; --q) { float aq = part[q * 64 + e_], bq = part[(4 + q) * 64 + e_]; B = aq * B + bq; A *= aq; }
;           }
;           const size_t cidx = ((size_t)ci * 2 + d) * 512 + nb * 64 + e_;
;           p.CA[cidx] = A; p.CB[cidx] = B;
;         }
	v_add_f32_e32 v20, v20, v134
	v_add_f32_e32 v21, v21, v135
	v_add_f32_e32 v24, v24, v138
	v_add_f32_e32 v25, v25, v139
	v_mul_f32_e32 v20, 0xbfb8aa3b, v20
	v_mul_f32_e32 v21, 0xbfb8aa3b, v21
	v_mul_f32_e32 v24, 0xbfb8aa3b, v24
	v_mul_f32_e32 v25, 0xbfb8aa3b, v25
	v_exp_f32_e32 v20, v20
	v_exp_f32_e32 v21, v21
	v_exp_f32_e32 v24, v24
	v_exp_f32_e32 v25, v25
	v_add_f32_e32 v20, 1.0, v20
	v_add_f32_e32 v21, 1.0, v21
	v_add_f32_e32 v24, 1.0, v24
	v_add_f32_e32 v25, 1.0, v25
	v_rcp_f32_e32 v20, v20
	v_rcp_f32_e32 v21, v21
	v_rcp_f32_e32 v24, v24
	v_rcp_f32_e32 v25, v25
	v_pk_mul_f32 v[12:13], v[20:21], v[150:151]
	s_nop 0
	v_pk_add_f32 v[14:15], v[12:13], v[12:13]
	v_mul_f32_e32 v20, 0x3fb8aa3b, v12
	v_mul_f32_e32 v21, 0x3fb8aa3b, v13
	v_exp_f32_e32 v20, v20
	v_exp_f32_e32 v21, v21
	v_mul_f32_e32 v16, 0x3e800000, v14
	v_fma_f32 v17, v14, s5, 1.0
	v_mul_f32_e32 v18, 0x3eaaaaab, v14
	v_fma_f32 v16, v16, v17, 1.0
	v_mul_f32_e32 v17, 0.5, v14
	v_fma_f32 v18, v18, v16, 1.0
	v_fma_f32 v17, v17, v18, 1.0
	v_mul_f32_e64 v17, v17, -v14
	v_fma_f32 v16, -v20, v20, 1.0
	v_cmp_lt_f32_e32 vcc, s6, v14
	v_mul_f32_e32 v19, 0x3e800000, v15
	v_fma_f32 v12, v15, s5, 1.0
	v_cndmask_b32_e32 v16, v16, v17, vcc
	v_mul_f32_e32 v13, 0x3eaaaaab, v15
	v_fma_f32 v19, v19, v12, 1.0
	v_mul_f32_e32 v12, 0.5, v15
	v_fma_f32 v13, v13, v19, 1.0
	v_fma_f32 v12, v12, v13, 1.0
	v_mul_f32_e64 v12, v12, -v15
	v_fma_f32 v13, -v21, v21, 1.0
	v_cmp_lt_f32_e32 vcc, s6, v15
	v_sqrt_f32_e32 v16, v16
	s_nop 1
	v_cndmask_b32_e32 v17, v13, v12, vcc
	v_sqrt_f32_e32 v17, v17
	s_nop 0
	v_pk_mul_f32 v[24:25], v[24:25], v[16:17]
	s_nop 0
	v_pk_mul_f32 v[24:25], v[28:29], v[24:25]
	v_add_f32_e32 v22, v22, v136
	v_add_f32_e32 v23, v23, v137
	v_add_f32_e32 v26, v26, v140
	v_add_f32_e32 v27, v27, v141
	v_mul_f32_e32 v22, 0xbfb8aa3b, v22
	v_mul_f32_e32 v23, 0xbfb8aa3b, v23
	v_mul_f32_e32 v26, 0xbfb8aa3b, v26
	v_mul_f32_e32 v27, 0xbfb8aa3b, v27
	v_exp_f32_e32 v22, v22
	v_exp_f32_e32 v23, v23
	v_exp_f32_e32 v26, v26
	v_exp_f32_e32 v27, v27
	v_add_f32_e32 v22, 1.0, v22
	v_add_f32_e32 v23, 1.0, v23
	v_add_f32_e32 v26, 1.0, v26
	v_add_f32_e32 v27, 1.0, v27
	v_rcp_f32_e32 v22, v22
	v_rcp_f32_e32 v23, v23
	v_rcp_f32_e32 v26, v26
	v_rcp_f32_e32 v27, v27
	v_pk_mul_f32 v[12:13], v[22:23], v[152:153]
	s_nop 0
	v_pk_add_f32 v[14:15], v[12:13], v[12:13]
	v_mul_f32_e32 v22, 0x3fb8aa3b, v12
	v_mul_f32_e32 v23, 0x3fb8aa3b, v13
	v_exp_f32_e32 v22, v22
	v_exp_f32_e32 v23, v23
	v_mul_f32_e32 v16, 0x3e800000, v14
	v_fma_f32 v17, v14, s5, 1.0
	v_mul_f32_e32 v18, 0x3eaaaaab, v14
	v_fma_f32 v16, v16, v17, 1.0
	v_mul_f32_e32 v17, 0.5, v14
	v_fma_f32 v18, v18, v16, 1.0
	v_fma_f32 v17, v17, v18, 1.0
	v_mul_f32_e64 v17, v17, -v14
	v_fma_f32 v16, -v22, v22, 1.0
	v_cmp_lt_f32_e32 vcc, s6, v14
	v_mul_f32_e32 v19, 0x3e800000, v15
	v_fma_f32 v12, v15, s5, 1.0
	v_cndmask_b32_e32 v16, v16, v17, vcc
	v_mul_f32_e32 v13, 0x3eaaaaab, v15
	v_fma_f32 v19, v19, v12, 1.0
	v_mul_f32_e32 v12, 0.5, v15
	v_fma_f32 v13, v13, v19, 1.0
	v_fma_f32 v12, v12, v13, 1.0
	v_mul_f32_e64 v12, v12, -v15
	v_fma_f32 v13, -v23, v23, 1.0
	v_cmp_lt_f32_e32 vcc, s6, v15
	v_sqrt_f32_e32 v16, v16
	s_nop 1
	v_cndmask_b32_e32 v17, v13, v12, vcc
	v_sqrt_f32_e32 v17, v17
	s_nop 0
	v_pk_mul_f32 v[26:27], v[26:27], v[16:17]
	s_nop 0
	v_pk_mul_f32 v[26:27], v[30:31], v[26:27]
	ds_write_b128 v204, v[20:23] offset:46592
	ds_write_b128 v204, v[24:27] offset:62976
	s_waitcnt lgkmcnt(0)
	s_barrier
	ds_read2st64_b32 v[12:13], v96 offset0:134 offset1:198
	ds_read2st64_b32 v[14:15], v95 offset0:134 offset1:198
	ds_read2st64_b32 v[16:17], v94 offset0:134 offset1:198
	ds_read2st64_b32 v[104:105], v83 offset0:134 offset1:198
	ds_read2st64_b32 v[106:107], v82 offset0:134 offset1:198
	s_waitcnt lgkmcnt(4)
	v_fmac_f32_e32 v13, 0, v12
	s_waitcnt lgkmcnt(3)
	v_mul_f32_e32 v18, v12, v14
	s_waitcnt lgkmcnt(2)
	v_mul_f32_e32 v20, v18, v16
	ds_read2st64_b32 v[18:19], v93 offset0:134 offset1:198
	v_fmac_f32_e32 v15, v14, v13
	v_fmac_f32_e32 v17, v16, v15
	ds_read2st64_b32 v[108:109], v49 offset0:134 offset1:198
	s_waitcnt lgkmcnt(1)
	v_mul_f32_e32 v22, v20, v18
	ds_read2st64_b32 v[20:21], v92 offset0:134 offset1:198
	v_fmac_f32_e32 v19, v18, v17
	s_waitcnt lgkmcnt(0)
	v_mul_f32_e32 v24, v22, v20
	ds_read2st64_b32 v[22:23], v91 offset0:134 offset1:198
	v_fmac_f32_e32 v21, v20, v19
	s_waitcnt lgkmcnt(0)
	v_mul_f32_e32 v26, v24, v22
	ds_read2st64_b32 v[24:25], v90 offset0:134 offset1:198
	v_fmac_f32_e32 v23, v22, v21
	s_waitcnt lgkmcnt(0)
	v_mul_f32_e32 v28, v26, v24
	ds_read2st64_b32 v[26:27], v89 offset0:134 offset1:198
	v_fmac_f32_e32 v25, v24, v23
	s_waitcnt lgkmcnt(0)
	v_mul_f32_e32 v30, v28, v26
	ds_read2st64_b32 v[28:29], v88 offset0:134 offset1:198
	v_fmac_f32_e32 v27, v26, v25
	s_waitcnt lgkmcnt(0)
	v_mul_f32_e32 v32, v30, v28
	ds_read2st64_b32 v[30:31], v87 offset0:134 offset1:198
	v_fmac_f32_e32 v29, v28, v27
	s_waitcnt lgkmcnt(0)
	v_mul_f32_e32 v34, v32, v30
	ds_read2st64_b32 v[32:33], v86 offset0:134 offset1:198
	v_fmac_f32_e32 v31, v30, v29
	s_waitcnt lgkmcnt(0)
	v_mul_f32_e32 v54, v34, v32
	ds_read2st64_b32 v[34:35], v85 offset0:134 offset1:198
	v_fmac_f32_e32 v33, v32, v31
	s_waitcnt lgkmcnt(0)
	v_mul_f32_e32 v56, v54, v34
	ds_read2st64_b32 v[54:55], v84 offset0:134 offset1:198
	v_fmac_f32_e32 v35, v34, v33
	s_waitcnt lgkmcnt(0)
	v_mul_f32_e32 v56, v56, v54
	v_mul_f32_e32 v56, v56, v104
	v_fmac_f32_e32 v55, v54, v35
	v_mul_f32_e32 v56, v56, v106
	v_fmac_f32_e32 v105, v104, v55
	v_mul_f32_e32 v56, v56, v108
	v_fmac_f32_e32 v107, v106, v105
	v_fmac_f32_e32 v109, v108, v107
	ds_write_b32 v64, v56
	ds_write_b32 v65, v109 offset:1024
	s_waitcnt lgkmcnt(0)
	s_barrier
	s_and_saveexec_b64 s[42:43], s[40:41]
	s_cbranch_execz .LBB0_374
	ds_read2st64_b32 v[12:13], v64 offset0:2 offset1:3
	ds_read2st64_b32 v[14:15], v64 offset1:1
	ds_read_b32 v17, v97
	s_waitcnt lgkmcnt(2)
	v_mul_f32_e32 v16, v13, v12
	s_waitcnt lgkmcnt(1)
	v_mul_f32_e32 v16, v16, v15
	s_waitcnt lgkmcnt(0)
	v_fmac_f32_e32 v17, 0, v13
	ds_read_b32 v13, v98
	v_mul_f32_e32 v16, v16, v14
	s_waitcnt lgkmcnt(0)
	v_fmac_f32_e32 v13, v12, v17
	ds_read_b32 v12, v99
	s_waitcnt lgkmcnt(0)
	v_fmac_f32_e32 v12, v15, v13
	ds_read_b32 v13, v100
	s_waitcnt lgkmcnt(0)
	v_fmac_f32_e32 v13, v14, v12
	global_store_dword v[50:51], v16, off offset:2048
	global_store_dword v[52:53], v13, off offset:2048
	s_branch .LBB0_374
